# static priority raise: all per-segment s_setprio toggles removed from the GEMM loops, one s_setprio 1 for waves 4-7 at each GEMM unit-loop head, reset at the phase-loop top
# speedup vs baseline: 1.0098x; 1.0014x over previous
; template <class Epi>
; __device__ __forceinline__ void gemm_phase(LAS unsigned char* lds, const Gemm g, const int G, const int cidx, const Epi& E) {
;     ...
;     for (;;) {
;         const bool has_next = S.next(ui + 1, nxt);
;         const char* nA = has_next ? PG8_ABASE(nxt) : cA; const char* nB = has_next ? (const char*)g.Bt + (size_t)nxt.pn * tstep : cB;
.LBB0_79:
	v_readfirstlane_b32 s98, v202
	s_cmp_lt_u32 s98, 0x100
	s_cbranch_scc1 .Lgprio_c
	s_setprio 1

; #define PG8_STAGE(bufoff, gbase, voff) do { _Pragma("unroll") for (int _i = 0; _i < 2; ++_i) \
;         __builtin_amdgcn_global_load_lds((const unsigned*)((const char*)(gbase) + (voff)[_i]), (LAS unsigned*)(lds + (bufoff) + ldsw + _i * 8192), 16, 0, 0); } while (0)
; #define PG8_LDA(dst, b, h) do { _Pragma("unroll") for (int m = 0; m < 4; ++m) _Pragma("unroll") for (int k = 0; k < 2; ++k) dst[m][k] = *(const LAS bf16x8*)(lds + PG8_SA(b, h) + aoff + m * 2048 + k * 1024); } while (0)
; #define PG8_LDB(dst, b, h) do { _Pragma("unroll") for (int n = 0; n < 2; ++n) _Pragma("unroll") for (int k = 0; k < 2; ++k) dst[n][k] = *(const LAS bf16x8*)(lds + PG8_SB(b, h) + boff + n * 2048 + k * 1024); } while (0)
; #define PG8_MMA(ai, bj, At, Bt) do { __builtin_amdgcn_s_setprio(1); _Pragma("unroll") for (int m = 0; m < 4; ++m) _Pragma("unroll") for (int n = 0; n < 2; ++n) _Pragma("unroll") for (int k = 0; k < 2; ++k) \
;         acc[ai][bj][m][n] = __builtin_amdgcn_mfma_f32_16x16x32_bf16(Bt[n][k], At[m][k], acc[ai][bj][m][n], 0, 0, 0); __builtin_amdgcn_s_setprio(0); } while (0)
; #define PG8_WAIT_V(n) asm volatile("s_waitcnt vmcnt(" #n ")" ::: "memory")
; template <class Epi>
; __device__ __forceinline__ void gemm_phase(LAS unsigned char* lds, const Gemm g, const int G, const int cidx, const Epi& E) {
;     ...
;         const bool has_next = S.next(ui + 1, nxt);
;         const char* nA = has_next ? PG8_ABASE(nxt) : cA; const char* nB = has_next ? (const char*)g.Bt + (size_t)nxt.pn * tstep : cB;
;         for (int t = 0; t < nt; t += 2) {
;             const bool last = (t == nt - 2);
;             const char* a1 = cA + (size_t)(t + 1) * kstep;
;             const char* a2 = last ? nA : cA + (size_t)(t + 2) * kstep; const char* b2 = last ? nB : cB + (size_t)(t + 2) * kstep;
;             const char* a3 = a2 + kstep; const char* b3 = b2 + kstep;
;             PG8_LDB(B0, 0, 0); PG8_LDB(B1, 0, 1); PG8_SCHED; PG8_LDA(At, 0, 0); PG8_STAGE(PG8_SA(1, 1), a1 + hstep, voffA);
;             PG8_WAIT_V(8); PG8_WAIT_L(0); PG8_BAR; PG8_MMA(0, 0, At, B0); PG8_MMA(0, 1, At, B1); PG8_BAR; PG8_SCHED;
;             PG8_LDA(At, 0, 1); PG8_STAGE(PG8_SB(0, 0), b2, voffB); PG8_STAGE(PG8_SB(0, 1), b2 + hstep, voffB); PG8_STAGE(PG8_SA(0, 0), a2, voffA);
;             PG8_WAIT_V(8); PG8_WAIT_L(0); PG8_BAR; PG8_MMA(1, 0, At, B0); PG8_MMA(1, 1, At, B1); PG8_BAR; PG8_SCHED;
.LBB0_81:
	s_ashr_i32 s13, s12, 31
	v_cmp_lt_i64_e32 vcc, s[14:15], v[240:241]
	s_lshl_b64 s[14:15], s[12:13], 19
	s_add_u32 s14, s42, s14
	s_addc_u32 s15, s94, s15
	s_and_b64 s[18:19], vcc, exec
	s_cselect_b32 s13, s15, s27
	s_cselect_b32 s17, s14, s26
	s_ashr_i32 s9, s8, 31
	s_lshl_b64 s[18:19], s[8:9], 19
	s_add_u32 s18, s96, s18
	s_addc_u32 s19, s97, s19
	s_and_b64 s[28:29], vcc, exec
	s_cselect_b32 s9, s19, s25
	s_cselect_b32 s22, s18, s24
	s_add_u32 s33, s24, 0x100
	s_addc_u32 s44, s25, 0
	s_add_u32 s24, s26, 0x40080
	s_addc_u32 s25, s27, 0
	s_mov_b32 s45, -2
	s_add_u32 s26, s24, 0xfffc0080
	s_addc_u32 s27, s25, -1
	s_add_i32 s43, 0, 0x10000
	s_cmp_eq_u32 s45, 12
	s_cselect_b32 s29, s13, s27
	s_cselect_b32 s28, s17, s26
	s_cselect_b32 s27, s9, s44
	s_cselect_b32 s26, s22, s33
	s_add_i32 s68, 0, 0x14000
	v_add_u32_e32 v162, s43, v145
	v_add_u32_e32 v178, s68, v145
	ds_read_b128 v[132:135], v162
	ds_read_b128 v[140:143], v162 offset:1024
	ds_read_b128 v[156:159], v162 offset:2048
	ds_read_b128 v[162:165], v162 offset:3072
	ds_read_b128 v[166:169], v178
	ds_read_b128 v[170:173], v178 offset:1024
	ds_read_b128 v[174:177], v178 offset:2048
	ds_read_b128 v[178:181], v178 offset:3072
	v_lshl_add_u64 v[226:227], s[24:25], 0, v[154:155]
	s_add_i32 m0, s21, 0xc000
	ds_read_b128 v[182:185], v161
	ds_read_b128 v[186:189], v161 offset:1024
	ds_read_b128 v[190:193], v161 offset:2048
	ds_read_b128 v[194:197], v161 offset:3072
	ds_read_b128 v[198:201], v161 offset:4096
	ds_read_b128 v[214:217], v161 offset:5120
	ds_read_b128 v[218:221], v161 offset:6144
	ds_read_b128 v[222:225], v161 offset:7168
	global_load_lds_dwordx4 v[226:227], off
	v_lshl_add_u64 v[226:227], s[24:25], 0, v[152:153]
	s_add_i32 m0, s21, 0xe000
	s_nop 0
	global_load_lds_dwordx4 v[226:227], off
	s_waitcnt vmcnt(8)
	s_waitcnt lgkmcnt(0)
	s_barrier
	s_waitcnt lgkmcnt(0)
	v_mfma_f32_16x16x32_bf16 v[128:131], v[132:135], v[182:185], 0
	v_mfma_f32_16x16x32_bf16 v[120:123], v[156:159], v[182:185], 0
	v_mfma_f32_16x16x32_bf16 v[112:115], v[132:135], v[190:193], 0
	v_mfma_f32_16x16x32_bf16 v[104:107], v[156:159], v[190:193], 0
	v_mfma_f32_16x16x32_bf16 v[96:99], v[132:135], v[198:201], 0
	v_mfma_f32_16x16x32_bf16 v[88:91], v[156:159], v[198:201], 0
	v_mfma_f32_16x16x32_bf16 v[80:83], v[132:135], v[218:221], 0
	v_mfma_f32_16x16x32_bf16 v[72:75], v[156:159], v[218:221], 0
	v_mfma_f32_16x16x32_bf16 v[128:131], v[140:143], v[186:189], v[128:131]
	v_mfma_f32_16x16x32_bf16 v[120:123], v[162:165], v[186:189], v[120:123]
	v_mfma_f32_16x16x32_bf16 v[112:115], v[140:143], v[194:197], v[112:115]
	v_mfma_f32_16x16x32_bf16 v[104:107], v[162:165], v[194:197], v[104:107]
	v_mfma_f32_16x16x32_bf16 v[96:99], v[140:143], v[214:217], v[96:99]
	v_mfma_f32_16x16x32_bf16 v[88:91], v[162:165], v[214:217], v[88:91]
	v_mfma_f32_16x16x32_bf16 v[80:83], v[140:143], v[222:225], v[80:83]
	v_mfma_f32_16x16x32_bf16 v[72:75], v[162:165], v[222:225], v[72:75]
	v_mfma_f32_16x16x32_bf16 v[124:127], v[166:169], v[182:185], 0
	v_mfma_f32_16x16x32_bf16 v[116:119], v[174:177], v[182:185], 0
	v_mfma_f32_16x16x32_bf16 v[108:111], v[166:169], v[190:193], 0
	v_mfma_f32_16x16x32_bf16 v[100:103], v[174:177], v[190:193], 0
	v_mfma_f32_16x16x32_bf16 v[92:95], v[166:169], v[198:201], 0
	v_mfma_f32_16x16x32_bf16 v[84:87], v[174:177], v[198:201], 0
	v_mfma_f32_16x16x32_bf16 v[76:79], v[166:169], v[218:221], 0
	v_mfma_f32_16x16x32_bf16 v[68:71], v[174:177], v[218:221], 0
	v_mfma_f32_16x16x32_bf16 v[124:127], v[170:173], v[186:189], v[124:127]
	v_mfma_f32_16x16x32_bf16 v[116:119], v[178:181], v[186:189], v[116:119]
	v_mfma_f32_16x16x32_bf16 v[108:111], v[170:173], v[194:197], v[108:111]
	v_mfma_f32_16x16x32_bf16 v[100:103], v[178:181], v[194:197], v[100:103]
	v_mfma_f32_16x16x32_bf16 v[92:95], v[170:173], v[214:217], v[92:95]
	v_mfma_f32_16x16x32_bf16 v[84:87], v[178:181], v[214:217], v[84:87]
	v_mfma_f32_16x16x32_bf16 v[76:79], v[170:173], v[222:225], v[76:79]
	v_mfma_f32_16x16x32_bf16 v[68:71], v[178:181], v[222:225], v[68:71]
	s_barrier
	s_add_i32 s43, s43, s36
	v_lshl_add_u64 v[226:227], s[26:27], 0, v[148:149]
	s_mov_b32 m0, s43
	ds_read_b128 v[182:185], v161 offset:16384
	ds_read_b128 v[186:189], v161 offset:17408
	ds_read_b128 v[190:193], v161 offset:18432
	ds_read_b128 v[194:197], v161 offset:19456
	ds_read_b128 v[198:201], v161 offset:20480
	ds_read_b128 v[214:217], v161 offset:21504
	ds_read_b128 v[218:221], v161 offset:22528
	ds_read_b128 v[222:225], v161 offset:23552
	global_load_lds_dwordx4 v[226:227], off
	s_add_i32 m0, s43, 0x2000
	s_add_u32 s76, s26, 0x40000
	v_lshl_add_u64 v[228:229], s[26:27], 0, v[0:1]
	s_addc_u32 s77, s27, 0
	s_add_i32 s43, s68, s36
	global_load_lds_dwordx4 v[228:229], off
	v_lshl_add_u64 v[230:231], s[76:77], 0, v[148:149]
	s_mov_b32 m0, s43
	v_lshl_add_u64 v[232:233], s[28:29], 0, v[146:147]
	global_load_lds_dwordx4 v[230:231], off
	v_lshl_add_u64 v[230:231], s[76:77], 0, v[0:1]
	s_add_i32 m0, s43, 0x2000
	s_nop 0
	global_load_lds_dwordx4 v[230:231], off
	v_lshl_add_u64 v[230:231], s[28:29], 0, v[150:151]
	s_mov_b32 m0, s21
	s_nop 0
	global_load_lds_dwordx4 v[230:231], off
	s_mov_b32 m0, s38
	s_nop 0
	global_load_lds_dwordx4 v[232:233], off
	s_waitcnt vmcnt(8)
	s_waitcnt lgkmcnt(0)
	s_barrier
; #define PG8_STAGE(bufoff, gbase, voff) do { _Pragma("unroll") for (int _i = 0; _i < 2; ++_i) \
;         __builtin_amdgcn_global_load_lds((const unsigned*)((const char*)(gbase) + (voff)[_i]), (LAS unsigned*)(lds + (bufoff) + ldsw + _i * 8192), 16, 0, 0); } while (0)
; #define PG8_LDA(dst, b, h) do { _Pragma("unroll") for (int m = 0; m < 4; ++m) _Pragma("unroll") for (int k = 0; k < 2; ++k) dst[m][k] = *(const LAS bf16x8*)(lds + PG8_SA(b, h) + aoff + m * 2048 + k * 1024); } while (0)
; #define PG8_LDB(dst, b, h) do { _Pragma("unroll") for (int n = 0; n < 2; ++n) _Pragma("unroll") for (int k = 0; k < 2; ++k) dst[n][k] = *(const LAS bf16x8*)(lds + PG8_SB(b, h) + boff + n * 2048 + k * 1024); } while (0)
; #define PG8_MMA(ai, bj, At, Bt) do { __builtin_amdgcn_s_setprio(1); _Pragma("unroll") for (int m = 0; m < 4; ++m) _Pragma("unroll") for (int n = 0; n < 2; ++n) _Pragma("unroll") for (int k = 0; k < 2; ++k) \
;         acc[ai][bj][m][n] = __builtin_amdgcn_mfma_f32_16x16x32_bf16(Bt[n][k], At[m][k], acc[ai][bj][m][n], 0, 0, 0); __builtin_amdgcn_s_setprio(0); } while (0)
; #define PG8_WAIT_V(n) asm volatile("s_waitcnt vmcnt(" #n ")" ::: "memory")
; #define PG8_WAIT_L(n) asm volatile("s_waitcnt lgkmcnt(" #n ")" ::: "memory")
; #define PG8_BAR __builtin_amdgcn_s_barrier()
; #define PG8_SCHED __builtin_amdgcn_sched_barrier(0)
; template <class Epi>
; __device__ __forceinline__ void gemm_phase(LAS unsigned char* lds, const Gemm g, const int G, const int cidx, const Epi& E) {
;     ...
;             PG8_WAIT_V(8); PG8_WAIT_L(0); PG8_BAR; PG8_MMA(1, 0, At, B0); PG8_MMA(1, 1, At, B1); PG8_BAR; PG8_SCHED;
;             PG8_LDB(B0, 1, 0); PG8_LDB(B1, 1, 1); PG8_SCHED; PG8_LDA(At, 1, 0); PG8_STAGE(PG8_SA(0, 1), a2 + hstep, voffA);
;             PG8_WAIT_V(8); PG8_WAIT_L(0); PG8_BAR; PG8_MMA(0, 0, At, B0); PG8_MMA(0, 1, At, B1); PG8_BAR; PG8_SCHED;
;             PG8_LDA(At, 1, 1); PG8_STAGE(PG8_SB(1, 0), b3, voffB); PG8_STAGE(PG8_SB(1, 1), b3 + hstep, voffB); PG8_STAGE(PG8_SA(1, 0), a3, voffA);
;             PG8_WAIT_V(8); PG8_WAIT_L(0); PG8_BAR; PG8_MMA(1, 0, At, B0); PG8_MMA(1, 1, At, B1); PG8_BAR; PG8_SCHED;
	s_waitcnt lgkmcnt(0)
	v_mfma_f32_16x16x32_bf16 v[64:67], v[132:135], v[182:185], 0
	v_mfma_f32_16x16x32_bf16 v[56:59], v[156:159], v[182:185], 0
	v_mfma_f32_16x16x32_bf16 v[48:51], v[132:135], v[190:193], 0
	v_mfma_f32_16x16x32_bf16 v[40:43], v[156:159], v[190:193], 0
	v_mfma_f32_16x16x32_bf16 v[32:35], v[132:135], v[198:201], 0
	v_mfma_f32_16x16x32_bf16 v[24:27], v[156:159], v[198:201], 0
	v_mfma_f32_16x16x32_bf16 v[16:19], v[132:135], v[218:221], 0
	v_mfma_f32_16x16x32_bf16 v[8:11], v[156:159], v[218:221], 0
	v_mfma_f32_16x16x32_bf16 v[64:67], v[140:143], v[186:189], v[64:67]
	v_mfma_f32_16x16x32_bf16 v[56:59], v[162:165], v[186:189], v[56:59]
	v_mfma_f32_16x16x32_bf16 v[48:51], v[140:143], v[194:197], v[48:51]
	v_mfma_f32_16x16x32_bf16 v[40:43], v[162:165], v[194:197], v[40:43]
	v_mfma_f32_16x16x32_bf16 v[32:35], v[140:143], v[214:217], v[32:35]
	v_mfma_f32_16x16x32_bf16 v[24:27], v[162:165], v[214:217], v[24:27]
	v_mfma_f32_16x16x32_bf16 v[16:19], v[140:143], v[222:225], v[16:19]
	v_mfma_f32_16x16x32_bf16 v[8:11], v[162:165], v[222:225], v[8:11]
	v_mfma_f32_16x16x32_bf16 v[60:63], v[166:169], v[182:185], 0
	v_mfma_f32_16x16x32_bf16 v[52:55], v[174:177], v[182:185], 0
	v_mfma_f32_16x16x32_bf16 v[44:47], v[166:169], v[190:193], 0
	v_mfma_f32_16x16x32_bf16 v[36:39], v[174:177], v[190:193], 0
	v_mfma_f32_16x16x32_bf16 v[28:31], v[166:169], v[198:201], 0
	v_mfma_f32_16x16x32_bf16 v[20:23], v[174:177], v[198:201], 0
	v_mfma_f32_16x16x32_bf16 v[12:15], v[166:169], v[218:221], 0
	v_mfma_f32_16x16x32_bf16 v[4:7], v[174:177], v[218:221], 0
	v_mfma_f32_16x16x32_bf16 v[60:63], v[170:173], v[186:189], v[60:63]
	v_mfma_f32_16x16x32_bf16 v[52:55], v[178:181], v[186:189], v[52:55]
	v_mfma_f32_16x16x32_bf16 v[44:47], v[170:173], v[194:197], v[44:47]
	v_mfma_f32_16x16x32_bf16 v[36:39], v[178:181], v[194:197], v[36:39]
	v_mfma_f32_16x16x32_bf16 v[28:31], v[170:173], v[214:217], v[28:31]
	v_mfma_f32_16x16x32_bf16 v[20:23], v[178:181], v[214:217], v[20:23]
	v_mfma_f32_16x16x32_bf16 v[12:15], v[170:173], v[222:225], v[12:15]
	v_mfma_f32_16x16x32_bf16 v[4:7], v[178:181], v[222:225], v[4:7]
	s_barrier
	s_add_i32 s43, 0, 0x18000
	s_add_i32 s68, 0, 0x1c000
	v_add_u32_e32 v162, s43, v145
	v_add_u32_e32 v178, s68, v145
	ds_read_b128 v[132:135], v162
	ds_read_b128 v[140:143], v162 offset:1024
	ds_read_b128 v[156:159], v162 offset:2048
	ds_read_b128 v[162:165], v162 offset:3072
	ds_read_b128 v[166:169], v178
	ds_read_b128 v[170:173], v178 offset:1024
	ds_read_b128 v[174:177], v178 offset:2048
	ds_read_b128 v[178:181], v178 offset:3072
	s_add_u32 s28, s28, 0x40000
	s_addc_u32 s29, s29, 0
	s_mov_b32 m0, s39
	v_lshl_add_u64 v[234:235], s[28:29], 0, v[150:151]
	ds_read_b128 v[182:185], v161 offset:32768
	ds_read_b128 v[186:189], v161 offset:33792
	ds_read_b128 v[190:193], v161 offset:34816
	ds_read_b128 v[194:197], v161 offset:35840
	ds_read_b128 v[198:201], v161 offset:36864
	ds_read_b128 v[214:217], v161 offset:37888
	ds_read_b128 v[218:221], v161 offset:38912
	ds_read_b128 v[222:225], v161 offset:39936
	global_load_lds_dwordx4 v[234:235], off
	v_lshl_add_u64 v[234:235], s[28:29], 0, v[146:147]
	s_mov_b32 m0, s75
	s_nop 0
	global_load_lds_dwordx4 v[234:235], off
	s_waitcnt vmcnt(8)
	s_waitcnt lgkmcnt(0)
	s_barrier
	s_waitcnt lgkmcnt(0)
	v_mfma_f32_16x16x32_bf16 v[128:131], v[132:135], v[182:185], v[128:131]
	v_mfma_f32_16x16x32_bf16 v[120:123], v[156:159], v[182:185], v[120:123]
	v_mfma_f32_16x16x32_bf16 v[112:115], v[132:135], v[190:193], v[112:115]
	v_mfma_f32_16x16x32_bf16 v[104:107], v[156:159], v[190:193], v[104:107]
	v_mfma_f32_16x16x32_bf16 v[96:99], v[132:135], v[198:201], v[96:99]
	v_mfma_f32_16x16x32_bf16 v[88:91], v[156:159], v[198:201], v[88:91]
	v_mfma_f32_16x16x32_bf16 v[80:83], v[132:135], v[218:221], v[80:83]
	v_mfma_f32_16x16x32_bf16 v[72:75], v[156:159], v[218:221], v[72:75]
	v_mfma_f32_16x16x32_bf16 v[128:131], v[140:143], v[186:189], v[128:131]
	v_mfma_f32_16x16x32_bf16 v[120:123], v[162:165], v[186:189], v[120:123]
	v_mfma_f32_16x16x32_bf16 v[112:115], v[140:143], v[194:197], v[112:115]
	v_mfma_f32_16x16x32_bf16 v[104:107], v[162:165], v[194:197], v[104:107]
	v_mfma_f32_16x16x32_bf16 v[96:99], v[140:143], v[214:217], v[96:99]
	v_mfma_f32_16x16x32_bf16 v[88:91], v[162:165], v[214:217], v[88:91]
	v_mfma_f32_16x16x32_bf16 v[80:83], v[140:143], v[222:225], v[80:83]
	v_mfma_f32_16x16x32_bf16 v[72:75], v[162:165], v[222:225], v[72:75]
	v_mfma_f32_16x16x32_bf16 v[124:127], v[166:169], v[182:185], v[124:127]
	v_mfma_f32_16x16x32_bf16 v[116:119], v[174:177], v[182:185], v[116:119]
	v_mfma_f32_16x16x32_bf16 v[108:111], v[166:169], v[190:193], v[108:111]
	v_mfma_f32_16x16x32_bf16 v[100:103], v[174:177], v[190:193], v[100:103]
	v_mfma_f32_16x16x32_bf16 v[92:95], v[166:169], v[198:201], v[92:95]
	v_mfma_f32_16x16x32_bf16 v[84:87], v[174:177], v[198:201], v[84:87]
	v_mfma_f32_16x16x32_bf16 v[76:79], v[166:169], v[218:221], v[76:79]
	v_mfma_f32_16x16x32_bf16 v[68:71], v[174:177], v[218:221], v[68:71]
	v_mfma_f32_16x16x32_bf16 v[124:127], v[170:173], v[186:189], v[124:127]
	v_mfma_f32_16x16x32_bf16 v[116:119], v[178:181], v[186:189], v[116:119]
	v_mfma_f32_16x16x32_bf16 v[108:111], v[170:173], v[194:197], v[108:111]
	v_mfma_f32_16x16x32_bf16 v[100:103], v[178:181], v[194:197], v[100:103]
	v_mfma_f32_16x16x32_bf16 v[92:95], v[170:173], v[214:217], v[92:95]
	v_mfma_f32_16x16x32_bf16 v[84:87], v[178:181], v[214:217], v[84:87]
	v_mfma_f32_16x16x32_bf16 v[76:79], v[170:173], v[222:225], v[76:79]
	v_mfma_f32_16x16x32_bf16 v[68:71], v[178:181], v[222:225], v[68:71]
	s_barrier
; #define PG8_STAGE(bufoff, gbase, voff) do { _Pragma("unroll") for (int _i = 0; _i < 2; ++_i) \
;         __builtin_amdgcn_global_load_lds((const unsigned*)((const char*)(gbase) + (voff)[_i]), (LAS unsigned*)(lds + (bufoff) + ldsw + _i * 8192), 16, 0, 0); } while (0)
; #define PG8_LDA(dst, b, h) do { _Pragma("unroll") for (int m = 0; m < 4; ++m) _Pragma("unroll") for (int k = 0; k < 2; ++k) dst[m][k] = *(const LAS bf16x8*)(lds + PG8_SA(b, h) + aoff + m * 2048 + k * 1024); } while (0)
; #define PG8_LDB(dst, b, h) do { _Pragma("unroll") for (int n = 0; n < 2; ++n) _Pragma("unroll") for (int k = 0; k < 2; ++k) dst[n][k] = *(const LAS bf16x8*)(lds + PG8_SB(b, h) + boff + n * 2048 + k * 1024); } while (0)
; #define PG8_MMA(ai, bj, At, Bt) do { __builtin_amdgcn_s_setprio(1); _Pragma("unroll") for (int m = 0; m < 4; ++m) _Pragma("unroll") for (int n = 0; n < 2; ++n) _Pragma("unroll") for (int k = 0; k < 2; ++k) \
;         acc[ai][bj][m][n] = __builtin_amdgcn_mfma_f32_16x16x32_bf16(Bt[n][k], At[m][k], acc[ai][bj][m][n], 0, 0, 0); __builtin_amdgcn_s_setprio(0); } while (0)
; #define PG8_WAIT_V(n) asm volatile("s_waitcnt vmcnt(" #n ")" ::: "memory")
; #define PG8_WAIT_L(n) asm volatile("s_waitcnt lgkmcnt(" #n ")" ::: "memory")
; #define PG8_BAR __builtin_amdgcn_s_barrier()
; #define PG8_SCHED __builtin_amdgcn_sched_barrier(0)
; template <class Epi>
; __device__ __forceinline__ void gemm_phase(LAS unsigned char* lds, const Gemm g, const int G, const int cidx, const Epi& E) {
;     ...
;         for (int t = 0; t < nt; t += 2) {
;             const bool last = (t == nt - 2);
;             const char* a1 = cA + (size_t)(t + 1) * kstep;
;             const char* a2 = last ? nA : cA + (size_t)(t + 2) * kstep; const char* b2 = last ? nB : cB + (size_t)(t + 2) * kstep;
;             const char* a3 = a2 + kstep; const char* b3 = b2 + kstep;
;             PG8_LDB(B0, 0, 0); PG8_LDB(B1, 0, 1); PG8_SCHED; PG8_LDA(At, 0, 0); PG8_STAGE(PG8_SA(1, 1), a1 + hstep, voffA);
;             PG8_WAIT_V(8); PG8_WAIT_L(0); PG8_BAR; PG8_MMA(0, 0, At, B0); PG8_MMA(0, 1, At, B1); PG8_BAR; PG8_SCHED;
;     ...
;             PG8_LDA(At, 1, 1); PG8_STAGE(PG8_SB(1, 0), b3, voffB); PG8_STAGE(PG8_SB(1, 1), b3 + hstep, voffB); PG8_STAGE(PG8_SA(1, 0), a3, voffA);
;             PG8_WAIT_V(8); PG8_WAIT_L(0); PG8_BAR; PG8_MMA(1, 0, At, B0); PG8_MMA(1, 1, At, B1); PG8_BAR; PG8_SCHED;
	s_add_i32 s28, s43, s36
	v_lshl_add_u64 v[226:227], v[226:227], 0, s[46:47]
	s_mov_b32 m0, s28
	ds_read_b128 v[182:185], v161 offset:49152
	ds_read_b128 v[186:189], v161 offset:50176
	ds_read_b128 v[190:193], v161 offset:51200
	ds_read_b128 v[194:197], v161 offset:52224
	ds_read_b128 v[198:201], v161 offset:53248
	ds_read_b128 v[214:217], v161 offset:54272
	ds_read_b128 v[218:221], v161 offset:55296
	ds_read_b128 v[222:225], v161 offset:56320
	global_load_lds_dwordx4 v[226:227], off
	s_add_i32 m0, s28, 0x2000
	s_add_u32 s26, s26, 0x40080
	v_lshl_add_u64 v[226:227], v[228:229], 0, s[46:47]
	s_addc_u32 s27, s27, 0
	s_add_i32 s28, s68, s36
	global_load_lds_dwordx4 v[226:227], off
	v_lshl_add_u64 v[226:227], s[26:27], 0, v[148:149]
	s_mov_b32 m0, s28
	s_nop 0
	global_load_lds_dwordx4 v[226:227], off
	v_lshl_add_u64 v[226:227], s[26:27], 0, v[0:1]
	s_add_i32 m0, s28, 0x2000
	s_nop 0
	global_load_lds_dwordx4 v[226:227], off
	v_lshl_add_u64 v[226:227], v[230:231], 0, s[46:47]
	s_mov_b32 m0, s79
	s_nop 0
	global_load_lds_dwordx4 v[226:227], off
	v_lshl_add_u64 v[226:227], v[232:233], 0, s[46:47]
	s_mov_b32 m0, s34
	s_nop 0
	global_load_lds_dwordx4 v[226:227], off
	s_waitcnt vmcnt(8)
	s_waitcnt lgkmcnt(0)
	s_barrier
	s_waitcnt lgkmcnt(0)
	v_mfma_f32_16x16x32_bf16 v[64:67], v[132:135], v[182:185], v[64:67]
	v_mfma_f32_16x16x32_bf16 v[56:59], v[156:159], v[182:185], v[56:59]
	v_mfma_f32_16x16x32_bf16 v[48:51], v[132:135], v[190:193], v[48:51]
	v_mfma_f32_16x16x32_bf16 v[40:43], v[156:159], v[190:193], v[40:43]
	v_mfma_f32_16x16x32_bf16 v[32:35], v[132:135], v[198:201], v[32:35]
	v_mfma_f32_16x16x32_bf16 v[24:27], v[156:159], v[198:201], v[24:27]
	v_mfma_f32_16x16x32_bf16 v[16:19], v[132:135], v[218:221], v[16:19]
	v_mfma_f32_16x16x32_bf16 v[8:11], v[156:159], v[218:221], v[8:11]
	v_mfma_f32_16x16x32_bf16 v[64:67], v[140:143], v[186:189], v[64:67]
	v_mfma_f32_16x16x32_bf16 v[56:59], v[162:165], v[186:189], v[56:59]
	v_mfma_f32_16x16x32_bf16 v[48:51], v[140:143], v[194:197], v[48:51]
	v_mfma_f32_16x16x32_bf16 v[40:43], v[162:165], v[194:197], v[40:43]
	v_mfma_f32_16x16x32_bf16 v[32:35], v[140:143], v[214:217], v[32:35]
	v_mfma_f32_16x16x32_bf16 v[24:27], v[162:165], v[214:217], v[24:27]
	v_mfma_f32_16x16x32_bf16 v[16:19], v[140:143], v[222:225], v[16:19]
	v_mfma_f32_16x16x32_bf16 v[8:11], v[162:165], v[222:225], v[8:11]
	v_mfma_f32_16x16x32_bf16 v[60:63], v[166:169], v[182:185], v[60:63]
	v_mfma_f32_16x16x32_bf16 v[52:55], v[174:177], v[182:185], v[52:55]
	v_mfma_f32_16x16x32_bf16 v[44:47], v[166:169], v[190:193], v[44:47]
	v_mfma_f32_16x16x32_bf16 v[36:39], v[174:177], v[190:193], v[36:39]
	v_mfma_f32_16x16x32_bf16 v[28:31], v[166:169], v[198:201], v[28:31]
	v_mfma_f32_16x16x32_bf16 v[20:23], v[174:177], v[198:201], v[20:23]
	v_mfma_f32_16x16x32_bf16 v[12:15], v[166:169], v[218:221], v[12:15]
	v_mfma_f32_16x16x32_bf16 v[4:7], v[174:177], v[218:221], v[4:7]
	v_mfma_f32_16x16x32_bf16 v[60:63], v[170:173], v[186:189], v[60:63]
	v_mfma_f32_16x16x32_bf16 v[52:55], v[178:181], v[186:189], v[52:55]
	v_mfma_f32_16x16x32_bf16 v[44:47], v[170:173], v[194:197], v[44:47]
	v_mfma_f32_16x16x32_bf16 v[36:39], v[178:181], v[194:197], v[36:39]
	v_mfma_f32_16x16x32_bf16 v[28:31], v[170:173], v[214:217], v[28:31]
	v_mfma_f32_16x16x32_bf16 v[20:23], v[178:181], v[214:217], v[20:23]
	v_mfma_f32_16x16x32_bf16 v[12:15], v[170:173], v[222:225], v[12:15]
	v_mfma_f32_16x16x32_bf16 v[4:7], v[178:181], v[222:225], v[4:7]
	s_barrier
	s_add_i32 s45, s45, 2
	s_add_u32 s33, s33, 0x100
	s_addc_u32 s44, s44, 0
	s_add_u32 s24, s24, 0x100
	s_addc_u32 s25, s25, 0
.LBB0_82:
	s_add_u32 s26, s24, 0xfffc0080
	s_addc_u32 s27, s25, -1
	s_add_i32 s43, 0, 0x10000
	s_cmp_eq_u32 s45, 12
	s_cselect_b32 s29, s13, s27
	s_cselect_b32 s28, s17, s26
	s_cselect_b32 s27, s9, s44
	s_cselect_b32 s26, s22, s33
	s_add_i32 s68, 0, 0x14000
	v_add_u32_e32 v162, s43, v145
	v_add_u32_e32 v178, s68, v145
	ds_read_b128 v[132:135], v162
	ds_read_b128 v[140:143], v162 offset:1024
	ds_read_b128 v[156:159], v162 offset:2048
	ds_read_b128 v[162:165], v162 offset:3072
	ds_read_b128 v[166:169], v178
	ds_read_b128 v[170:173], v178 offset:1024
	ds_read_b128 v[174:177], v178 offset:2048
	ds_read_b128 v[178:181], v178 offset:3072
	v_lshl_add_u64 v[226:227], s[24:25], 0, v[154:155]
	s_add_i32 m0, s21, 0xc000
	ds_read_b128 v[182:185], v161
	ds_read_b128 v[186:189], v161 offset:1024
	ds_read_b128 v[190:193], v161 offset:2048
	ds_read_b128 v[194:197], v161 offset:3072
	ds_read_b128 v[198:201], v161 offset:4096
	ds_read_b128 v[214:217], v161 offset:5120
	ds_read_b128 v[218:221], v161 offset:6144
	ds_read_b128 v[222:225], v161 offset:7168
	global_load_lds_dwordx4 v[226:227], off
	v_lshl_add_u64 v[226:227], s[24:25], 0, v[152:153]
	s_add_i32 m0, s21, 0xe000
	s_nop 0
	global_load_lds_dwordx4 v[226:227], off
	s_waitcnt vmcnt(8)
	s_waitcnt lgkmcnt(0)
	s_barrier
; #define PG8_STAGE(bufoff, gbase, voff) do { _Pragma("unroll") for (int _i = 0; _i < 2; ++_i) \
;         __builtin_amdgcn_global_load_lds((const unsigned*)((const char*)(gbase) + (voff)[_i]), (LAS unsigned*)(lds + (bufoff) + ldsw + _i * 8192), 16, 0, 0); } while (0)
; #define PG8_LDA(dst, b, h) do { _Pragma("unroll") for (int m = 0; m < 4; ++m) _Pragma("unroll") for (int k = 0; k < 2; ++k) dst[m][k] = *(const LAS bf16x8*)(lds + PG8_SA(b, h) + aoff + m * 2048 + k * 1024); } while (0)
; #define PG8_LDB(dst, b, h) do { _Pragma("unroll") for (int n = 0; n < 2; ++n) _Pragma("unroll") for (int k = 0; k < 2; ++k) dst[n][k] = *(const LAS bf16x8*)(lds + PG8_SB(b, h) + boff + n * 2048 + k * 1024); } while (0)
; #define PG8_MMA(ai, bj, At, Bt) do { __builtin_amdgcn_s_setprio(1); _Pragma("unroll") for (int m = 0; m < 4; ++m) _Pragma("unroll") for (int n = 0; n < 2; ++n) _Pragma("unroll") for (int k = 0; k < 2; ++k) \
;         acc[ai][bj][m][n] = __builtin_amdgcn_mfma_f32_16x16x32_bf16(Bt[n][k], At[m][k], acc[ai][bj][m][n], 0, 0, 0); __builtin_amdgcn_s_setprio(0); } while (0)
; #define PG8_WAIT_V(n) asm volatile("s_waitcnt vmcnt(" #n ")" ::: "memory")
; #define PG8_WAIT_L(n) asm volatile("s_waitcnt lgkmcnt(" #n ")" ::: "memory")
; #define PG8_BAR __builtin_amdgcn_s_barrier()
; #define PG8_SCHED __builtin_amdgcn_sched_barrier(0)
; template <class Epi>
; __device__ __forceinline__ void gemm_phase(LAS unsigned char* lds, const Gemm g, const int G, const int cidx, const Epi& E) {
;     ...
;             PG8_WAIT_V(8); PG8_WAIT_L(0); PG8_BAR; PG8_MMA(0, 0, At, B0); PG8_MMA(0, 1, At, B1); PG8_BAR; PG8_SCHED;
;             PG8_LDA(At, 0, 1); PG8_STAGE(PG8_SB(0, 0), b2, voffB); PG8_STAGE(PG8_SB(0, 1), b2 + hstep, voffB); PG8_STAGE(PG8_SA(0, 0), a2, voffA);
;             PG8_WAIT_V(8); PG8_WAIT_L(0); PG8_BAR; PG8_MMA(1, 0, At, B0); PG8_MMA(1, 1, At, B1); PG8_BAR; PG8_SCHED;
;             PG8_LDB(B0, 1, 0); PG8_LDB(B1, 1, 1); PG8_SCHED; PG8_LDA(At, 1, 0); PG8_STAGE(PG8_SA(0, 1), a2 + hstep, voffA);
;             PG8_WAIT_V(8); PG8_WAIT_L(0); PG8_BAR; PG8_MMA(0, 0, At, B0); PG8_MMA(0, 1, At, B1); PG8_BAR; PG8_SCHED;
	s_waitcnt lgkmcnt(0)
	v_mfma_f32_16x16x32_bf16 v[128:131], v[132:135], v[182:185], v[128:131]
	v_mfma_f32_16x16x32_bf16 v[120:123], v[156:159], v[182:185], v[120:123]
	v_mfma_f32_16x16x32_bf16 v[112:115], v[132:135], v[190:193], v[112:115]
	v_mfma_f32_16x16x32_bf16 v[104:107], v[156:159], v[190:193], v[104:107]
	v_mfma_f32_16x16x32_bf16 v[96:99], v[132:135], v[198:201], v[96:99]
	v_mfma_f32_16x16x32_bf16 v[88:91], v[156:159], v[198:201], v[88:91]
	v_mfma_f32_16x16x32_bf16 v[80:83], v[132:135], v[218:221], v[80:83]
	v_mfma_f32_16x16x32_bf16 v[72:75], v[156:159], v[218:221], v[72:75]
	v_mfma_f32_16x16x32_bf16 v[128:131], v[140:143], v[186:189], v[128:131]
	v_mfma_f32_16x16x32_bf16 v[120:123], v[162:165], v[186:189], v[120:123]
	v_mfma_f32_16x16x32_bf16 v[112:115], v[140:143], v[194:197], v[112:115]
	v_mfma_f32_16x16x32_bf16 v[104:107], v[162:165], v[194:197], v[104:107]
	v_mfma_f32_16x16x32_bf16 v[96:99], v[140:143], v[214:217], v[96:99]
	v_mfma_f32_16x16x32_bf16 v[88:91], v[162:165], v[214:217], v[88:91]
	v_mfma_f32_16x16x32_bf16 v[80:83], v[140:143], v[222:225], v[80:83]
	v_mfma_f32_16x16x32_bf16 v[72:75], v[162:165], v[222:225], v[72:75]
	v_mfma_f32_16x16x32_bf16 v[124:127], v[166:169], v[182:185], v[124:127]
	v_mfma_f32_16x16x32_bf16 v[116:119], v[174:177], v[182:185], v[116:119]
	v_mfma_f32_16x16x32_bf16 v[108:111], v[166:169], v[190:193], v[108:111]
	v_mfma_f32_16x16x32_bf16 v[100:103], v[174:177], v[190:193], v[100:103]
	v_mfma_f32_16x16x32_bf16 v[92:95], v[166:169], v[198:201], v[92:95]
	v_mfma_f32_16x16x32_bf16 v[84:87], v[174:177], v[198:201], v[84:87]
	v_mfma_f32_16x16x32_bf16 v[76:79], v[166:169], v[218:221], v[76:79]
	v_mfma_f32_16x16x32_bf16 v[68:71], v[174:177], v[218:221], v[68:71]
	v_mfma_f32_16x16x32_bf16 v[124:127], v[170:173], v[186:189], v[124:127]
	v_mfma_f32_16x16x32_bf16 v[116:119], v[178:181], v[186:189], v[116:119]
	v_mfma_f32_16x16x32_bf16 v[108:111], v[170:173], v[194:197], v[108:111]
	v_mfma_f32_16x16x32_bf16 v[100:103], v[178:181], v[194:197], v[100:103]
	v_mfma_f32_16x16x32_bf16 v[92:95], v[170:173], v[214:217], v[92:95]
	v_mfma_f32_16x16x32_bf16 v[84:87], v[178:181], v[214:217], v[84:87]
	v_mfma_f32_16x16x32_bf16 v[76:79], v[170:173], v[222:225], v[76:79]
	v_mfma_f32_16x16x32_bf16 v[68:71], v[178:181], v[222:225], v[68:71]
	s_barrier
	s_add_i32 s43, s43, s36
	v_lshl_add_u64 v[226:227], s[26:27], 0, v[148:149]
	s_mov_b32 m0, s43
	ds_read_b128 v[182:185], v161 offset:16384
	ds_read_b128 v[186:189], v161 offset:17408
	ds_read_b128 v[190:193], v161 offset:18432
	ds_read_b128 v[194:197], v161 offset:19456
	ds_read_b128 v[198:201], v161 offset:20480
	ds_read_b128 v[214:217], v161 offset:21504
	ds_read_b128 v[218:221], v161 offset:22528
	ds_read_b128 v[222:225], v161 offset:23552
	global_load_lds_dwordx4 v[226:227], off
	s_add_i32 m0, s43, 0x2000
	s_add_u32 s76, s26, 0x40000
	v_lshl_add_u64 v[228:229], s[26:27], 0, v[0:1]
	s_addc_u32 s77, s27, 0
	s_add_i32 s43, s68, s36
	global_load_lds_dwordx4 v[228:229], off
	v_lshl_add_u64 v[230:231], s[76:77], 0, v[148:149]
	s_mov_b32 m0, s43
	v_lshl_add_u64 v[232:233], s[28:29], 0, v[146:147]
	global_load_lds_dwordx4 v[230:231], off
	v_lshl_add_u64 v[230:231], s[76:77], 0, v[0:1]
	s_add_i32 m0, s43, 0x2000
	s_nop 0
	global_load_lds_dwordx4 v[230:231], off
	v_lshl_add_u64 v[230:231], s[28:29], 0, v[150:151]
	s_mov_b32 m0, s21
	s_nop 0
	global_load_lds_dwordx4 v[230:231], off
	s_mov_b32 m0, s38
	s_nop 0
	global_load_lds_dwordx4 v[232:233], off
	s_waitcnt vmcnt(8)
	s_waitcnt lgkmcnt(0)
	s_barrier
	s_waitcnt lgkmcnt(0)
	v_mfma_f32_16x16x32_bf16 v[64:67], v[132:135], v[182:185], v[64:67]
	v_mfma_f32_16x16x32_bf16 v[56:59], v[156:159], v[182:185], v[56:59]
	v_mfma_f32_16x16x32_bf16 v[48:51], v[132:135], v[190:193], v[48:51]
	v_mfma_f32_16x16x32_bf16 v[40:43], v[156:159], v[190:193], v[40:43]
	v_mfma_f32_16x16x32_bf16 v[32:35], v[132:135], v[198:201], v[32:35]
	v_mfma_f32_16x16x32_bf16 v[24:27], v[156:159], v[198:201], v[24:27]
	v_mfma_f32_16x16x32_bf16 v[16:19], v[132:135], v[218:221], v[16:19]
	v_mfma_f32_16x16x32_bf16 v[8:11], v[156:159], v[218:221], v[8:11]
	v_mfma_f32_16x16x32_bf16 v[64:67], v[140:143], v[186:189], v[64:67]
	v_mfma_f32_16x16x32_bf16 v[56:59], v[162:165], v[186:189], v[56:59]
	v_mfma_f32_16x16x32_bf16 v[48:51], v[140:143], v[194:197], v[48:51]
	v_mfma_f32_16x16x32_bf16 v[40:43], v[162:165], v[194:197], v[40:43]
	v_mfma_f32_16x16x32_bf16 v[32:35], v[140:143], v[214:217], v[32:35]
	v_mfma_f32_16x16x32_bf16 v[24:27], v[162:165], v[214:217], v[24:27]
	v_mfma_f32_16x16x32_bf16 v[16:19], v[140:143], v[222:225], v[16:19]
	v_mfma_f32_16x16x32_bf16 v[8:11], v[162:165], v[222:225], v[8:11]
	v_mfma_f32_16x16x32_bf16 v[60:63], v[166:169], v[182:185], v[60:63]
	v_mfma_f32_16x16x32_bf16 v[52:55], v[174:177], v[182:185], v[52:55]
	v_mfma_f32_16x16x32_bf16 v[44:47], v[166:169], v[190:193], v[44:47]
	v_mfma_f32_16x16x32_bf16 v[36:39], v[174:177], v[190:193], v[36:39]
	v_mfma_f32_16x16x32_bf16 v[28:31], v[166:169], v[198:201], v[28:31]
	v_mfma_f32_16x16x32_bf16 v[20:23], v[174:177], v[198:201], v[20:23]
	v_mfma_f32_16x16x32_bf16 v[12:15], v[166:169], v[218:221], v[12:15]
	v_mfma_f32_16x16x32_bf16 v[4:7], v[174:177], v[218:221], v[4:7]
	v_mfma_f32_16x16x32_bf16 v[60:63], v[170:173], v[186:189], v[60:63]
	v_mfma_f32_16x16x32_bf16 v[52:55], v[178:181], v[186:189], v[52:55]
	v_mfma_f32_16x16x32_bf16 v[44:47], v[170:173], v[194:197], v[44:47]
	v_mfma_f32_16x16x32_bf16 v[36:39], v[178:181], v[194:197], v[36:39]
	v_mfma_f32_16x16x32_bf16 v[28:31], v[170:173], v[214:217], v[28:31]
	v_mfma_f32_16x16x32_bf16 v[20:23], v[178:181], v[214:217], v[20:23]
	v_mfma_f32_16x16x32_bf16 v[12:15], v[170:173], v[222:225], v[12:15]
	v_mfma_f32_16x16x32_bf16 v[4:7], v[178:181], v[222:225], v[4:7]
	s_barrier
; #define PG8_STAGE(bufoff, gbase, voff) do { _Pragma("unroll") for (int _i = 0; _i < 2; ++_i) \
;         __builtin_amdgcn_global_load_lds((const unsigned*)((const char*)(gbase) + (voff)[_i]), (LAS unsigned*)(lds + (bufoff) + ldsw + _i * 8192), 16, 0, 0); } while (0)
; #define PG8_LDA(dst, b, h) do { _Pragma("unroll") for (int m = 0; m < 4; ++m) _Pragma("unroll") for (int k = 0; k < 2; ++k) dst[m][k] = *(const LAS bf16x8*)(lds + PG8_SA(b, h) + aoff + m * 2048 + k * 1024); } while (0)
; #define PG8_LDB(dst, b, h) do { _Pragma("unroll") for (int n = 0; n < 2; ++n) _Pragma("unroll") for (int k = 0; k < 2; ++k) dst[n][k] = *(const LAS bf16x8*)(lds + PG8_SB(b, h) + boff + n * 2048 + k * 1024); } while (0)
; #define PG8_MMA(ai, bj, At, Bt) do { __builtin_amdgcn_s_setprio(1); _Pragma("unroll") for (int m = 0; m < 4; ++m) _Pragma("unroll") for (int n = 0; n < 2; ++n) _Pragma("unroll") for (int k = 0; k < 2; ++k) \
;         acc[ai][bj][m][n] = __builtin_amdgcn_mfma_f32_16x16x32_bf16(Bt[n][k], At[m][k], acc[ai][bj][m][n], 0, 0, 0); __builtin_amdgcn_s_setprio(0); } while (0)
; #define PG8_WAIT_V(n) asm volatile("s_waitcnt vmcnt(" #n ")" ::: "memory")
; #define PG8_WAIT_L(n) asm volatile("s_waitcnt lgkmcnt(" #n ")" ::: "memory")
; #define PG8_BAR __builtin_amdgcn_s_barrier()
; #define PG8_SCHED __builtin_amdgcn_sched_barrier(0)
; template <class Epi>
; __device__ __forceinline__ void gemm_phase(LAS unsigned char* lds, const Gemm g, const int G, const int cidx, const Epi& E) {
;     ...
;             PG8_LDB(B0, 1, 0); PG8_LDB(B1, 1, 1); PG8_SCHED; PG8_LDA(At, 1, 0); PG8_STAGE(PG8_SA(0, 1), a2 + hstep, voffA);
;             PG8_WAIT_V(8); PG8_WAIT_L(0); PG8_BAR; PG8_MMA(0, 0, At, B0); PG8_MMA(0, 1, At, B1); PG8_BAR; PG8_SCHED;
;             PG8_LDA(At, 1, 1); PG8_STAGE(PG8_SB(1, 0), b3, voffB); PG8_STAGE(PG8_SB(1, 1), b3 + hstep, voffB); PG8_STAGE(PG8_SA(1, 0), a3, voffA);
;             PG8_WAIT_V(8); PG8_WAIT_L(0); PG8_BAR; PG8_MMA(1, 0, At, B0); PG8_MMA(1, 1, At, B1); PG8_BAR; PG8_SCHED;
	s_add_i32 s43, 0, 0x18000
	s_add_i32 s68, 0, 0x1c000
	v_add_u32_e32 v162, s43, v145
	v_add_u32_e32 v178, s68, v145
	ds_read_b128 v[132:135], v162
	ds_read_b128 v[140:143], v162 offset:1024
	ds_read_b128 v[156:159], v162 offset:2048
	ds_read_b128 v[162:165], v162 offset:3072
	ds_read_b128 v[166:169], v178
	ds_read_b128 v[170:173], v178 offset:1024
	ds_read_b128 v[174:177], v178 offset:2048
	ds_read_b128 v[178:181], v178 offset:3072
	s_add_u32 s28, s28, 0x40000
	s_addc_u32 s29, s29, 0
	s_mov_b32 m0, s39
	v_lshl_add_u64 v[234:235], s[28:29], 0, v[150:151]
	ds_read_b128 v[182:185], v161 offset:32768
	ds_read_b128 v[186:189], v161 offset:33792
	ds_read_b128 v[190:193], v161 offset:34816
	ds_read_b128 v[194:197], v161 offset:35840
	ds_read_b128 v[198:201], v161 offset:36864
	ds_read_b128 v[214:217], v161 offset:37888
	ds_read_b128 v[218:221], v161 offset:38912
	ds_read_b128 v[222:225], v161 offset:39936
	global_load_lds_dwordx4 v[234:235], off
	v_lshl_add_u64 v[234:235], s[28:29], 0, v[146:147]
	s_mov_b32 m0, s75
	s_nop 0
	global_load_lds_dwordx4 v[234:235], off
	s_waitcnt vmcnt(8)
	s_waitcnt lgkmcnt(0)
	s_barrier
	s_waitcnt lgkmcnt(0)
	v_mfma_f32_16x16x32_bf16 v[128:131], v[132:135], v[182:185], v[128:131]
	v_mfma_f32_16x16x32_bf16 v[120:123], v[156:159], v[182:185], v[120:123]
	v_mfma_f32_16x16x32_bf16 v[112:115], v[132:135], v[190:193], v[112:115]
	v_mfma_f32_16x16x32_bf16 v[104:107], v[156:159], v[190:193], v[104:107]
	v_mfma_f32_16x16x32_bf16 v[96:99], v[132:135], v[198:201], v[96:99]
	v_mfma_f32_16x16x32_bf16 v[88:91], v[156:159], v[198:201], v[88:91]
	v_mfma_f32_16x16x32_bf16 v[80:83], v[132:135], v[218:221], v[80:83]
	v_mfma_f32_16x16x32_bf16 v[72:75], v[156:159], v[218:221], v[72:75]
	v_mfma_f32_16x16x32_bf16 v[128:131], v[140:143], v[186:189], v[128:131]
	v_mfma_f32_16x16x32_bf16 v[120:123], v[162:165], v[186:189], v[120:123]
	v_mfma_f32_16x16x32_bf16 v[112:115], v[140:143], v[194:197], v[112:115]
	v_mfma_f32_16x16x32_bf16 v[104:107], v[162:165], v[194:197], v[104:107]
	v_mfma_f32_16x16x32_bf16 v[96:99], v[140:143], v[214:217], v[96:99]
	v_mfma_f32_16x16x32_bf16 v[88:91], v[162:165], v[214:217], v[88:91]
	v_mfma_f32_16x16x32_bf16 v[80:83], v[140:143], v[222:225], v[80:83]
	v_mfma_f32_16x16x32_bf16 v[72:75], v[162:165], v[222:225], v[72:75]
	v_mfma_f32_16x16x32_bf16 v[124:127], v[166:169], v[182:185], v[124:127]
	v_mfma_f32_16x16x32_bf16 v[116:119], v[174:177], v[182:185], v[116:119]
	v_mfma_f32_16x16x32_bf16 v[108:111], v[166:169], v[190:193], v[108:111]
	v_mfma_f32_16x16x32_bf16 v[100:103], v[174:177], v[190:193], v[100:103]
	v_mfma_f32_16x16x32_bf16 v[92:95], v[166:169], v[198:201], v[92:95]
	v_mfma_f32_16x16x32_bf16 v[84:87], v[174:177], v[198:201], v[84:87]
	v_mfma_f32_16x16x32_bf16 v[76:79], v[166:169], v[218:221], v[76:79]
	v_mfma_f32_16x16x32_bf16 v[68:71], v[174:177], v[218:221], v[68:71]
	v_mfma_f32_16x16x32_bf16 v[124:127], v[170:173], v[186:189], v[124:127]
	v_mfma_f32_16x16x32_bf16 v[116:119], v[178:181], v[186:189], v[116:119]
	v_mfma_f32_16x16x32_bf16 v[108:111], v[170:173], v[194:197], v[108:111]
	v_mfma_f32_16x16x32_bf16 v[100:103], v[178:181], v[194:197], v[100:103]
	v_mfma_f32_16x16x32_bf16 v[92:95], v[170:173], v[214:217], v[92:95]
	v_mfma_f32_16x16x32_bf16 v[84:87], v[178:181], v[214:217], v[84:87]
	v_mfma_f32_16x16x32_bf16 v[76:79], v[170:173], v[222:225], v[76:79]
	v_mfma_f32_16x16x32_bf16 v[68:71], v[178:181], v[222:225], v[68:71]
	s_barrier
	s_add_i32 s28, s43, s36
	v_lshl_add_u64 v[226:227], v[226:227], 0, s[46:47]
	s_mov_b32 m0, s28
	ds_read_b128 v[182:185], v161 offset:49152
	ds_read_b128 v[186:189], v161 offset:50176
	ds_read_b128 v[190:193], v161 offset:51200
	ds_read_b128 v[194:197], v161 offset:52224
	ds_read_b128 v[198:201], v161 offset:53248
	ds_read_b128 v[214:217], v161 offset:54272
	ds_read_b128 v[218:221], v161 offset:55296
	ds_read_b128 v[222:225], v161 offset:56320
	global_load_lds_dwordx4 v[226:227], off
	s_add_i32 m0, s28, 0x2000
	s_add_u32 s26, s26, 0x40080
	v_lshl_add_u64 v[226:227], v[228:229], 0, s[46:47]
	s_addc_u32 s27, s27, 0
	s_add_i32 s28, s68, s36
	global_load_lds_dwordx4 v[226:227], off
	v_lshl_add_u64 v[226:227], s[26:27], 0, v[148:149]
	s_mov_b32 m0, s28
	s_nop 0
	global_load_lds_dwordx4 v[226:227], off
	v_lshl_add_u64 v[226:227], s[26:27], 0, v[0:1]
	s_add_i32 m0, s28, 0x2000
	s_nop 0
	global_load_lds_dwordx4 v[226:227], off
	v_lshl_add_u64 v[226:227], v[230:231], 0, s[46:47]
	s_mov_b32 m0, s79
	s_nop 0
	global_load_lds_dwordx4 v[226:227], off
	v_lshl_add_u64 v[226:227], v[232:233], 0, s[46:47]
	s_mov_b32 m0, s34
	s_nop 0
	global_load_lds_dwordx4 v[226:227], off
	s_waitcnt vmcnt(8)
	s_waitcnt lgkmcnt(0)
	s_barrier
; __device__ __forceinline__ unsigned pk2(float lo, float hi) { unsigned r; asm("v_cvt_pk_bf16_f32 %0, %1, %2" : "=v"(r) : "v"(lo), "v"(hi)); return r; }
; __device__ __forceinline__ float silu(float x) { return x * sigm(x); }
; #define PG8_MMA(ai, bj, At, Bt) do { __builtin_amdgcn_s_setprio(1); _Pragma("unroll") for (int m = 0; m < 4; ++m) _Pragma("unroll") for (int n = 0; n < 2; ++n) _Pragma("unroll") for (int k = 0; k < 2; ++k) \
;         acc[ai][bj][m][n] = __builtin_amdgcn_mfma_f32_16x16x32_bf16(Bt[n][k], At[m][k], acc[ai][bj][m][n], 0, 0, 0); __builtin_amdgcn_s_setprio(0); } while (0)
; #define PG8_WAIT_V(n) asm volatile("s_waitcnt vmcnt(" #n ")" ::: "memory")
; #define PG8_WAIT_L(n) asm volatile("s_waitcnt lgkmcnt(" #n ")" ::: "memory")
; #define PG8_BAR __builtin_amdgcn_s_barrier()
; #define PG8_SCHED __builtin_amdgcn_sched_barrier(0)
;     __device__ __forceinline__ void operator()(const f32x4 (&acc)[2][2][4][2], const Unit& u, int wr, int wc, int fr, int fq) const {
;         const int row0 = u.pm * BM + wr * 64 + fr, col0 = u.pn * HALF + wc * 32 + 8 * fq;
; #pragma unroll
;         for (int ai = 0; ai < 2; ++ai)
; #pragma unroll
;             for (int m = 0; m < 4; ++m) { bf16_t* rowp = O + (size_t)(row0 + ai * HALF + m * 16) * ldc + col0;
;                 const f32x4 g0 = acc[ai][0][m][0], g1 = acc[ai][0][m][1], u0 = acc[ai][1][m][0], u1 = acc[ai][1][m][1];
;                 u32x4 w; w.x = pk2(silu(g0[0]) * u0[0], silu(g0[1]) * u0[1]); w.y = pk2(silu(g0[2]) * u0[2], silu(g0[3]) * u0[3]);
;                 w.z = pk2(silu(g1[0]) * u1[0], silu(g1[1]) * u1[1]); w.w = pk2(silu(g1[2]) * u1[2], silu(g1[3]) * u1[3]);
;                 *(u32x4*)rowp = w; }
; template <class Epi>
; __device__ __forceinline__ void gemm_phase(LAS unsigned char* lds, const Gemm g, const int G, const int cidx, const Epi& E) {
;     ...
;             PG8_WAIT_V(8); PG8_WAIT_L(0); PG8_BAR; PG8_MMA(1, 0, At, B0); PG8_MMA(1, 1, At, B1); PG8_BAR; PG8_SCHED;
;         }
	s_waitcnt lgkmcnt(0)
	v_mfma_f32_16x16x32_bf16 v[64:67], v[132:135], v[182:185], v[64:67]
	v_mfma_f32_16x16x32_bf16 v[56:59], v[156:159], v[182:185], v[56:59]
	v_mfma_f32_16x16x32_bf16 v[48:51], v[132:135], v[190:193], v[48:51]
	v_mfma_f32_16x16x32_bf16 v[40:43], v[156:159], v[190:193], v[40:43]
	v_mfma_f32_16x16x32_bf16 v[32:35], v[132:135], v[198:201], v[32:35]
	v_mfma_f32_16x16x32_bf16 v[24:27], v[156:159], v[198:201], v[24:27]
	v_mfma_f32_16x16x32_bf16 v[16:19], v[132:135], v[218:221], v[16:19]
	v_mfma_f32_16x16x32_bf16 v[8:11], v[156:159], v[218:221], v[8:11]
	v_mfma_f32_16x16x32_bf16 v[64:67], v[140:143], v[186:189], v[64:67]
	v_mfma_f32_16x16x32_bf16 v[56:59], v[162:165], v[186:189], v[56:59]
	v_mfma_f32_16x16x32_bf16 v[48:51], v[140:143], v[194:197], v[48:51]
	v_mfma_f32_16x16x32_bf16 v[40:43], v[162:165], v[194:197], v[40:43]
	v_mfma_f32_16x16x32_bf16 v[32:35], v[140:143], v[214:217], v[32:35]
	v_mfma_f32_16x16x32_bf16 v[24:27], v[162:165], v[214:217], v[24:27]
	v_mfma_f32_16x16x32_bf16 v[16:19], v[140:143], v[222:225], v[16:19]
	v_mfma_f32_16x16x32_bf16 v[8:11], v[162:165], v[222:225], v[8:11]
	v_mfma_f32_16x16x32_bf16 v[60:63], v[166:169], v[182:185], v[60:63]
	v_mfma_f32_16x16x32_bf16 v[52:55], v[174:177], v[182:185], v[52:55]
	v_mfma_f32_16x16x32_bf16 v[44:47], v[166:169], v[190:193], v[44:47]
	v_mfma_f32_16x16x32_bf16 v[36:39], v[174:177], v[190:193], v[36:39]
	v_mfma_f32_16x16x32_bf16 v[28:31], v[166:169], v[198:201], v[28:31]
	v_mfma_f32_16x16x32_bf16 v[20:23], v[174:177], v[198:201], v[20:23]
	v_mfma_f32_16x16x32_bf16 v[12:15], v[166:169], v[218:221], v[12:15]
	v_mfma_f32_16x16x32_bf16 v[4:7], v[174:177], v[218:221], v[4:7]
	v_mfma_f32_16x16x32_bf16 v[60:63], v[170:173], v[186:189], v[60:63]
	v_mfma_f32_16x16x32_bf16 v[52:55], v[178:181], v[186:189], v[52:55]
	v_mfma_f32_16x16x32_bf16 v[44:47], v[170:173], v[194:197], v[44:47]
	v_mfma_f32_16x16x32_bf16 v[36:39], v[178:181], v[194:197], v[36:39]
	v_mfma_f32_16x16x32_bf16 v[28:31], v[170:173], v[214:217], v[28:31]
	v_mfma_f32_16x16x32_bf16 v[20:23], v[178:181], v[214:217], v[20:23]
	v_mfma_f32_16x16x32_bf16 v[12:15], v[170:173], v[222:225], v[12:15]
	v_mfma_f32_16x16x32_bf16 v[4:7], v[178:181], v[222:225], v[4:7]
	s_barrier
	s_add_i32 s45, s45, 2
	s_add_u32 s33, s33, 0x100
	s_addc_u32 s44, s44, 0
	s_add_u32 s24, s24, 0x100
	s_addc_u32 s25, s25, 0
	s_cmp_gt_u32 s45, 13
	s_cbranch_scc0 .LBB0_82
	v_lshl_or_b32 v132, s16, 7, v160
	v_lshl_add_u32 v162, s20, 8, v3
	v_ashrrev_i32_e32 v133, 31, v132
	v_mov_b64_e32 v[156:157], s[6:7]
	s_movk_i32 s9, 0x1600
	v_mad_i64_i32 v[134:135], s[16:17], v162, s9, v[156:157]
	v_lshlrev_b64 v[158:159], 1, v[132:133]
	v_lshl_add_u64 v[132:133], v[134:135], 0, v[158:159]
	v_mul_f32_e32 v134, 0xbfb8aa3b, v128
	v_exp_f32_e32 v134, v134
	s_and_b64 vcc, exec, s[4:5]
	s_mov_b32 s20, s12
	s_mov_b64 s[24:25], s[18:19]
	v_add_f32_e32 v134, 1.0, v134
	v_rcp_f32_e32 v134, v134
	s_mov_b64 s[26:27], s[14:15]
	v_mul_f32_e32 v128, v128, v134
	v_mul_f32_e32 v124, v128, v124
	v_mul_f32_e32 v128, 0xbfb8aa3b, v129
	v_exp_f32_e32 v128, v128
	s_nop 0
	v_add_f32_e32 v128, 1.0, v128
	v_rcp_f32_e32 v128, v128
	s_nop 0
	v_mul_f32_e32 v128, v129, v128
	v_mul_f32_e32 v125, v128, v125
	v_cvt_pk_bf16_f32 v124, v124, v125
	v_mul_f32_e32 v125, 0xbfb8aa3b, v130
	v_exp_f32_e32 v125, v125
	s_nop 0
	v_add_f32_e32 v125, 1.0, v125
	v_rcp_f32_e32 v125, v125
	s_nop 0
	v_mul_f32_e32 v125, v130, v125
	v_mul_f32_e32 v125, v125, v126
	v_mul_f32_e32 v126, 0xbfb8aa3b, v131
	v_exp_f32_e32 v126, v126
	s_nop 0
	v_add_f32_e32 v126, 1.0, v126
	v_rcp_f32_e32 v126, v126
	s_nop 0
	v_mul_f32_e32 v126, v131, v126
	v_mul_f32_e32 v126, v126, v127
	v_cvt_pk_bf16_f32 v125, v125, v126
	v_mul_f32_e32 v126, 0xbfb8aa3b, v120
	v_exp_f32_e32 v126, v126
	s_nop 0
	v_add_f32_e32 v126, 1.0, v126
	v_rcp_f32_e32 v126, v126
	s_nop 0
	v_mul_f32_e32 v120, v120, v126
	v_mul_f32_e32 v116, v120, v116
	v_mul_f32_e32 v120, 0xbfb8aa3b, v121
	v_exp_f32_e32 v120, v120
	s_nop 0
	v_add_f32_e32 v120, 1.0, v120
	v_rcp_f32_e32 v120, v120
	s_nop 0
	v_mul_f32_e32 v120, v121, v120
	v_mul_f32_e32 v117, v120, v117
	v_cvt_pk_bf16_f32 v126, v116, v117
	v_mul_f32_e32 v116, 0xbfb8aa3b, v122
	v_exp_f32_e32 v116, v116
	v_mul_f32_e32 v117, 0xbfb8aa3b, v123
	v_exp_f32_e32 v117, v117
	v_add_f32_e32 v116, 1.0, v116
	v_rcp_f32_e32 v116, v116
	v_add_f32_e32 v117, 1.0, v117
	v_rcp_f32_e32 v117, v117
	v_mul_f32_e32 v116, v122, v116
	v_mul_f32_e32 v116, v116, v118
	v_mul_f32_e32 v118, 0xbfb8aa3b, v112
	v_exp_f32_e32 v118, v118
	v_mul_f32_e32 v117, v123, v117
	v_mul_f32_e32 v117, v117, v119
	v_cvt_pk_bf16_f32 v127, v116, v117
	v_add_f32_e32 v118, 1.0, v118
	v_rcp_f32_e32 v118, v118
	s_mov_b64 s[98:99], 0x16000
	v_mul_f32_e32 v112, v112, v118
	v_mul_f32_e32 v108, v112, v108
	v_mul_f32_e32 v112, 0xbfb8aa3b, v113
	v_exp_f32_e32 v112, v112
	v_lshl_add_u64 v[116:117], v[132:133], 0, s[98:99]
	global_store_dwordx4 v[132:133], v[124:127], off
	v_add_f32_e32 v112, 1.0, v112
	v_rcp_f32_e32 v112, v112
	s_nop 0
	v_mul_f32_e32 v112, v113, v112
	v_mul_f32_e32 v109, v112, v109
	v_cvt_pk_bf16_f32 v108, v108, v109
	v_mul_f32_e32 v109, 0xbfb8aa3b, v114
	v_exp_f32_e32 v109, v109
	s_nop 0
	v_add_f32_e32 v109, 1.0, v109
	v_rcp_f32_e32 v109, v109
	s_nop 0
	v_mul_f32_e32 v109, v114, v109
	v_mul_f32_e32 v109, v109, v110
	v_mul_f32_e32 v110, 0xbfb8aa3b, v115
	v_exp_f32_e32 v110, v110
	s_nop 0
	v_add_f32_e32 v110, 1.0, v110
	v_rcp_f32_e32 v110, v110
	s_nop 0
	v_mul_f32_e32 v110, v115, v110
	v_mul_f32_e32 v110, v110, v111
	v_cvt_pk_bf16_f32 v109, v109, v110
	v_mul_f32_e32 v110, 0xbfb8aa3b, v104
	v_exp_f32_e32 v110, v110
	s_nop 0
	v_add_f32_e32 v110, 1.0, v110
; __device__ __forceinline__ unsigned pk2(float lo, float hi) { unsigned r; asm("v_cvt_pk_bf16_f32 %0, %1, %2" : "=v"(r) : "v"(lo), "v"(hi)); return r; }
; __device__ __forceinline__ float silu(float x) { return x * sigm(x); }
;     __device__ __forceinline__ void operator()(const f32x4 (&acc)[2][2][4][2], const Unit& u, int wr, int wc, int fr, int fq) const {
;     ...
;             for (int m = 0; m < 4; ++m) { bf16_t* rowp = O + (size_t)(row0 + ai * HALF + m * 16) * ldc + col0;
;                 const f32x4 g0 = acc[ai][0][m][0], g1 = acc[ai][0][m][1], u0 = acc[ai][1][m][0], u1 = acc[ai][1][m][1];
;                 u32x4 w; w.x = pk2(silu(g0[0]) * u0[0], silu(g0[1]) * u0[1]); w.y = pk2(silu(g0[2]) * u0[2], silu(g0[3]) * u0[3]);
;                 w.z = pk2(silu(g1[0]) * u1[0], silu(g1[1]) * u1[1]); w.w = pk2(silu(g1[2]) * u1[2], silu(g1[3]) * u1[3]);
;                 *(u32x4*)rowp = w; }
	v_rcp_f32_e32 v110, v110
	s_nop 0
	v_mul_f32_e32 v104, v104, v110
	v_mul_f32_e32 v100, v104, v100
	v_mul_f32_e32 v104, 0xbfb8aa3b, v105
	v_exp_f32_e32 v104, v104
	s_nop 0
	v_add_f32_e32 v104, 1.0, v104
	v_rcp_f32_e32 v104, v104
	s_nop 0
	v_mul_f32_e32 v104, v105, v104
	v_mul_f32_e32 v101, v104, v101
	v_cvt_pk_bf16_f32 v110, v100, v101
	v_mul_f32_e32 v100, 0xbfb8aa3b, v106
	v_exp_f32_e32 v100, v100
	v_mul_f32_e32 v101, 0xbfb8aa3b, v107
	v_exp_f32_e32 v101, v101
	v_add_f32_e32 v100, 1.0, v100
	v_rcp_f32_e32 v100, v100
	v_add_f32_e32 v101, 1.0, v101
	v_rcp_f32_e32 v101, v101
	v_mul_f32_e32 v100, v106, v100
	v_mul_f32_e32 v100, v100, v102
	v_mul_f32_e32 v102, 0xbfb8aa3b, v96
	v_exp_f32_e32 v102, v102
	v_mul_f32_e32 v101, v107, v101
	v_mul_f32_e32 v101, v101, v103
	v_cvt_pk_bf16_f32 v111, v100, v101
	v_add_f32_e32 v102, 1.0, v102
	v_rcp_f32_e32 v102, v102
	s_mov_b64 s[98:99], 0x2c000
	v_mul_f32_e32 v96, v96, v102
	v_mul_f32_e32 v92, v96, v92
	v_mul_f32_e32 v96, 0xbfb8aa3b, v97
	v_exp_f32_e32 v96, v96
	v_lshl_add_u64 v[100:101], v[132:133], 0, s[98:99]
	global_store_dwordx4 v[116:117], v[108:111], off
	v_add_f32_e32 v96, 1.0, v96
	v_rcp_f32_e32 v96, v96
	s_nop 0
	v_mul_f32_e32 v96, v97, v96
	v_mul_f32_e32 v93, v96, v93
	v_cvt_pk_bf16_f32 v92, v92, v93
	v_mul_f32_e32 v93, 0xbfb8aa3b, v98
	v_exp_f32_e32 v93, v93
	s_nop 0
	v_add_f32_e32 v93, 1.0, v93
	v_rcp_f32_e32 v93, v93
	s_nop 0
	v_mul_f32_e32 v93, v98, v93
	v_mul_f32_e32 v93, v93, v94
	v_mul_f32_e32 v94, 0xbfb8aa3b, v99
	v_exp_f32_e32 v94, v94
	s_nop 0
	v_add_f32_e32 v94, 1.0, v94
	v_rcp_f32_e32 v94, v94
	s_nop 0
	v_mul_f32_e32 v94, v99, v94
	v_mul_f32_e32 v94, v94, v95
	v_cvt_pk_bf16_f32 v93, v93, v94
	v_mul_f32_e32 v94, 0xbfb8aa3b, v88
	v_exp_f32_e32 v94, v94
	s_nop 0
	v_add_f32_e32 v94, 1.0, v94
	v_rcp_f32_e32 v94, v94
	s_nop 0
	v_mul_f32_e32 v88, v88, v94
	v_mul_f32_e32 v84, v88, v84
	v_mul_f32_e32 v88, 0xbfb8aa3b, v89
	v_exp_f32_e32 v88, v88
	s_nop 0
	v_add_f32_e32 v88, 1.0, v88
	v_rcp_f32_e32 v88, v88
	s_nop 0
	v_mul_f32_e32 v88, v89, v88
	v_mul_f32_e32 v85, v88, v85
	v_cvt_pk_bf16_f32 v94, v84, v85
	v_mul_f32_e32 v84, 0xbfb8aa3b, v90
	v_exp_f32_e32 v84, v84
	v_mul_f32_e32 v85, 0xbfb8aa3b, v91
	v_exp_f32_e32 v85, v85
	v_add_f32_e32 v84, 1.0, v84
	v_rcp_f32_e32 v84, v84
	v_add_f32_e32 v85, 1.0, v85
	v_rcp_f32_e32 v85, v85
	v_mul_f32_e32 v84, v90, v84
	v_mul_f32_e32 v84, v84, v86
	v_mul_f32_e32 v86, 0xbfb8aa3b, v80
	v_exp_f32_e32 v86, v86
	v_mul_f32_e32 v85, v91, v85
	v_mul_f32_e32 v85, v85, v87
	v_cvt_pk_bf16_f32 v95, v84, v85
	v_add_f32_e32 v86, 1.0, v86
	v_rcp_f32_e32 v86, v86
	s_mov_b64 s[98:99], 0x42000
	v_mul_f32_e32 v80, v80, v86
	v_mul_f32_e32 v76, v80, v76
	v_mul_f32_e32 v80, 0xbfb8aa3b, v81
	v_exp_f32_e32 v80, v80
	v_lshl_add_u64 v[84:85], v[132:133], 0, s[98:99]
	global_store_dwordx4 v[100:101], v[92:95], off
	v_add_f32_e32 v80, 1.0, v80
	v_rcp_f32_e32 v80, v80
	s_nop 0
	v_mul_f32_e32 v80, v81, v80
	v_mul_f32_e32 v77, v80, v77
	v_cvt_pk_bf16_f32 v76, v76, v77
	v_mul_f32_e32 v77, 0xbfb8aa3b, v82
	v_exp_f32_e32 v77, v77
	s_nop 0
	v_add_f32_e32 v77, 1.0, v77
	v_rcp_f32_e32 v77, v77
	s_nop 0
	v_mul_f32_e32 v77, v82, v77
	v_mul_f32_e32 v77, v77, v78
	v_mul_f32_e32 v78, 0xbfb8aa3b, v83
	v_exp_f32_e32 v78, v78
	s_nop 0
	v_add_f32_e32 v78, 1.0, v78
	v_rcp_f32_e32 v78, v78
	s_nop 0
	v_mul_f32_e32 v78, v83, v78
	v_mul_f32_e32 v78, v78, v79
	v_cvt_pk_bf16_f32 v77, v77, v78
	v_mul_f32_e32 v78, 0xbfb8aa3b, v72
	v_exp_f32_e32 v78, v78
	s_nop 0
	v_add_f32_e32 v78, 1.0, v78
	v_rcp_f32_e32 v78, v78
	s_nop 0
	v_mul_f32_e32 v72, v72, v78
	v_mul_f32_e32 v68, v72, v68
	v_mul_f32_e32 v72, 0xbfb8aa3b, v73
	v_exp_f32_e32 v72, v72
	s_nop 0
	v_add_f32_e32 v72, 1.0, v72
	v_rcp_f32_e32 v72, v72
	s_nop 0
	v_mul_f32_e32 v72, v73, v72
	v_mul_f32_e32 v69, v72, v69
	v_cvt_pk_bf16_f32 v78, v68, v69
	v_mul_f32_e32 v68, 0xbfb8aa3b, v74
	v_exp_f32_e32 v68, v68
	v_mul_f32_e32 v69, 0xbfb8aa3b, v75
	v_exp_f32_e32 v69, v69
	v_add_f32_e32 v68, 1.0, v68
	v_rcp_f32_e32 v68, v68
	v_add_f32_e32 v69, 1.0, v69
	v_rcp_f32_e32 v69, v69
	v_mul_f32_e32 v68, v74, v68
	v_mul_f32_e32 v68, v68, v70
	v_mul_f32_e32 v70, 0xbfb8aa3b, v64
	v_exp_f32_e32 v70, v70
	v_mul_f32_e32 v69, v75, v69
	v_mul_f32_e32 v69, v69, v71
	v_cvt_pk_bf16_f32 v79, v68, v69
	v_add_f32_e32 v70, 1.0, v70
	v_rcp_f32_e32 v70, v70
	s_mov_b64 s[98:99], 0xb0000
	v_mul_f32_e32 v64, v64, v70
	v_mul_f32_e32 v60, v64, v60
	v_mul_f32_e32 v64, 0xbfb8aa3b, v65
	v_exp_f32_e32 v64, v64
	v_lshl_add_u64 v[68:69], v[132:133], 0, s[98:99]
	global_store_dwordx4 v[84:85], v[76:79], off
	v_add_f32_e32 v64, 1.0, v64
	v_rcp_f32_e32 v64, v64
	s_nop 0
	v_mul_f32_e32 v64, v65, v64
	v_mul_f32_e32 v61, v64, v61
	v_cvt_pk_bf16_f32 v60, v60, v61
	v_mul_f32_e32 v61, 0xbfb8aa3b, v66
	v_exp_f32_e32 v61, v61
	s_nop 0
	v_add_f32_e32 v61, 1.0, v61
	v_rcp_f32_e32 v61, v61
	s_nop 0
	v_mul_f32_e32 v61, v66, v61
	v_mul_f32_e32 v61, v61, v62
	v_mul_f32_e32 v62, 0xbfb8aa3b, v67
	v_exp_f32_e32 v62, v62
	s_nop 0
	v_add_f32_e32 v62, 1.0, v62
	v_rcp_f32_e32 v62, v62
	s_nop 0
	v_mul_f32_e32 v62, v67, v62
	v_mul_f32_e32 v62, v62, v63
	v_cvt_pk_bf16_f32 v61, v61, v62
	v_mul_f32_e32 v62, 0xbfb8aa3b, v56
	v_exp_f32_e32 v62, v62
	s_nop 0
	v_add_f32_e32 v62, 1.0, v62
	v_rcp_f32_e32 v62, v62
	s_nop 0
	v_mul_f32_e32 v56, v56, v62
	v_mul_f32_e32 v52, v56, v52
	v_mul_f32_e32 v56, 0xbfb8aa3b, v57
	v_exp_f32_e32 v56, v56
	s_nop 0
	v_add_f32_e32 v56, 1.0, v56
	v_rcp_f32_e32 v56, v56
	s_nop 0
	v_mul_f32_e32 v56, v57, v56
	v_mul_f32_e32 v53, v56, v53
	v_cvt_pk_bf16_f32 v62, v52, v53
	v_mul_f32_e32 v52, 0xbfb8aa3b, v58
	v_exp_f32_e32 v52, v52
	v_mul_f32_e32 v53, 0xbfb8aa3b, v59
; __device__ __forceinline__ unsigned pk2(float lo, float hi) { unsigned r; asm("v_cvt_pk_bf16_f32 %0, %1, %2" : "=v"(r) : "v"(lo), "v"(hi)); return r; }
; __device__ __forceinline__ float silu(float x) { return x * sigm(x); }
; #define PG8_WAIT_V(n) asm volatile("s_waitcnt vmcnt(" #n ")" ::: "memory")
; #define PG8_BAR __builtin_amdgcn_s_barrier()
;     __device__ __forceinline__ void operator()(const f32x4 (&acc)[2][2][4][2], const Unit& u, int wr, int wc, int fr, int fq) const {
;     ...
;             for (int m = 0; m < 4; ++m) { bf16_t* rowp = O + (size_t)(row0 + ai * HALF + m * 16) * ldc + col0;
;                 const f32x4 g0 = acc[ai][0][m][0], g1 = acc[ai][0][m][1], u0 = acc[ai][1][m][0], u1 = acc[ai][1][m][1];
;                 u32x4 w; w.x = pk2(silu(g0[0]) * u0[0], silu(g0[1]) * u0[1]); w.y = pk2(silu(g0[2]) * u0[2], silu(g0[3]) * u0[3]);
;                 w.z = pk2(silu(g1[0]) * u1[0], silu(g1[1]) * u1[1]); w.w = pk2(silu(g1[2]) * u1[2], silu(g1[3]) * u1[3]);
;                 *(u32x4*)rowp = w; }
; template <class Epi>
; __device__ __forceinline__ void gemm_phase(LAS unsigned char* lds, const Gemm g, const int G, const int cidx, const Epi& E) {
;     ...
;         if constexpr (!Epi::AFTER_DRAIN) E(acc, cur, wr, wc, fr, fq);
;         if (!has_next) break;
; #pragma unroll
;         for (int a = 0; a < 2; ++a)
; #pragma unroll
;             for (int b = 0; b < 2; ++b)
; #pragma unroll
;                 for (int m = 0; m < 4; ++m)
; #pragma unroll
;                     for (int n = 0; n < 2; ++n) acc[a][b][m][n] = ZERO4;
;         cur = nxt; cA = nA; cB = nB; ++ui;
;     }
;     PG8_WAIT_V(0);
;     if (wr == 0) PG8_BAR;
	v_exp_f32_e32 v53, v53
	v_add_f32_e32 v52, 1.0, v52
	v_rcp_f32_e32 v52, v52
	v_add_f32_e32 v53, 1.0, v53
	v_rcp_f32_e32 v53, v53
	v_mul_f32_e32 v52, v58, v52
	v_mul_f32_e32 v52, v52, v54
	v_mul_f32_e32 v54, 0xbfb8aa3b, v48
	v_exp_f32_e32 v54, v54
	v_mul_f32_e32 v53, v59, v53
	v_mul_f32_e32 v53, v53, v55
	v_cvt_pk_bf16_f32 v63, v52, v53
	v_add_f32_e32 v54, 1.0, v54
	v_rcp_f32_e32 v54, v54
	s_mov_b64 s[98:99], 0xc6000
	v_mul_f32_e32 v48, v48, v54
	v_mul_f32_e32 v44, v48, v44
	v_mul_f32_e32 v48, 0xbfb8aa3b, v49
	v_exp_f32_e32 v48, v48
	v_lshl_add_u64 v[52:53], v[132:133], 0, s[98:99]
	global_store_dwordx4 v[68:69], v[60:63], off
	v_add_f32_e32 v48, 1.0, v48
	v_rcp_f32_e32 v48, v48
	s_nop 0
	v_mul_f32_e32 v48, v49, v48
	v_mul_f32_e32 v45, v48, v45
	v_cvt_pk_bf16_f32 v44, v44, v45
	v_mul_f32_e32 v45, 0xbfb8aa3b, v50
	v_exp_f32_e32 v45, v45
	s_nop 0
	v_add_f32_e32 v45, 1.0, v45
	v_rcp_f32_e32 v45, v45
	s_nop 0
	v_mul_f32_e32 v45, v50, v45
	v_mul_f32_e32 v45, v45, v46
	v_mul_f32_e32 v46, 0xbfb8aa3b, v51
	v_exp_f32_e32 v46, v46
	s_nop 0
	v_add_f32_e32 v46, 1.0, v46
	v_rcp_f32_e32 v46, v46
	s_nop 0
	v_mul_f32_e32 v46, v51, v46
	v_mul_f32_e32 v46, v46, v47
	v_cvt_pk_bf16_f32 v45, v45, v46
	v_mul_f32_e32 v46, 0xbfb8aa3b, v40
	v_exp_f32_e32 v46, v46
	s_nop 0
	v_add_f32_e32 v46, 1.0, v46
	v_rcp_f32_e32 v46, v46
	s_nop 0
	v_mul_f32_e32 v40, v40, v46
	v_mul_f32_e32 v36, v40, v36
	v_mul_f32_e32 v40, 0xbfb8aa3b, v41
	v_exp_f32_e32 v40, v40
	s_nop 0
	v_add_f32_e32 v40, 1.0, v40
	v_rcp_f32_e32 v40, v40
	s_nop 0
	v_mul_f32_e32 v40, v41, v40
	v_mul_f32_e32 v37, v40, v37
	v_cvt_pk_bf16_f32 v46, v36, v37
	v_mul_f32_e32 v36, 0xbfb8aa3b, v42
	v_exp_f32_e32 v36, v36
	v_mul_f32_e32 v37, 0xbfb8aa3b, v43
	v_exp_f32_e32 v37, v37
	v_add_f32_e32 v36, 1.0, v36
	v_rcp_f32_e32 v36, v36
	v_add_f32_e32 v37, 1.0, v37
	v_rcp_f32_e32 v37, v37
	v_mul_f32_e32 v36, v42, v36
	v_mul_f32_e32 v36, v36, v38
	v_mul_f32_e32 v38, 0xbfb8aa3b, v32
	v_exp_f32_e32 v38, v38
	v_mul_f32_e32 v37, v43, v37
	v_mul_f32_e32 v37, v37, v39
	v_cvt_pk_bf16_f32 v47, v36, v37
	v_add_f32_e32 v38, 1.0, v38
	v_rcp_f32_e32 v38, v38
	s_mov_b64 s[98:99], 0xdc000
	v_mul_f32_e32 v32, v32, v38
	v_mul_f32_e32 v28, v32, v28
	v_mul_f32_e32 v32, 0xbfb8aa3b, v33
	v_exp_f32_e32 v32, v32
	v_lshl_add_u64 v[36:37], v[132:133], 0, s[98:99]
	global_store_dwordx4 v[52:53], v[44:47], off
	v_add_f32_e32 v32, 1.0, v32
	v_rcp_f32_e32 v32, v32
	s_nop 0
	v_mul_f32_e32 v32, v33, v32
	v_mul_f32_e32 v29, v32, v29
	v_cvt_pk_bf16_f32 v28, v28, v29
	v_mul_f32_e32 v29, 0xbfb8aa3b, v34
	v_exp_f32_e32 v29, v29
	s_nop 0
	v_add_f32_e32 v29, 1.0, v29
	v_rcp_f32_e32 v29, v29
	s_nop 0
	v_mul_f32_e32 v29, v34, v29
	v_mul_f32_e32 v29, v29, v30
	v_mul_f32_e32 v30, 0xbfb8aa3b, v35
	v_exp_f32_e32 v30, v30
	s_nop 0
	v_add_f32_e32 v30, 1.0, v30
	v_rcp_f32_e32 v30, v30
	s_nop 0
	v_mul_f32_e32 v30, v35, v30
	v_mul_f32_e32 v30, v30, v31
	v_cvt_pk_bf16_f32 v29, v29, v30
	v_mul_f32_e32 v30, 0xbfb8aa3b, v24
	v_exp_f32_e32 v30, v30
	s_nop 0
	v_add_f32_e32 v30, 1.0, v30
	v_rcp_f32_e32 v30, v30
	s_nop 0
	v_mul_f32_e32 v24, v24, v30
	v_mul_f32_e32 v20, v24, v20
	v_mul_f32_e32 v24, 0xbfb8aa3b, v25
	v_exp_f32_e32 v24, v24
	s_nop 0
	v_add_f32_e32 v24, 1.0, v24
	v_rcp_f32_e32 v24, v24
	s_nop 0
	v_mul_f32_e32 v24, v25, v24
	v_mul_f32_e32 v21, v24, v21
	v_cvt_pk_bf16_f32 v30, v20, v21
	v_mul_f32_e32 v20, 0xbfb8aa3b, v26
	v_exp_f32_e32 v20, v20
	v_mul_f32_e32 v21, 0xbfb8aa3b, v27
	v_exp_f32_e32 v21, v21
	v_add_f32_e32 v20, 1.0, v20
	v_rcp_f32_e32 v20, v20
	v_add_f32_e32 v21, 1.0, v21
	v_rcp_f32_e32 v21, v21
	v_mul_f32_e32 v20, v26, v20
	v_mul_f32_e32 v20, v20, v22
	v_mul_f32_e32 v22, 0xbfb8aa3b, v16
	v_exp_f32_e32 v22, v22
	v_mul_f32_e32 v21, v27, v21
	v_mul_f32_e32 v21, v21, v23
	v_cvt_pk_bf16_f32 v31, v20, v21
	v_add_f32_e32 v22, 1.0, v22
	v_rcp_f32_e32 v22, v22
	s_mov_b64 s[98:99], 0xf2000
	v_mul_f32_e32 v16, v16, v22
	v_mul_f32_e32 v12, v16, v12
	v_mul_f32_e32 v16, 0xbfb8aa3b, v17
	v_exp_f32_e32 v16, v16
	v_lshl_add_u64 v[20:21], v[132:133], 0, s[98:99]
	s_mov_b32 s16, s8
	global_store_dwordx4 v[36:37], v[28:31], off
	v_add_f32_e32 v16, 1.0, v16
	v_rcp_f32_e32 v16, v16
	s_nop 0
	v_mul_f32_e32 v16, v17, v16
	v_mul_f32_e32 v13, v16, v13
	v_cvt_pk_bf16_f32 v12, v12, v13
	v_mul_f32_e32 v13, 0xbfb8aa3b, v18
	v_exp_f32_e32 v13, v13
	s_nop 0
	v_add_f32_e32 v13, 1.0, v13
	v_rcp_f32_e32 v13, v13
	s_nop 0
	v_mul_f32_e32 v13, v18, v13
	v_mul_f32_e32 v13, v13, v14
	v_mul_f32_e32 v14, 0xbfb8aa3b, v19
	v_exp_f32_e32 v14, v14
	s_nop 0
	v_add_f32_e32 v14, 1.0, v14
	v_rcp_f32_e32 v14, v14
	s_nop 0
	v_mul_f32_e32 v14, v19, v14
	v_mul_f32_e32 v14, v14, v15
	v_cvt_pk_bf16_f32 v13, v13, v14
	v_mul_f32_e32 v14, 0xbfb8aa3b, v8
	v_exp_f32_e32 v14, v14
	s_nop 0
	v_add_f32_e32 v14, 1.0, v14
	v_rcp_f32_e32 v14, v14
	s_nop 0
	v_mul_f32_e32 v8, v8, v14
	v_mul_f32_e32 v4, v8, v4
	v_mul_f32_e32 v8, 0xbfb8aa3b, v9
	v_exp_f32_e32 v8, v8
	s_nop 0
	v_add_f32_e32 v8, 1.0, v8
	v_rcp_f32_e32 v8, v8
	s_nop 0
	v_mul_f32_e32 v8, v9, v8
	v_mul_f32_e32 v5, v8, v5
	v_cvt_pk_bf16_f32 v14, v4, v5
	v_mul_f32_e32 v4, 0xbfb8aa3b, v10
	v_mul_f32_e32 v5, 0xbfb8aa3b, v11
	v_exp_f32_e32 v4, v4
	v_exp_f32_e32 v5, v5
	v_add_f32_e32 v4, 1.0, v4
	v_add_f32_e32 v5, 1.0, v5
	v_rcp_f32_e32 v4, v4
	v_rcp_f32_e32 v5, v5
	v_mul_f32_e32 v4, v10, v4
	v_mul_f32_e32 v5, v11, v5
	v_mul_f32_e32 v4, v4, v6
	v_mul_f32_e32 v5, v5, v7
	v_cvt_pk_bf16_f32 v15, v4, v5
	global_store_dwordx4 v[20:21], v[12:15], off
	s_cbranch_vccz .LBB0_79
	s_waitcnt vmcnt(0)
	s_cmpk_gt_u32 s95, 0xff
	s_mov_b32 s73, s83
	v_readlane_b32 s79, v255, 21
	s_cbranch_scc1 .LBB0_86
	s_barrier

; #define PG8_STAGE(bufoff, gbase, voff) do { _Pragma("unroll") for (int _i = 0; _i < 2; ++_i) \
;         __builtin_amdgcn_global_load_lds((const unsigned*)((const char*)(gbase) + (voff)[_i]), (LAS unsigned*)(lds + (bufoff) + ldsw + _i * 8192), 16, 0, 0); } while (0)
; #define PG8_LDA(dst, b, h) do { _Pragma("unroll") for (int m = 0; m < 4; ++m) _Pragma("unroll") for (int k = 0; k < 2; ++k) dst[m][k] = *(const LAS bf16x8*)(lds + PG8_SA(b, h) + aoff + m * 2048 + k * 1024); } while (0)
; #define PG8_LDB(dst, b, h) do { _Pragma("unroll") for (int n = 0; n < 2; ++n) _Pragma("unroll") for (int k = 0; k < 2; ++k) dst[n][k] = *(const LAS bf16x8*)(lds + PG8_SB(b, h) + boff + n * 2048 + k * 1024); } while (0)
; #define PG8_MMA(ai, bj, At, Bt) do { __builtin_amdgcn_s_setprio(1); _Pragma("unroll") for (int m = 0; m < 4; ++m) _Pragma("unroll") for (int n = 0; n < 2; ++n) _Pragma("unroll") for (int k = 0; k < 2; ++k) \
;         acc[ai][bj][m][n] = __builtin_amdgcn_mfma_f32_16x16x32_bf16(Bt[n][k], At[m][k], acc[ai][bj][m][n], 0, 0, 0); __builtin_amdgcn_s_setprio(0); } while (0)
; #define PG8_WAIT_V(n) asm volatile("s_waitcnt vmcnt(" #n ")" ::: "memory")
; template <class Epi>
; __device__ __forceinline__ void gemm_phase(LAS unsigned char* lds, const Gemm g, const int G, const int cidx, const Epi& E) {
;     ...
;         const bool has_next = S.next(ui + 1, nxt);
;         const char* nA = has_next ? PG8_ABASE(nxt) : cA; const char* nB = has_next ? (const char*)g.Bt + (size_t)nxt.pn * tstep : cB;
;         for (int t = 0; t < nt; t += 2) {
;             const bool last = (t == nt - 2);
;             const char* a1 = cA + (size_t)(t + 1) * kstep;
;             const char* a2 = last ? nA : cA + (size_t)(t + 2) * kstep; const char* b2 = last ? nB : cB + (size_t)(t + 2) * kstep;
;             const char* a3 = a2 + kstep; const char* b3 = b2 + kstep;
;             PG8_LDB(B0, 0, 0); PG8_LDB(B1, 0, 1); PG8_SCHED; PG8_LDA(At, 0, 0); PG8_STAGE(PG8_SA(1, 1), a1 + hstep, voffA);
;             PG8_WAIT_V(8); PG8_WAIT_L(0); PG8_BAR; PG8_MMA(0, 0, At, B0); PG8_MMA(0, 1, At, B1); PG8_BAR; PG8_SCHED;
;             PG8_LDA(At, 0, 1); PG8_STAGE(PG8_SB(0, 0), b2, voffB); PG8_STAGE(PG8_SB(0, 1), b2 + hstep, voffB); PG8_STAGE(PG8_SA(0, 0), a2, voffA);
;             PG8_WAIT_V(8); PG8_WAIT_L(0); PG8_BAR; PG8_MMA(1, 0, At, B0); PG8_MMA(1, 1, At, B1); PG8_BAR; PG8_SCHED;
.LBB0_215:
	s_add_u32 s43, s70, 0x100
	s_addc_u32 s44, s71, 0
	s_ashr_i32 s31, s30, 31
	s_lshl_b64 s[34:35], s[30:31], 19
	s_add_u32 s36, s12, s34
	s_addc_u32 s37, s13, s35
	s_and_b64 s[34:35], s[6:7], exec
	s_cselect_b32 s31, s37, s9
	s_cselect_b32 s45, s36, s8
	s_ashr_i32 s29, s28, 31
	s_lshl_b64 s[34:35], s[28:29], 19
	s_add_u32 s34, s17, s34
	s_addc_u32 s35, s22, s35
	s_and_b64 s[72:73], s[6:7], exec
	s_cselect_b32 s29, s35, s71
	s_cselect_b32 s68, s34, s70
	s_add_u32 s70, s8, 0x40080
	s_addc_u32 s71, s9, 0
	v_lshl_add_u64 v[0:1], s[70:71], 0, v[150:151]
	v_lshl_add_u64 v[154:155], s[70:71], 0, v[152:153]
	s_mov_b32 s77, -2
	s_mov_b64 s[70:71], 0
	s_add_u32 s72, s8, s70
	s_addc_u32 s73, s9, s71
	s_add_u32 s72, s72, 0x100
	s_addc_u32 s73, s73, 0
	s_add_u32 s83, s43, s70
	s_addc_u32 s86, s44, s71
	s_add_i32 s87, 0, 0x10000
	s_cmpk_eq_i32 s70, 0x700
	s_cselect_b32 s75, s31, s73
	s_cselect_b32 s74, s45, s72
	v_add_u32_e32 v3, s87, v158
	s_cselect_b32 s73, s29, s86
	s_cselect_b32 s72, s68, s83
	s_add_i32 s83, 0, 0x14000
	ds_read_b128 v[132:135], v3
	ds_read_b128 v[140:143], v3 offset:1024
	ds_read_b128 v[160:163], v3 offset:2048
	ds_read_b128 v[164:167], v3 offset:3072
	v_add_u32_e32 v3, s83, v158
	ds_read_b128 v[168:171], v3
	ds_read_b128 v[172:175], v3 offset:1024
	ds_read_b128 v[176:179], v3 offset:2048
	ds_read_b128 v[180:183], v3 offset:3072
	v_lshl_add_u64 v[200:201], v[154:155], 0, s[70:71]
	s_add_i32 m0, s19, 0xc000
	ds_read_b128 v[184:187], v159
	ds_read_b128 v[188:191], v159 offset:1024
	ds_read_b128 v[192:195], v159 offset:2048
	ds_read_b128 v[196:199], v159 offset:3072
	ds_read_b128 v[214:217], v159 offset:4096
	ds_read_b128 v[218:221], v159 offset:5120
	ds_read_b128 v[222:225], v159 offset:6144
	ds_read_b128 v[226:229], v159 offset:7168
	global_load_lds_dwordx4 v[200:201], off
	v_lshl_add_u64 v[200:201], v[0:1], 0, s[70:71]
	s_add_i32 m0, s19, 0xe000
	s_nop 0
	global_load_lds_dwordx4 v[200:201], off
	s_waitcnt vmcnt(8)
	s_waitcnt lgkmcnt(0)
	s_barrier
	s_waitcnt lgkmcnt(0)
	v_mfma_f32_16x16x32_bf16 v[64:67], v[132:135], v[184:187], 0
	v_mfma_f32_16x16x32_bf16 v[72:75], v[160:163], v[184:187], 0
	v_mfma_f32_16x16x32_bf16 v[92:95], v[132:135], v[192:195], 0
	v_mfma_f32_16x16x32_bf16 v[96:99], v[160:163], v[192:195], 0
	v_mfma_f32_16x16x32_bf16 v[116:119], v[132:135], v[214:217], 0
	v_mfma_f32_16x16x32_bf16 v[124:127], v[160:163], v[214:217], 0
	v_mfma_f32_16x16x32_bf16 v[112:115], v[132:135], v[222:225], 0
	v_mfma_f32_16x16x32_bf16 v[100:103], v[160:163], v[222:225], 0
	v_mfma_f32_16x16x32_bf16 v[64:67], v[140:143], v[188:191], v[64:67]
	v_mfma_f32_16x16x32_bf16 v[72:75], v[164:167], v[188:191], v[72:75]
	v_mfma_f32_16x16x32_bf16 v[92:95], v[140:143], v[196:199], v[92:95]
	v_mfma_f32_16x16x32_bf16 v[96:99], v[164:167], v[196:199], v[96:99]
	v_mfma_f32_16x16x32_bf16 v[116:119], v[140:143], v[218:221], v[116:119]
	v_mfma_f32_16x16x32_bf16 v[124:127], v[164:167], v[218:221], v[124:127]
	v_mfma_f32_16x16x32_bf16 v[112:115], v[140:143], v[226:229], v[112:115]
	v_mfma_f32_16x16x32_bf16 v[100:103], v[164:167], v[226:229], v[100:103]
	v_mfma_f32_16x16x32_bf16 v[76:79], v[168:171], v[184:187], 0
	v_mfma_f32_16x16x32_bf16 v[84:87], v[176:179], v[184:187], 0
	v_mfma_f32_16x16x32_bf16 v[104:107], v[168:171], v[192:195], 0
	v_mfma_f32_16x16x32_bf16 v[108:111], v[176:179], v[192:195], 0
	v_mfma_f32_16x16x32_bf16 v[128:131], v[168:171], v[214:217], 0
	v_mfma_f32_16x16x32_bf16 v[120:123], v[176:179], v[214:217], 0
	v_mfma_f32_16x16x32_bf16 v[88:91], v[168:171], v[222:225], 0
	v_mfma_f32_16x16x32_bf16 v[80:83], v[176:179], v[222:225], 0
	v_mfma_f32_16x16x32_bf16 v[76:79], v[172:175], v[188:191], v[76:79]
	v_mfma_f32_16x16x32_bf16 v[84:87], v[180:183], v[188:191], v[84:87]
	v_mfma_f32_16x16x32_bf16 v[104:107], v[172:175], v[196:199], v[104:107]
	v_mfma_f32_16x16x32_bf16 v[108:111], v[180:183], v[196:199], v[108:111]
	v_mfma_f32_16x16x32_bf16 v[128:131], v[172:175], v[218:221], v[128:131]
	v_mfma_f32_16x16x32_bf16 v[120:123], v[180:183], v[218:221], v[120:123]
	v_mfma_f32_16x16x32_bf16 v[88:91], v[172:175], v[226:229], v[88:91]
	v_mfma_f32_16x16x32_bf16 v[80:83], v[180:183], v[226:229], v[80:83]
	s_barrier
	s_add_i32 s86, s87, s40
	v_lshl_add_u64 v[200:201], s[72:73], 0, v[146:147]
	s_mov_b32 m0, s86
	ds_read_b128 v[184:187], v159 offset:16384
	ds_read_b128 v[188:191], v159 offset:17408
	ds_read_b128 v[192:195], v159 offset:18432
	ds_read_b128 v[196:199], v159 offset:19456
	ds_read_b128 v[214:217], v159 offset:20480
	ds_read_b128 v[218:221], v159 offset:21504
	ds_read_b128 v[222:225], v159 offset:22528
	ds_read_b128 v[226:229], v159 offset:23552
	global_load_lds_dwordx4 v[200:201], off
	s_add_i32 m0, s86, 0x2000
	s_add_u32 s86, s72, 0x40000
	v_lshl_add_u64 v[230:231], s[72:73], 0, v[148:149]
	s_addc_u32 s87, s73, 0
	s_add_i32 s83, s83, s40
	global_load_lds_dwordx4 v[230:231], off
	v_lshl_add_u64 v[232:233], s[86:87], 0, v[146:147]
	s_mov_b32 m0, s83
	v_lshl_add_u64 v[234:235], s[74:75], 0, v[148:149]
	global_load_lds_dwordx4 v[232:233], off
	v_lshl_add_u64 v[232:233], s[86:87], 0, v[148:149]
	s_add_i32 m0, s83, 0x2000
	s_nop 0
	global_load_lds_dwordx4 v[232:233], off
	v_lshl_add_u64 v[232:233], s[74:75], 0, v[146:147]
	s_mov_b32 m0, s19
	s_nop 0
	global_load_lds_dwordx4 v[232:233], off
	s_mov_b32 m0, s76
	s_nop 0
	global_load_lds_dwordx4 v[234:235], off
	s_waitcnt vmcnt(8)
	s_waitcnt lgkmcnt(0)
	s_barrier
; #define PG8_STAGE(bufoff, gbase, voff) do { _Pragma("unroll") for (int _i = 0; _i < 2; ++_i) \
;         __builtin_amdgcn_global_load_lds((const unsigned*)((const char*)(gbase) + (voff)[_i]), (LAS unsigned*)(lds + (bufoff) + ldsw + _i * 8192), 16, 0, 0); } while (0)
; #define PG8_LDA(dst, b, h) do { _Pragma("unroll") for (int m = 0; m < 4; ++m) _Pragma("unroll") for (int k = 0; k < 2; ++k) dst[m][k] = *(const LAS bf16x8*)(lds + PG8_SA(b, h) + aoff + m * 2048 + k * 1024); } while (0)
; #define PG8_LDB(dst, b, h) do { _Pragma("unroll") for (int n = 0; n < 2; ++n) _Pragma("unroll") for (int k = 0; k < 2; ++k) dst[n][k] = *(const LAS bf16x8*)(lds + PG8_SB(b, h) + boff + n * 2048 + k * 1024); } while (0)
; #define PG8_MMA(ai, bj, At, Bt) do { __builtin_amdgcn_s_setprio(1); _Pragma("unroll") for (int m = 0; m < 4; ++m) _Pragma("unroll") for (int n = 0; n < 2; ++n) _Pragma("unroll") for (int k = 0; k < 2; ++k) \
;         acc[ai][bj][m][n] = __builtin_amdgcn_mfma_f32_16x16x32_bf16(Bt[n][k], At[m][k], acc[ai][bj][m][n], 0, 0, 0); __builtin_amdgcn_s_setprio(0); } while (0)
; #define PG8_WAIT_V(n) asm volatile("s_waitcnt vmcnt(" #n ")" ::: "memory")
; #define PG8_WAIT_L(n) asm volatile("s_waitcnt lgkmcnt(" #n ")" ::: "memory")
; #define PG8_BAR __builtin_amdgcn_s_barrier()
; #define PG8_SCHED __builtin_amdgcn_sched_barrier(0)
; template <class Epi>
; __device__ __forceinline__ void gemm_phase(LAS unsigned char* lds, const Gemm g, const int G, const int cidx, const Epi& E) {
;     ...
;             PG8_WAIT_V(8); PG8_WAIT_L(0); PG8_BAR; PG8_MMA(1, 0, At, B0); PG8_MMA(1, 1, At, B1); PG8_BAR; PG8_SCHED;
;             PG8_LDB(B0, 1, 0); PG8_LDB(B1, 1, 1); PG8_SCHED; PG8_LDA(At, 1, 0); PG8_STAGE(PG8_SA(0, 1), a2 + hstep, voffA);
;             PG8_WAIT_V(8); PG8_WAIT_L(0); PG8_BAR; PG8_MMA(0, 0, At, B0); PG8_MMA(0, 1, At, B1); PG8_BAR; PG8_SCHED;
;             PG8_LDA(At, 1, 1); PG8_STAGE(PG8_SB(1, 0), b3, voffB); PG8_STAGE(PG8_SB(1, 1), b3 + hstep, voffB); PG8_STAGE(PG8_SA(1, 0), a3, voffA);
;             PG8_WAIT_V(8); PG8_WAIT_L(0); PG8_BAR; PG8_MMA(1, 0, At, B0); PG8_MMA(1, 1, At, B1); PG8_BAR; PG8_SCHED;
	s_waitcnt lgkmcnt(0)
	v_mfma_f32_16x16x32_bf16 v[68:71], v[132:135], v[184:187], 0
	v_mfma_f32_16x16x32_bf16 v[60:63], v[160:163], v[184:187], 0
	v_mfma_f32_16x16x32_bf16 v[48:51], v[132:135], v[192:195], 0
	v_mfma_f32_16x16x32_bf16 v[44:47], v[160:163], v[192:195], 0
	v_mfma_f32_16x16x32_bf16 v[32:35], v[132:135], v[214:217], 0
	v_mfma_f32_16x16x32_bf16 v[28:31], v[160:163], v[214:217], 0
	v_mfma_f32_16x16x32_bf16 v[16:19], v[132:135], v[222:225], 0
	v_mfma_f32_16x16x32_bf16 v[12:15], v[160:163], v[222:225], 0
	v_mfma_f32_16x16x32_bf16 v[68:71], v[140:143], v[188:191], v[68:71]
	v_mfma_f32_16x16x32_bf16 v[60:63], v[164:167], v[188:191], v[60:63]
	v_mfma_f32_16x16x32_bf16 v[48:51], v[140:143], v[196:199], v[48:51]
	v_mfma_f32_16x16x32_bf16 v[44:47], v[164:167], v[196:199], v[44:47]
	v_mfma_f32_16x16x32_bf16 v[32:35], v[140:143], v[218:221], v[32:35]
	v_mfma_f32_16x16x32_bf16 v[28:31], v[164:167], v[218:221], v[28:31]
	v_mfma_f32_16x16x32_bf16 v[16:19], v[140:143], v[226:229], v[16:19]
	v_mfma_f32_16x16x32_bf16 v[12:15], v[164:167], v[226:229], v[12:15]
	v_mfma_f32_16x16x32_bf16 v[56:59], v[168:171], v[184:187], 0
	v_mfma_f32_16x16x32_bf16 v[52:55], v[176:179], v[184:187], 0
	v_mfma_f32_16x16x32_bf16 v[40:43], v[168:171], v[192:195], 0
	v_mfma_f32_16x16x32_bf16 v[36:39], v[176:179], v[192:195], 0
	v_mfma_f32_16x16x32_bf16 v[24:27], v[168:171], v[214:217], 0
	v_mfma_f32_16x16x32_bf16 v[20:23], v[176:179], v[214:217], 0
	v_mfma_f32_16x16x32_bf16 v[8:11], v[168:171], v[222:225], 0
	v_mfma_f32_16x16x32_bf16 v[4:7], v[176:179], v[222:225], 0
	v_mfma_f32_16x16x32_bf16 v[56:59], v[172:175], v[188:191], v[56:59]
	v_mfma_f32_16x16x32_bf16 v[52:55], v[180:183], v[188:191], v[52:55]
	v_mfma_f32_16x16x32_bf16 v[40:43], v[172:175], v[196:199], v[40:43]
	v_mfma_f32_16x16x32_bf16 v[36:39], v[180:183], v[196:199], v[36:39]
	v_mfma_f32_16x16x32_bf16 v[24:27], v[172:175], v[218:221], v[24:27]
	v_mfma_f32_16x16x32_bf16 v[20:23], v[180:183], v[218:221], v[20:23]
	v_mfma_f32_16x16x32_bf16 v[8:11], v[172:175], v[226:229], v[8:11]
	v_mfma_f32_16x16x32_bf16 v[4:7], v[180:183], v[226:229], v[4:7]
	s_barrier
	s_add_i32 s83, 0, 0x18000
	v_add_u32_e32 v3, s83, v158
	s_add_i32 s86, 0, 0x1c000
	ds_read_b128 v[132:135], v3
	ds_read_b128 v[140:143], v3 offset:1024
	ds_read_b128 v[160:163], v3 offset:2048
	ds_read_b128 v[164:167], v3 offset:3072
	v_add_u32_e32 v3, s86, v158
	ds_read_b128 v[168:171], v3
	ds_read_b128 v[172:175], v3 offset:1024
	ds_read_b128 v[176:179], v3 offset:2048
	ds_read_b128 v[180:183], v3 offset:3072
	s_add_u32 s74, s74, 0x40000
	s_addc_u32 s75, s75, 0
	s_mov_b32 m0, s84
	v_lshl_add_u64 v[236:237], s[74:75], 0, v[146:147]
	ds_read_b128 v[184:187], v159 offset:32768
	ds_read_b128 v[188:191], v159 offset:33792
	ds_read_b128 v[192:195], v159 offset:34816
	ds_read_b128 v[196:199], v159 offset:35840
	ds_read_b128 v[214:217], v159 offset:36864
	ds_read_b128 v[218:221], v159 offset:37888
	ds_read_b128 v[222:225], v159 offset:38912
	ds_read_b128 v[226:229], v159 offset:39936
	global_load_lds_dwordx4 v[236:237], off
	v_lshl_add_u64 v[236:237], s[74:75], 0, v[148:149]
	s_mov_b32 m0, s97
	s_nop 0
	global_load_lds_dwordx4 v[236:237], off
	s_waitcnt vmcnt(8)
	s_waitcnt lgkmcnt(0)
	s_barrier
	s_waitcnt lgkmcnt(0)
	v_mfma_f32_16x16x32_bf16 v[64:67], v[132:135], v[184:187], v[64:67]
	v_mfma_f32_16x16x32_bf16 v[72:75], v[160:163], v[184:187], v[72:75]
	v_mfma_f32_16x16x32_bf16 v[92:95], v[132:135], v[192:195], v[92:95]
	v_mfma_f32_16x16x32_bf16 v[96:99], v[160:163], v[192:195], v[96:99]
	v_mfma_f32_16x16x32_bf16 v[116:119], v[132:135], v[214:217], v[116:119]
	v_mfma_f32_16x16x32_bf16 v[124:127], v[160:163], v[214:217], v[124:127]
	v_mfma_f32_16x16x32_bf16 v[112:115], v[132:135], v[222:225], v[112:115]
	v_mfma_f32_16x16x32_bf16 v[100:103], v[160:163], v[222:225], v[100:103]
	v_mfma_f32_16x16x32_bf16 v[64:67], v[140:143], v[188:191], v[64:67]
	v_mfma_f32_16x16x32_bf16 v[72:75], v[164:167], v[188:191], v[72:75]
	v_mfma_f32_16x16x32_bf16 v[92:95], v[140:143], v[196:199], v[92:95]
	v_mfma_f32_16x16x32_bf16 v[96:99], v[164:167], v[196:199], v[96:99]
	v_mfma_f32_16x16x32_bf16 v[116:119], v[140:143], v[218:221], v[116:119]
	v_mfma_f32_16x16x32_bf16 v[124:127], v[164:167], v[218:221], v[124:127]
	v_mfma_f32_16x16x32_bf16 v[112:115], v[140:143], v[226:229], v[112:115]
	v_mfma_f32_16x16x32_bf16 v[100:103], v[164:167], v[226:229], v[100:103]
	v_mfma_f32_16x16x32_bf16 v[76:79], v[168:171], v[184:187], v[76:79]
	v_mfma_f32_16x16x32_bf16 v[84:87], v[176:179], v[184:187], v[84:87]
	v_mfma_f32_16x16x32_bf16 v[104:107], v[168:171], v[192:195], v[104:107]
	v_mfma_f32_16x16x32_bf16 v[108:111], v[176:179], v[192:195], v[108:111]
	v_mfma_f32_16x16x32_bf16 v[128:131], v[168:171], v[214:217], v[128:131]
	v_mfma_f32_16x16x32_bf16 v[120:123], v[176:179], v[214:217], v[120:123]
	v_mfma_f32_16x16x32_bf16 v[88:91], v[168:171], v[222:225], v[88:91]
	v_mfma_f32_16x16x32_bf16 v[80:83], v[176:179], v[222:225], v[80:83]
	v_mfma_f32_16x16x32_bf16 v[76:79], v[172:175], v[188:191], v[76:79]
	v_mfma_f32_16x16x32_bf16 v[84:87], v[180:183], v[188:191], v[84:87]
	v_mfma_f32_16x16x32_bf16 v[104:107], v[172:175], v[196:199], v[104:107]
	v_mfma_f32_16x16x32_bf16 v[108:111], v[180:183], v[196:199], v[108:111]
	v_mfma_f32_16x16x32_bf16 v[128:131], v[172:175], v[218:221], v[128:131]
	v_mfma_f32_16x16x32_bf16 v[120:123], v[180:183], v[218:221], v[120:123]
	v_mfma_f32_16x16x32_bf16 v[88:91], v[172:175], v[226:229], v[88:91]
	v_mfma_f32_16x16x32_bf16 v[80:83], v[180:183], v[226:229], v[80:83]
	s_barrier
; #define PG8_STAGE(bufoff, gbase, voff) do { _Pragma("unroll") for (int _i = 0; _i < 2; ++_i) \
;         __builtin_amdgcn_global_load_lds((const unsigned*)((const char*)(gbase) + (voff)[_i]), (LAS unsigned*)(lds + (bufoff) + ldsw + _i * 8192), 16, 0, 0); } while (0)
; #define PG8_LDA(dst, b, h) do { _Pragma("unroll") for (int m = 0; m < 4; ++m) _Pragma("unroll") for (int k = 0; k < 2; ++k) dst[m][k] = *(const LAS bf16x8*)(lds + PG8_SA(b, h) + aoff + m * 2048 + k * 1024); } while (0)
; #define PG8_LDB(dst, b, h) do { _Pragma("unroll") for (int n = 0; n < 2; ++n) _Pragma("unroll") for (int k = 0; k < 2; ++k) dst[n][k] = *(const LAS bf16x8*)(lds + PG8_SB(b, h) + boff + n * 2048 + k * 1024); } while (0)
; #define PG8_MMA(ai, bj, At, Bt) do { __builtin_amdgcn_s_setprio(1); _Pragma("unroll") for (int m = 0; m < 4; ++m) _Pragma("unroll") for (int n = 0; n < 2; ++n) _Pragma("unroll") for (int k = 0; k < 2; ++k) \
;         acc[ai][bj][m][n] = __builtin_amdgcn_mfma_f32_16x16x32_bf16(Bt[n][k], At[m][k], acc[ai][bj][m][n], 0, 0, 0); __builtin_amdgcn_s_setprio(0); } while (0)
; #define PG8_WAIT_V(n) asm volatile("s_waitcnt vmcnt(" #n ")" ::: "memory")
; #define PG8_WAIT_L(n) asm volatile("s_waitcnt lgkmcnt(" #n ")" ::: "memory")
; #define PG8_BAR __builtin_amdgcn_s_barrier()
; #define PG8_SCHED __builtin_amdgcn_sched_barrier(0)
; template <class Epi>
; __device__ __forceinline__ void gemm_phase(LAS unsigned char* lds, const Gemm g, const int G, const int cidx, const Epi& E) {
;     ...
;         for (int t = 0; t < nt; t += 2) {
;             const bool last = (t == nt - 2);
;             const char* a1 = cA + (size_t)(t + 1) * kstep;
;             const char* a2 = last ? nA : cA + (size_t)(t + 2) * kstep; const char* b2 = last ? nB : cB + (size_t)(t + 2) * kstep;
;             const char* a3 = a2 + kstep; const char* b3 = b2 + kstep;
;             PG8_LDB(B0, 0, 0); PG8_LDB(B1, 0, 1); PG8_SCHED; PG8_LDA(At, 0, 0); PG8_STAGE(PG8_SA(1, 1), a1 + hstep, voffA);
;     ...
;             PG8_LDA(At, 1, 1); PG8_STAGE(PG8_SB(1, 0), b3, voffB); PG8_STAGE(PG8_SB(1, 1), b3 + hstep, voffB); PG8_STAGE(PG8_SA(1, 0), a3, voffA);
;             PG8_WAIT_V(8); PG8_WAIT_L(0); PG8_BAR; PG8_MMA(1, 0, At, B0); PG8_MMA(1, 1, At, B1); PG8_BAR; PG8_SCHED;
	s_add_i32 s74, s83, s40
	v_lshl_add_u64 v[200:201], v[200:201], 0, s[46:47]
	s_mov_b32 m0, s74
	ds_read_b128 v[184:187], v159 offset:49152
	ds_read_b128 v[188:191], v159 offset:50176
	ds_read_b128 v[192:195], v159 offset:51200
	ds_read_b128 v[196:199], v159 offset:52224
	ds_read_b128 v[214:217], v159 offset:53248
	ds_read_b128 v[218:221], v159 offset:54272
	ds_read_b128 v[222:225], v159 offset:55296
	ds_read_b128 v[226:229], v159 offset:56320
	global_load_lds_dwordx4 v[200:201], off
	s_add_i32 m0, s74, 0x2000
	s_add_u32 s72, s72, 0x40080
	v_lshl_add_u64 v[200:201], v[230:231], 0, s[46:47]
	s_addc_u32 s73, s73, 0
	s_add_i32 s74, s86, s40
	global_load_lds_dwordx4 v[200:201], off
	v_lshl_add_u64 v[200:201], s[72:73], 0, v[146:147]
	s_mov_b32 m0, s74
	s_nop 0
	global_load_lds_dwordx4 v[200:201], off
	v_lshl_add_u64 v[200:201], s[72:73], 0, v[148:149]
	s_add_i32 m0, s74, 0x2000
	s_nop 0
	global_load_lds_dwordx4 v[200:201], off
	v_lshl_add_u64 v[200:201], v[232:233], 0, s[46:47]
	s_mov_b32 m0, s0
	s_nop 0
	global_load_lds_dwordx4 v[200:201], off
	v_lshl_add_u64 v[200:201], v[234:235], 0, s[46:47]
	s_mov_b32 m0, s2
	s_nop 0
	global_load_lds_dwordx4 v[200:201], off
	s_waitcnt vmcnt(8)
	s_waitcnt lgkmcnt(0)
	s_barrier
	s_waitcnt lgkmcnt(0)
	v_mfma_f32_16x16x32_bf16 v[68:71], v[132:135], v[184:187], v[68:71]
	v_mfma_f32_16x16x32_bf16 v[60:63], v[160:163], v[184:187], v[60:63]
	v_mfma_f32_16x16x32_bf16 v[48:51], v[132:135], v[192:195], v[48:51]
	v_mfma_f32_16x16x32_bf16 v[44:47], v[160:163], v[192:195], v[44:47]
	v_mfma_f32_16x16x32_bf16 v[32:35], v[132:135], v[214:217], v[32:35]
	v_mfma_f32_16x16x32_bf16 v[28:31], v[160:163], v[214:217], v[28:31]
	v_mfma_f32_16x16x32_bf16 v[16:19], v[132:135], v[222:225], v[16:19]
	v_mfma_f32_16x16x32_bf16 v[12:15], v[160:163], v[222:225], v[12:15]
	v_mfma_f32_16x16x32_bf16 v[68:71], v[140:143], v[188:191], v[68:71]
	v_mfma_f32_16x16x32_bf16 v[60:63], v[164:167], v[188:191], v[60:63]
	v_mfma_f32_16x16x32_bf16 v[48:51], v[140:143], v[196:199], v[48:51]
	v_mfma_f32_16x16x32_bf16 v[44:47], v[164:167], v[196:199], v[44:47]
	v_mfma_f32_16x16x32_bf16 v[32:35], v[140:143], v[218:221], v[32:35]
	v_mfma_f32_16x16x32_bf16 v[28:31], v[164:167], v[218:221], v[28:31]
	v_mfma_f32_16x16x32_bf16 v[16:19], v[140:143], v[226:229], v[16:19]
	v_mfma_f32_16x16x32_bf16 v[12:15], v[164:167], v[226:229], v[12:15]
	v_mfma_f32_16x16x32_bf16 v[56:59], v[168:171], v[184:187], v[56:59]
	v_mfma_f32_16x16x32_bf16 v[52:55], v[176:179], v[184:187], v[52:55]
	v_mfma_f32_16x16x32_bf16 v[40:43], v[168:171], v[192:195], v[40:43]
	v_mfma_f32_16x16x32_bf16 v[36:39], v[176:179], v[192:195], v[36:39]
	v_mfma_f32_16x16x32_bf16 v[24:27], v[168:171], v[214:217], v[24:27]
	v_mfma_f32_16x16x32_bf16 v[20:23], v[176:179], v[214:217], v[20:23]
	v_mfma_f32_16x16x32_bf16 v[8:11], v[168:171], v[222:225], v[8:11]
	v_mfma_f32_16x16x32_bf16 v[4:7], v[176:179], v[222:225], v[4:7]
	v_mfma_f32_16x16x32_bf16 v[56:59], v[172:175], v[188:191], v[56:59]
	v_mfma_f32_16x16x32_bf16 v[52:55], v[180:183], v[188:191], v[52:55]
	v_mfma_f32_16x16x32_bf16 v[40:43], v[172:175], v[196:199], v[40:43]
	v_mfma_f32_16x16x32_bf16 v[36:39], v[180:183], v[196:199], v[36:39]
	v_mfma_f32_16x16x32_bf16 v[24:27], v[172:175], v[218:221], v[24:27]
	v_mfma_f32_16x16x32_bf16 v[20:23], v[180:183], v[218:221], v[20:23]
	v_mfma_f32_16x16x32_bf16 v[8:11], v[172:175], v[226:229], v[8:11]
	v_mfma_f32_16x16x32_bf16 v[4:7], v[180:183], v[226:229], v[4:7]
	s_barrier
	s_add_i32 s77, s77, 2
	s_add_u32 s70, s70, 0x100
	s_addc_u32 s71, s71, 0
.LBB0_216:
	s_add_u32 s72, s8, s70
	s_addc_u32 s73, s9, s71
	s_add_u32 s72, s72, 0x100
	s_addc_u32 s73, s73, 0
	s_add_u32 s83, s43, s70
	s_addc_u32 s86, s44, s71
	s_add_i32 s87, 0, 0x10000
	s_cmpk_eq_i32 s70, 0x700
	s_cselect_b32 s75, s31, s73
	s_cselect_b32 s74, s45, s72
	v_add_u32_e32 v3, s87, v158
	s_cselect_b32 s73, s29, s86
	s_cselect_b32 s72, s68, s83
	s_add_i32 s83, 0, 0x14000
	ds_read_b128 v[132:135], v3
	ds_read_b128 v[140:143], v3 offset:1024
	ds_read_b128 v[160:163], v3 offset:2048
	ds_read_b128 v[164:167], v3 offset:3072
	v_add_u32_e32 v3, s83, v158
	ds_read_b128 v[168:171], v3
	ds_read_b128 v[172:175], v3 offset:1024
	ds_read_b128 v[176:179], v3 offset:2048
	ds_read_b128 v[180:183], v3 offset:3072
	v_lshl_add_u64 v[200:201], v[154:155], 0, s[70:71]
	s_add_i32 m0, s19, 0xc000
	ds_read_b128 v[184:187], v159
	ds_read_b128 v[188:191], v159 offset:1024
	ds_read_b128 v[192:195], v159 offset:2048
	ds_read_b128 v[196:199], v159 offset:3072
	ds_read_b128 v[214:217], v159 offset:4096
	ds_read_b128 v[218:221], v159 offset:5120
	ds_read_b128 v[222:225], v159 offset:6144
	ds_read_b128 v[226:229], v159 offset:7168
	global_load_lds_dwordx4 v[200:201], off
	v_lshl_add_u64 v[200:201], v[0:1], 0, s[70:71]
	s_add_i32 m0, s19, 0xe000
	s_nop 0
	global_load_lds_dwordx4 v[200:201], off
	s_waitcnt vmcnt(8)
	s_waitcnt lgkmcnt(0)
	s_barrier
; #define PG8_STAGE(bufoff, gbase, voff) do { _Pragma("unroll") for (int _i = 0; _i < 2; ++_i) \
;         __builtin_amdgcn_global_load_lds((const unsigned*)((const char*)(gbase) + (voff)[_i]), (LAS unsigned*)(lds + (bufoff) + ldsw + _i * 8192), 16, 0, 0); } while (0)
; #define PG8_LDA(dst, b, h) do { _Pragma("unroll") for (int m = 0; m < 4; ++m) _Pragma("unroll") for (int k = 0; k < 2; ++k) dst[m][k] = *(const LAS bf16x8*)(lds + PG8_SA(b, h) + aoff + m * 2048 + k * 1024); } while (0)
; #define PG8_LDB(dst, b, h) do { _Pragma("unroll") for (int n = 0; n < 2; ++n) _Pragma("unroll") for (int k = 0; k < 2; ++k) dst[n][k] = *(const LAS bf16x8*)(lds + PG8_SB(b, h) + boff + n * 2048 + k * 1024); } while (0)
; #define PG8_MMA(ai, bj, At, Bt) do { __builtin_amdgcn_s_setprio(1); _Pragma("unroll") for (int m = 0; m < 4; ++m) _Pragma("unroll") for (int n = 0; n < 2; ++n) _Pragma("unroll") for (int k = 0; k < 2; ++k) \
;         acc[ai][bj][m][n] = __builtin_amdgcn_mfma_f32_16x16x32_bf16(Bt[n][k], At[m][k], acc[ai][bj][m][n], 0, 0, 0); __builtin_amdgcn_s_setprio(0); } while (0)
; #define PG8_WAIT_V(n) asm volatile("s_waitcnt vmcnt(" #n ")" ::: "memory")
; #define PG8_WAIT_L(n) asm volatile("s_waitcnt lgkmcnt(" #n ")" ::: "memory")
; #define PG8_BAR __builtin_amdgcn_s_barrier()
; #define PG8_SCHED __builtin_amdgcn_sched_barrier(0)
; template <class Epi>
; __device__ __forceinline__ void gemm_phase(LAS unsigned char* lds, const Gemm g, const int G, const int cidx, const Epi& E) {
;     ...
;             PG8_WAIT_V(8); PG8_WAIT_L(0); PG8_BAR; PG8_MMA(0, 0, At, B0); PG8_MMA(0, 1, At, B1); PG8_BAR; PG8_SCHED;
;             PG8_LDA(At, 0, 1); PG8_STAGE(PG8_SB(0, 0), b2, voffB); PG8_STAGE(PG8_SB(0, 1), b2 + hstep, voffB); PG8_STAGE(PG8_SA(0, 0), a2, voffA);
;             PG8_WAIT_V(8); PG8_WAIT_L(0); PG8_BAR; PG8_MMA(1, 0, At, B0); PG8_MMA(1, 1, At, B1); PG8_BAR; PG8_SCHED;
;             PG8_LDB(B0, 1, 0); PG8_LDB(B1, 1, 1); PG8_SCHED; PG8_LDA(At, 1, 0); PG8_STAGE(PG8_SA(0, 1), a2 + hstep, voffA);
;             PG8_WAIT_V(8); PG8_WAIT_L(0); PG8_BAR; PG8_MMA(0, 0, At, B0); PG8_MMA(0, 1, At, B1); PG8_BAR; PG8_SCHED;
	s_waitcnt lgkmcnt(0)
	v_mfma_f32_16x16x32_bf16 v[64:67], v[132:135], v[184:187], v[64:67]
	v_mfma_f32_16x16x32_bf16 v[72:75], v[160:163], v[184:187], v[72:75]
	v_mfma_f32_16x16x32_bf16 v[92:95], v[132:135], v[192:195], v[92:95]
	v_mfma_f32_16x16x32_bf16 v[96:99], v[160:163], v[192:195], v[96:99]
	v_mfma_f32_16x16x32_bf16 v[116:119], v[132:135], v[214:217], v[116:119]
	v_mfma_f32_16x16x32_bf16 v[124:127], v[160:163], v[214:217], v[124:127]
	v_mfma_f32_16x16x32_bf16 v[112:115], v[132:135], v[222:225], v[112:115]
	v_mfma_f32_16x16x32_bf16 v[100:103], v[160:163], v[222:225], v[100:103]
	v_mfma_f32_16x16x32_bf16 v[64:67], v[140:143], v[188:191], v[64:67]
	v_mfma_f32_16x16x32_bf16 v[72:75], v[164:167], v[188:191], v[72:75]
	v_mfma_f32_16x16x32_bf16 v[92:95], v[140:143], v[196:199], v[92:95]
	v_mfma_f32_16x16x32_bf16 v[96:99], v[164:167], v[196:199], v[96:99]
	v_mfma_f32_16x16x32_bf16 v[116:119], v[140:143], v[218:221], v[116:119]
	v_mfma_f32_16x16x32_bf16 v[124:127], v[164:167], v[218:221], v[124:127]
	v_mfma_f32_16x16x32_bf16 v[112:115], v[140:143], v[226:229], v[112:115]
	v_mfma_f32_16x16x32_bf16 v[100:103], v[164:167], v[226:229], v[100:103]
	v_mfma_f32_16x16x32_bf16 v[76:79], v[168:171], v[184:187], v[76:79]
	v_mfma_f32_16x16x32_bf16 v[84:87], v[176:179], v[184:187], v[84:87]
	v_mfma_f32_16x16x32_bf16 v[104:107], v[168:171], v[192:195], v[104:107]
	v_mfma_f32_16x16x32_bf16 v[108:111], v[176:179], v[192:195], v[108:111]
	v_mfma_f32_16x16x32_bf16 v[128:131], v[168:171], v[214:217], v[128:131]
	v_mfma_f32_16x16x32_bf16 v[120:123], v[176:179], v[214:217], v[120:123]
	v_mfma_f32_16x16x32_bf16 v[88:91], v[168:171], v[222:225], v[88:91]
	v_mfma_f32_16x16x32_bf16 v[80:83], v[176:179], v[222:225], v[80:83]
	v_mfma_f32_16x16x32_bf16 v[76:79], v[172:175], v[188:191], v[76:79]
	v_mfma_f32_16x16x32_bf16 v[84:87], v[180:183], v[188:191], v[84:87]
	v_mfma_f32_16x16x32_bf16 v[104:107], v[172:175], v[196:199], v[104:107]
	v_mfma_f32_16x16x32_bf16 v[108:111], v[180:183], v[196:199], v[108:111]
	v_mfma_f32_16x16x32_bf16 v[128:131], v[172:175], v[218:221], v[128:131]
	v_mfma_f32_16x16x32_bf16 v[120:123], v[180:183], v[218:221], v[120:123]
	v_mfma_f32_16x16x32_bf16 v[88:91], v[172:175], v[226:229], v[88:91]
	v_mfma_f32_16x16x32_bf16 v[80:83], v[180:183], v[226:229], v[80:83]
	s_barrier
	s_add_i32 s86, s87, s40
	v_lshl_add_u64 v[200:201], s[72:73], 0, v[146:147]
	s_mov_b32 m0, s86
	ds_read_b128 v[184:187], v159 offset:16384
	ds_read_b128 v[188:191], v159 offset:17408
	ds_read_b128 v[192:195], v159 offset:18432
	ds_read_b128 v[196:199], v159 offset:19456
	ds_read_b128 v[214:217], v159 offset:20480
	ds_read_b128 v[218:221], v159 offset:21504
	ds_read_b128 v[222:225], v159 offset:22528
	ds_read_b128 v[226:229], v159 offset:23552
	global_load_lds_dwordx4 v[200:201], off
	s_add_i32 m0, s86, 0x2000
	s_add_u32 s86, s72, 0x40000
	v_lshl_add_u64 v[230:231], s[72:73], 0, v[148:149]
	s_addc_u32 s87, s73, 0
	s_add_i32 s83, s83, s40
	global_load_lds_dwordx4 v[230:231], off
	v_lshl_add_u64 v[232:233], s[86:87], 0, v[146:147]
	s_mov_b32 m0, s83
	v_lshl_add_u64 v[234:235], s[74:75], 0, v[148:149]
	global_load_lds_dwordx4 v[232:233], off
	v_lshl_add_u64 v[232:233], s[86:87], 0, v[148:149]
	s_add_i32 m0, s83, 0x2000
	s_nop 0
	global_load_lds_dwordx4 v[232:233], off
	v_lshl_add_u64 v[232:233], s[74:75], 0, v[146:147]
	s_mov_b32 m0, s19
	s_nop 0
	global_load_lds_dwordx4 v[232:233], off
	s_mov_b32 m0, s76
	s_nop 0
	global_load_lds_dwordx4 v[234:235], off
	s_waitcnt vmcnt(8)
	s_waitcnt lgkmcnt(0)
	s_barrier
	s_waitcnt lgkmcnt(0)
	v_mfma_f32_16x16x32_bf16 v[68:71], v[132:135], v[184:187], v[68:71]
	v_mfma_f32_16x16x32_bf16 v[60:63], v[160:163], v[184:187], v[60:63]
	v_mfma_f32_16x16x32_bf16 v[48:51], v[132:135], v[192:195], v[48:51]
	v_mfma_f32_16x16x32_bf16 v[44:47], v[160:163], v[192:195], v[44:47]
	v_mfma_f32_16x16x32_bf16 v[32:35], v[132:135], v[214:217], v[32:35]
	v_mfma_f32_16x16x32_bf16 v[28:31], v[160:163], v[214:217], v[28:31]
	v_mfma_f32_16x16x32_bf16 v[16:19], v[132:135], v[222:225], v[16:19]
	v_mfma_f32_16x16x32_bf16 v[12:15], v[160:163], v[222:225], v[12:15]
	v_mfma_f32_16x16x32_bf16 v[68:71], v[140:143], v[188:191], v[68:71]
	v_mfma_f32_16x16x32_bf16 v[60:63], v[164:167], v[188:191], v[60:63]
	v_mfma_f32_16x16x32_bf16 v[48:51], v[140:143], v[196:199], v[48:51]
	v_mfma_f32_16x16x32_bf16 v[44:47], v[164:167], v[196:199], v[44:47]
	v_mfma_f32_16x16x32_bf16 v[32:35], v[140:143], v[218:221], v[32:35]
	v_mfma_f32_16x16x32_bf16 v[28:31], v[164:167], v[218:221], v[28:31]
	v_mfma_f32_16x16x32_bf16 v[16:19], v[140:143], v[226:229], v[16:19]
	v_mfma_f32_16x16x32_bf16 v[12:15], v[164:167], v[226:229], v[12:15]
	v_mfma_f32_16x16x32_bf16 v[56:59], v[168:171], v[184:187], v[56:59]
	v_mfma_f32_16x16x32_bf16 v[52:55], v[176:179], v[184:187], v[52:55]
	v_mfma_f32_16x16x32_bf16 v[40:43], v[168:171], v[192:195], v[40:43]
	v_mfma_f32_16x16x32_bf16 v[36:39], v[176:179], v[192:195], v[36:39]
	v_mfma_f32_16x16x32_bf16 v[24:27], v[168:171], v[214:217], v[24:27]
	v_mfma_f32_16x16x32_bf16 v[20:23], v[176:179], v[214:217], v[20:23]
	v_mfma_f32_16x16x32_bf16 v[8:11], v[168:171], v[222:225], v[8:11]
	v_mfma_f32_16x16x32_bf16 v[4:7], v[176:179], v[222:225], v[4:7]
	v_mfma_f32_16x16x32_bf16 v[56:59], v[172:175], v[188:191], v[56:59]
	v_mfma_f32_16x16x32_bf16 v[52:55], v[180:183], v[188:191], v[52:55]
	v_mfma_f32_16x16x32_bf16 v[40:43], v[172:175], v[196:199], v[40:43]
	v_mfma_f32_16x16x32_bf16 v[36:39], v[180:183], v[196:199], v[36:39]
	v_mfma_f32_16x16x32_bf16 v[24:27], v[172:175], v[218:221], v[24:27]
	v_mfma_f32_16x16x32_bf16 v[20:23], v[180:183], v[218:221], v[20:23]
	v_mfma_f32_16x16x32_bf16 v[8:11], v[172:175], v[226:229], v[8:11]
	v_mfma_f32_16x16x32_bf16 v[4:7], v[180:183], v[226:229], v[4:7]
	s_barrier
; #define PG8_STAGE(bufoff, gbase, voff) do { _Pragma("unroll") for (int _i = 0; _i < 2; ++_i) \
;         __builtin_amdgcn_global_load_lds((const unsigned*)((const char*)(gbase) + (voff)[_i]), (LAS unsigned*)(lds + (bufoff) + ldsw + _i * 8192), 16, 0, 0); } while (0)
; #define PG8_LDA(dst, b, h) do { _Pragma("unroll") for (int m = 0; m < 4; ++m) _Pragma("unroll") for (int k = 0; k < 2; ++k) dst[m][k] = *(const LAS bf16x8*)(lds + PG8_SA(b, h) + aoff + m * 2048 + k * 1024); } while (0)
; #define PG8_LDB(dst, b, h) do { _Pragma("unroll") for (int n = 0; n < 2; ++n) _Pragma("unroll") for (int k = 0; k < 2; ++k) dst[n][k] = *(const LAS bf16x8*)(lds + PG8_SB(b, h) + boff + n * 2048 + k * 1024); } while (0)
; #define PG8_MMA(ai, bj, At, Bt) do { __builtin_amdgcn_s_setprio(1); _Pragma("unroll") for (int m = 0; m < 4; ++m) _Pragma("unroll") for (int n = 0; n < 2; ++n) _Pragma("unroll") for (int k = 0; k < 2; ++k) \
;         acc[ai][bj][m][n] = __builtin_amdgcn_mfma_f32_16x16x32_bf16(Bt[n][k], At[m][k], acc[ai][bj][m][n], 0, 0, 0); __builtin_amdgcn_s_setprio(0); } while (0)
; #define PG8_WAIT_V(n) asm volatile("s_waitcnt vmcnt(" #n ")" ::: "memory")
; #define PG8_WAIT_L(n) asm volatile("s_waitcnt lgkmcnt(" #n ")" ::: "memory")
; #define PG8_BAR __builtin_amdgcn_s_barrier()
; #define PG8_SCHED __builtin_amdgcn_sched_barrier(0)
; template <class Epi>
; __device__ __forceinline__ void gemm_phase(LAS unsigned char* lds, const Gemm g, const int G, const int cidx, const Epi& E) {
;     ...
;             PG8_LDB(B0, 1, 0); PG8_LDB(B1, 1, 1); PG8_SCHED; PG8_LDA(At, 1, 0); PG8_STAGE(PG8_SA(0, 1), a2 + hstep, voffA);
;             PG8_WAIT_V(8); PG8_WAIT_L(0); PG8_BAR; PG8_MMA(0, 0, At, B0); PG8_MMA(0, 1, At, B1); PG8_BAR; PG8_SCHED;
;             PG8_LDA(At, 1, 1); PG8_STAGE(PG8_SB(1, 0), b3, voffB); PG8_STAGE(PG8_SB(1, 1), b3 + hstep, voffB); PG8_STAGE(PG8_SA(1, 0), a3, voffA);
;             PG8_WAIT_V(8); PG8_WAIT_L(0); PG8_BAR; PG8_MMA(1, 0, At, B0); PG8_MMA(1, 1, At, B1); PG8_BAR; PG8_SCHED;
	s_add_i32 s83, 0, 0x18000
	v_add_u32_e32 v3, s83, v158
	s_add_i32 s86, 0, 0x1c000
	ds_read_b128 v[132:135], v3
	ds_read_b128 v[140:143], v3 offset:1024
	ds_read_b128 v[160:163], v3 offset:2048
	ds_read_b128 v[164:167], v3 offset:3072
	v_add_u32_e32 v3, s86, v158
	ds_read_b128 v[168:171], v3
	ds_read_b128 v[172:175], v3 offset:1024
	ds_read_b128 v[176:179], v3 offset:2048
	ds_read_b128 v[180:183], v3 offset:3072
	s_add_u32 s74, s74, 0x40000
	s_addc_u32 s75, s75, 0
	s_mov_b32 m0, s84
	v_lshl_add_u64 v[236:237], s[74:75], 0, v[146:147]
	ds_read_b128 v[184:187], v159 offset:32768
	ds_read_b128 v[188:191], v159 offset:33792
	ds_read_b128 v[192:195], v159 offset:34816
	ds_read_b128 v[196:199], v159 offset:35840
	ds_read_b128 v[214:217], v159 offset:36864
	ds_read_b128 v[218:221], v159 offset:37888
	ds_read_b128 v[222:225], v159 offset:38912
	ds_read_b128 v[226:229], v159 offset:39936
	global_load_lds_dwordx4 v[236:237], off
	v_lshl_add_u64 v[236:237], s[74:75], 0, v[148:149]
	s_mov_b32 m0, s97
	s_nop 0
	global_load_lds_dwordx4 v[236:237], off
	s_waitcnt vmcnt(8)
	s_waitcnt lgkmcnt(0)
	s_barrier
	s_waitcnt lgkmcnt(0)
	v_mfma_f32_16x16x32_bf16 v[64:67], v[132:135], v[184:187], v[64:67]
	v_mfma_f32_16x16x32_bf16 v[72:75], v[160:163], v[184:187], v[72:75]
	v_mfma_f32_16x16x32_bf16 v[92:95], v[132:135], v[192:195], v[92:95]
	v_mfma_f32_16x16x32_bf16 v[96:99], v[160:163], v[192:195], v[96:99]
	v_mfma_f32_16x16x32_bf16 v[116:119], v[132:135], v[214:217], v[116:119]
	v_mfma_f32_16x16x32_bf16 v[124:127], v[160:163], v[214:217], v[124:127]
	v_mfma_f32_16x16x32_bf16 v[112:115], v[132:135], v[222:225], v[112:115]
	v_mfma_f32_16x16x32_bf16 v[100:103], v[160:163], v[222:225], v[100:103]
	v_mfma_f32_16x16x32_bf16 v[64:67], v[140:143], v[188:191], v[64:67]
	v_mfma_f32_16x16x32_bf16 v[72:75], v[164:167], v[188:191], v[72:75]
	v_mfma_f32_16x16x32_bf16 v[92:95], v[140:143], v[196:199], v[92:95]
	v_mfma_f32_16x16x32_bf16 v[96:99], v[164:167], v[196:199], v[96:99]
	v_mfma_f32_16x16x32_bf16 v[116:119], v[140:143], v[218:221], v[116:119]
	v_mfma_f32_16x16x32_bf16 v[124:127], v[164:167], v[218:221], v[124:127]
	v_mfma_f32_16x16x32_bf16 v[112:115], v[140:143], v[226:229], v[112:115]
	v_mfma_f32_16x16x32_bf16 v[100:103], v[164:167], v[226:229], v[100:103]
	v_mfma_f32_16x16x32_bf16 v[76:79], v[168:171], v[184:187], v[76:79]
	v_mfma_f32_16x16x32_bf16 v[84:87], v[176:179], v[184:187], v[84:87]
	v_mfma_f32_16x16x32_bf16 v[104:107], v[168:171], v[192:195], v[104:107]
	v_mfma_f32_16x16x32_bf16 v[108:111], v[176:179], v[192:195], v[108:111]
	v_mfma_f32_16x16x32_bf16 v[128:131], v[168:171], v[214:217], v[128:131]
	v_mfma_f32_16x16x32_bf16 v[120:123], v[176:179], v[214:217], v[120:123]
	v_mfma_f32_16x16x32_bf16 v[88:91], v[168:171], v[222:225], v[88:91]
	v_mfma_f32_16x16x32_bf16 v[80:83], v[176:179], v[222:225], v[80:83]
	v_mfma_f32_16x16x32_bf16 v[76:79], v[172:175], v[188:191], v[76:79]
	v_mfma_f32_16x16x32_bf16 v[84:87], v[180:183], v[188:191], v[84:87]
	v_mfma_f32_16x16x32_bf16 v[104:107], v[172:175], v[196:199], v[104:107]
	v_mfma_f32_16x16x32_bf16 v[108:111], v[180:183], v[196:199], v[108:111]
	v_mfma_f32_16x16x32_bf16 v[128:131], v[172:175], v[218:221], v[128:131]
	v_mfma_f32_16x16x32_bf16 v[120:123], v[180:183], v[218:221], v[120:123]
	v_mfma_f32_16x16x32_bf16 v[88:91], v[172:175], v[226:229], v[88:91]
	v_mfma_f32_16x16x32_bf16 v[80:83], v[180:183], v[226:229], v[80:83]
	s_barrier
	s_add_i32 s74, s83, s40
	v_lshl_add_u64 v[200:201], v[200:201], 0, s[46:47]
	s_mov_b32 m0, s74
	ds_read_b128 v[184:187], v159 offset:49152
	ds_read_b128 v[188:191], v159 offset:50176
	ds_read_b128 v[192:195], v159 offset:51200
	ds_read_b128 v[196:199], v159 offset:52224
	ds_read_b128 v[214:217], v159 offset:53248
	ds_read_b128 v[218:221], v159 offset:54272
	ds_read_b128 v[222:225], v159 offset:55296
	ds_read_b128 v[226:229], v159 offset:56320
	global_load_lds_dwordx4 v[200:201], off
	s_add_i32 m0, s74, 0x2000
	s_add_u32 s72, s72, 0x40080
	v_lshl_add_u64 v[200:201], v[230:231], 0, s[46:47]
	s_addc_u32 s73, s73, 0
	s_add_i32 s74, s86, s40
	global_load_lds_dwordx4 v[200:201], off
	v_lshl_add_u64 v[200:201], s[72:73], 0, v[146:147]
	s_mov_b32 m0, s74
	s_nop 0
	global_load_lds_dwordx4 v[200:201], off
	v_lshl_add_u64 v[200:201], s[72:73], 0, v[148:149]
	s_add_i32 m0, s74, 0x2000
	s_nop 0
	global_load_lds_dwordx4 v[200:201], off
	v_lshl_add_u64 v[200:201], v[232:233], 0, s[46:47]
	s_mov_b32 m0, s0
	s_nop 0
	global_load_lds_dwordx4 v[200:201], off
	v_lshl_add_u64 v[200:201], v[234:235], 0, s[46:47]
	s_mov_b32 m0, s2
	s_nop 0
	global_load_lds_dwordx4 v[200:201], off
	s_waitcnt vmcnt(8)
	s_waitcnt lgkmcnt(0)
	s_barrier
; #define PG8_MMA(ai, bj, At, Bt) do { __builtin_amdgcn_s_setprio(1); _Pragma("unroll") for (int m = 0; m < 4; ++m) _Pragma("unroll") for (int n = 0; n < 2; ++n) _Pragma("unroll") for (int k = 0; k < 2; ++k) \
;         acc[ai][bj][m][n] = __builtin_amdgcn_mfma_f32_16x16x32_bf16(Bt[n][k], At[m][k], acc[ai][bj][m][n], 0, 0, 0); __builtin_amdgcn_s_setprio(0); } while (0)
; #define PG8_WAIT_V(n) asm volatile("s_waitcnt vmcnt(" #n ")" ::: "memory")
; #define PG8_WAIT_L(n) asm volatile("s_waitcnt lgkmcnt(" #n ")" ::: "memory")
; #define PG8_BAR __builtin_amdgcn_s_barrier()
; #define PG8_SCHED __builtin_amdgcn_sched_barrier(0)
; template <class Epi>
; __device__ __forceinline__ void gemm_phase(LAS unsigned char* lds, const Gemm g, const int G, const int cidx, const Epi& E) {
;     ...
;             PG8_WAIT_V(8); PG8_WAIT_L(0); PG8_BAR; PG8_MMA(1, 0, At, B0); PG8_MMA(1, 1, At, B1); PG8_BAR; PG8_SCHED;
;         }
;         if constexpr (!Epi::AFTER_DRAIN) E(acc, cur, wr, wc, fr, fq);
;         if (!has_next) break;
; #pragma unroll
;         for (int a = 0; a < 2; ++a)
; #pragma unroll
;             for (int b = 0; b < 2; ++b)
; #pragma unroll
;                 for (int m = 0; m < 4; ++m)
; #pragma unroll
;                     for (int n = 0; n < 2; ++n) acc[a][b][m][n] = ZERO4;
;         cur = nxt; cA = nA; cB = nB; ++ui;
	s_waitcnt lgkmcnt(0)
	v_mfma_f32_16x16x32_bf16 v[68:71], v[132:135], v[184:187], v[68:71]
	v_mfma_f32_16x16x32_bf16 v[60:63], v[160:163], v[184:187], v[60:63]
	v_mfma_f32_16x16x32_bf16 v[48:51], v[132:135], v[192:195], v[48:51]
	v_mfma_f32_16x16x32_bf16 v[44:47], v[160:163], v[192:195], v[44:47]
	v_mfma_f32_16x16x32_bf16 v[32:35], v[132:135], v[214:217], v[32:35]
	v_mfma_f32_16x16x32_bf16 v[28:31], v[160:163], v[214:217], v[28:31]
	v_mfma_f32_16x16x32_bf16 v[16:19], v[132:135], v[222:225], v[16:19]
	v_mfma_f32_16x16x32_bf16 v[12:15], v[160:163], v[222:225], v[12:15]
	v_mfma_f32_16x16x32_bf16 v[68:71], v[140:143], v[188:191], v[68:71]
	v_mfma_f32_16x16x32_bf16 v[60:63], v[164:167], v[188:191], v[60:63]
	v_mfma_f32_16x16x32_bf16 v[48:51], v[140:143], v[196:199], v[48:51]
	v_mfma_f32_16x16x32_bf16 v[44:47], v[164:167], v[196:199], v[44:47]
	v_mfma_f32_16x16x32_bf16 v[32:35], v[140:143], v[218:221], v[32:35]
	v_mfma_f32_16x16x32_bf16 v[28:31], v[164:167], v[218:221], v[28:31]
	v_mfma_f32_16x16x32_bf16 v[16:19], v[140:143], v[226:229], v[16:19]
	v_mfma_f32_16x16x32_bf16 v[12:15], v[164:167], v[226:229], v[12:15]
	v_mfma_f32_16x16x32_bf16 v[56:59], v[168:171], v[184:187], v[56:59]
	v_mfma_f32_16x16x32_bf16 v[52:55], v[176:179], v[184:187], v[52:55]
	v_mfma_f32_16x16x32_bf16 v[40:43], v[168:171], v[192:195], v[40:43]
	v_mfma_f32_16x16x32_bf16 v[36:39], v[176:179], v[192:195], v[36:39]
	v_mfma_f32_16x16x32_bf16 v[24:27], v[168:171], v[214:217], v[24:27]
	v_mfma_f32_16x16x32_bf16 v[20:23], v[176:179], v[214:217], v[20:23]
	v_mfma_f32_16x16x32_bf16 v[8:11], v[168:171], v[222:225], v[8:11]
	v_mfma_f32_16x16x32_bf16 v[4:7], v[176:179], v[222:225], v[4:7]
	v_mfma_f32_16x16x32_bf16 v[56:59], v[172:175], v[188:191], v[56:59]
	v_mfma_f32_16x16x32_bf16 v[52:55], v[180:183], v[188:191], v[52:55]
	v_mfma_f32_16x16x32_bf16 v[40:43], v[172:175], v[196:199], v[40:43]
	v_mfma_f32_16x16x32_bf16 v[36:39], v[180:183], v[196:199], v[36:39]
	v_mfma_f32_16x16x32_bf16 v[24:27], v[172:175], v[218:221], v[24:27]
	v_mfma_f32_16x16x32_bf16 v[20:23], v[180:183], v[218:221], v[20:23]
	v_mfma_f32_16x16x32_bf16 v[8:11], v[172:175], v[226:229], v[8:11]
	v_mfma_f32_16x16x32_bf16 v[4:7], v[180:183], v[226:229], v[4:7]
	s_barrier
	s_add_i32 s77, s77, 2
	s_add_u32 s70, s70, 0x100
	s_addc_u32 s71, s71, 0
	s_cmp_gt_u32 s77, 13
	s_cbranch_scc0 .LBB0_216
	s_add_u32 s70, s43, 0xffffff00
	s_addc_u32 s71, s44, -1
	s_andn2_b64 vcc, exec, s[6:7]
	s_cbranch_vccnz .LBB0_219
	v_mov_b32_e32 v4, 0
	s_mov_b32 s20, s28
	s_mov_b32 s18, s30
	s_mov_b64 s[8:9], s[36:37]
	s_mov_b32 s38, s33
	v_mov_b32_e32 v5, v4
	v_mov_b32_e32 v6, v4
	v_mov_b32_e32 v7, v4
	v_mov_b32_e32 v8, v4
	v_mov_b32_e32 v9, v4
	v_mov_b32_e32 v10, v4
	v_mov_b32_e32 v11, v4
	v_mov_b32_e32 v20, v4
	v_mov_b32_e32 v21, v4
	v_mov_b32_e32 v22, v4
	v_mov_b32_e32 v23, v4
	v_mov_b32_e32 v24, v4
	v_mov_b32_e32 v25, v4
	v_mov_b32_e32 v26, v4
	v_mov_b32_e32 v27, v4
	v_mov_b32_e32 v36, v4
	v_mov_b32_e32 v37, v4
	v_mov_b32_e32 v38, v4
	v_mov_b32_e32 v39, v4
	v_mov_b32_e32 v40, v4
	v_mov_b32_e32 v41, v4
	v_mov_b32_e32 v42, v4
	v_mov_b32_e32 v43, v4
	v_mov_b32_e32 v52, v4
	v_mov_b32_e32 v53, v4
	v_mov_b32_e32 v54, v4
	v_mov_b32_e32 v55, v4
	v_mov_b32_e32 v56, v4
	v_mov_b32_e32 v57, v4
	v_mov_b32_e32 v58, v4
	v_mov_b32_e32 v59, v4
	v_mov_b32_e32 v12, v4
	v_mov_b32_e32 v13, v4
	v_mov_b32_e32 v14, v4
	v_mov_b32_e32 v15, v4
	v_mov_b32_e32 v16, v4
	v_mov_b32_e32 v17, v4
	v_mov_b32_e32 v18, v4
	v_mov_b32_e32 v19, v4
	v_mov_b32_e32 v28, v4
	v_mov_b32_e32 v29, v4
	v_mov_b32_e32 v30, v4
	v_mov_b32_e32 v31, v4
	v_mov_b32_e32 v32, v4
	v_mov_b32_e32 v33, v4
	v_mov_b32_e32 v34, v4
	v_mov_b32_e32 v35, v4
	v_mov_b32_e32 v44, v4
	v_mov_b32_e32 v45, v4
	v_mov_b32_e32 v46, v4
	v_mov_b32_e32 v47, v4
	v_mov_b32_e32 v48, v4
	v_mov_b32_e32 v49, v4
	v_mov_b32_e32 v50, v4
	v_mov_b32_e32 v51, v4
	v_mov_b32_e32 v60, v4
	v_mov_b32_e32 v61, v4
	v_mov_b32_e32 v62, v4
	v_mov_b32_e32 v63, v4
	v_mov_b32_e32 v68, v4
	v_mov_b32_e32 v69, v4
	v_mov_b32_e32 v70, v4
	v_mov_b32_e32 v71, v4
	v_mov_b32_e32 v80, v4
	v_mov_b32_e32 v81, v4
	v_mov_b32_e32 v82, v4
	v_mov_b32_e32 v83, v4
	v_mov_b32_e32 v88, v4
	v_mov_b32_e32 v89, v4
	v_mov_b32_e32 v90, v4
	v_mov_b32_e32 v91, v4
	v_mov_b32_e32 v120, v4
	v_mov_b32_e32 v121, v4
	v_mov_b32_e32 v122, v4
	v_mov_b32_e32 v123, v4
	v_mov_b32_e32 v128, v4
	v_mov_b32_e32 v129, v4
	v_mov_b32_e32 v130, v4
	v_mov_b32_e32 v131, v4
	v_mov_b32_e32 v108, v4
	v_mov_b32_e32 v109, v4
	v_mov_b32_e32 v110, v4
	v_mov_b32_e32 v111, v4
	v_mov_b32_e32 v104, v4
	v_mov_b32_e32 v105, v4
	v_mov_b32_e32 v106, v4
	v_mov_b32_e32 v107, v4
	v_mov_b32_e32 v84, v4
	v_mov_b32_e32 v85, v4
	v_mov_b32_e32 v86, v4
	v_mov_b32_e32 v87, v4
	v_mov_b32_e32 v76, v4
	v_mov_b32_e32 v77, v4
	v_mov_b32_e32 v78, v4
	v_mov_b32_e32 v79, v4
	v_mov_b32_e32 v100, v4
	v_mov_b32_e32 v101, v4
	v_mov_b32_e32 v102, v4
	v_mov_b32_e32 v103, v4
	v_mov_b32_e32 v112, v4
	v_mov_b32_e32 v113, v4
	v_mov_b32_e32 v114, v4
	v_mov_b32_e32 v115, v4
	v_mov_b32_e32 v124, v4
	v_mov_b32_e32 v125, v4
	v_mov_b32_e32 v126, v4
	v_mov_b32_e32 v127, v4
	v_mov_b32_e32 v116, v4
	v_mov_b32_e32 v117, v4
	v_mov_b32_e32 v118, v4
	v_mov_b32_e32 v119, v4
	v_mov_b32_e32 v96, v4
	v_mov_b32_e32 v97, v4
	v_mov_b32_e32 v98, v4
	v_mov_b32_e32 v99, v4
	v_mov_b32_e32 v92, v4
	v_mov_b32_e32 v93, v4
	v_mov_b32_e32 v94, v4
	v_mov_b32_e32 v95, v4
	v_mov_b32_e32 v72, v4
	v_mov_b32_e32 v73, v4
	v_mov_b32_e32 v74, v4
	v_mov_b32_e32 v75, v4
	v_mov_b32_e32 v64, v4
	v_mov_b32_e32 v65, v4
	v_mov_b32_e32 v66, v4
	v_mov_b32_e32 v67, v4
	s_mov_b32 s83, 0x18000
	s_mov_b32 s86, 0x3fb8aa3b
	s_andn2_b64 vcc, exec, s[4:5]
	s_cbranch_vccnz .LBB0_220
	s_branch .LBB0_221

; #define PG8_STAGE(bufoff, gbase, voff) do { _Pragma("unroll") for (int _i = 0; _i < 2; ++_i) \
;         __builtin_amdgcn_global_load_lds((const unsigned*)((const char*)(gbase) + (voff)[_i]), (LAS unsigned*)(lds + (bufoff) + ldsw + _i * 8192), 16, 0, 0); } while (0)
; #define PG8_LDA(dst, b, h) do { _Pragma("unroll") for (int m = 0; m < 4; ++m) _Pragma("unroll") for (int k = 0; k < 2; ++k) dst[m][k] = *(const LAS bf16x8*)(lds + PG8_SA(b, h) + aoff + m * 2048 + k * 1024); } while (0)
; #define PG8_LDB(dst, b, h) do { _Pragma("unroll") for (int n = 0; n < 2; ++n) _Pragma("unroll") for (int k = 0; k < 2; ++k) dst[n][k] = *(const LAS bf16x8*)(lds + PG8_SB(b, h) + boff + n * 2048 + k * 1024); } while (0)
; #define PG8_MMA(ai, bj, At, Bt) do { __builtin_amdgcn_s_setprio(1); _Pragma("unroll") for (int m = 0; m < 4; ++m) _Pragma("unroll") for (int n = 0; n < 2; ++n) _Pragma("unroll") for (int k = 0; k < 2; ++k) \
;         acc[ai][bj][m][n] = __builtin_amdgcn_mfma_f32_16x16x32_bf16(Bt[n][k], At[m][k], acc[ai][bj][m][n], 0, 0, 0); __builtin_amdgcn_s_setprio(0); } while (0)
; #define PG8_WAIT_V(n) asm volatile("s_waitcnt vmcnt(" #n ")" ::: "memory")
; template <class Epi>
; __device__ __forceinline__ void gemm_phase(LAS unsigned char* lds, const Gemm g, const int G, const int cidx, const Epi& E) {
;     ...
;         const bool has_next = S.next(ui + 1, nxt);
;         const char* nA = has_next ? PG8_ABASE(nxt) : cA; const char* nB = has_next ? (const char*)g.Bt + (size_t)nxt.pn * tstep : cB;
;         for (int t = 0; t < nt; t += 2) {
;             const bool last = (t == nt - 2);
;             const char* a1 = cA + (size_t)(t + 1) * kstep;
;             const char* a2 = last ? nA : cA + (size_t)(t + 2) * kstep; const char* b2 = last ? nB : cB + (size_t)(t + 2) * kstep;
;             const char* a3 = a2 + kstep; const char* b3 = b2 + kstep;
;             PG8_LDB(B0, 0, 0); PG8_LDB(B1, 0, 1); PG8_SCHED; PG8_LDA(At, 0, 0); PG8_STAGE(PG8_SA(1, 1), a1 + hstep, voffA);
;             PG8_WAIT_V(8); PG8_WAIT_L(0); PG8_BAR; PG8_MMA(0, 0, At, B0); PG8_MMA(0, 1, At, B1); PG8_BAR; PG8_SCHED;
;             PG8_LDA(At, 0, 1); PG8_STAGE(PG8_SB(0, 0), b2, voffB); PG8_STAGE(PG8_SB(0, 1), b2 + hstep, voffB); PG8_STAGE(PG8_SA(0, 0), a2, voffA);
;             PG8_WAIT_V(8); PG8_WAIT_L(0); PG8_BAR; PG8_MMA(1, 0, At, B0); PG8_MMA(1, 1, At, B1); PG8_BAR; PG8_SCHED;
.LBB0_449:
	s_add_u32 s43, s24, 0x100
	s_addc_u32 s44, s25, 0
	s_add_u32 s24, s10, 0xb0080
	s_addc_u32 s25, s11, 0
	v_lshl_add_u64 v[0:1], s[24:25], 0, v[150:151]
	v_lshl_add_u64 v[154:155], s[24:25], 0, v[152:153]
	s_mov_b32 s45, -2
	s_mov_b64 s[24:25], 0
	s_add_u32 s26, s10, s24
	s_addc_u32 s27, s11, s25
	s_add_u32 s26, s26, 0x100
	s_addc_u32 s27, s27, 0
	s_add_u32 s68, s43, s24
	s_addc_u32 s77, s44, s25
	s_add_i32 s83, 0, 0x10000
	s_cmpk_eq_i32 s24, 0x1500
	s_cselect_b32 s29, s21, s27
	s_cselect_b32 s28, s20, s26
	v_add_u32_e32 v3, s83, v157
	s_cselect_b32 s27, s9, s77
	s_cselect_b32 s26, s8, s68
	s_add_i32 s68, 0, 0x14000
	ds_read_b128 v[132:135], v3
	ds_read_b128 v[140:143], v3 offset:1024
	ds_read_b128 v[160:163], v3 offset:2048
	ds_read_b128 v[164:167], v3 offset:3072
	v_add_u32_e32 v3, s68, v157
	ds_read_b128 v[168:171], v3
	ds_read_b128 v[172:175], v3 offset:1024
	ds_read_b128 v[176:179], v3 offset:2048
	ds_read_b128 v[180:183], v3 offset:3072
	v_lshl_add_u64 v[200:201], v[154:155], 0, s[24:25]
	s_add_i32 m0, s71, 0xc000
	ds_read_b128 v[184:187], v159
	ds_read_b128 v[188:191], v159 offset:1024
	ds_read_b128 v[192:195], v159 offset:2048
	ds_read_b128 v[196:199], v159 offset:3072
	ds_read_b128 v[214:217], v159 offset:4096
	ds_read_b128 v[218:221], v159 offset:5120
	ds_read_b128 v[222:225], v159 offset:6144
	ds_read_b128 v[226:229], v159 offset:7168
	global_load_lds_dwordx4 v[200:201], off
	v_lshl_add_u64 v[200:201], v[0:1], 0, s[24:25]
	s_add_i32 m0, s71, 0xe000
	s_nop 0
	global_load_lds_dwordx4 v[200:201], off
	s_waitcnt vmcnt(8)
	s_waitcnt lgkmcnt(0)
	s_barrier
	s_waitcnt lgkmcnt(0)
	v_mfma_f32_16x16x32_bf16 v[100:103], v[132:135], v[184:187], 0
	v_mfma_f32_16x16x32_bf16 v[108:111], v[160:163], v[184:187], 0
	v_mfma_f32_16x16x32_bf16 v[120:123], v[132:135], v[192:195], 0
	v_mfma_f32_16x16x32_bf16 v[128:131], v[160:163], v[192:195], 0
	v_mfma_f32_16x16x32_bf16 v[96:99], v[132:135], v[214:217], 0
	v_mfma_f32_16x16x32_bf16 v[92:95], v[160:163], v[214:217], 0
	v_mfma_f32_16x16x32_bf16 v[80:83], v[132:135], v[222:225], 0
	v_mfma_f32_16x16x32_bf16 v[76:79], v[160:163], v[222:225], 0
	v_mfma_f32_16x16x32_bf16 v[100:103], v[140:143], v[188:191], v[100:103]
	v_mfma_f32_16x16x32_bf16 v[108:111], v[164:167], v[188:191], v[108:111]
	v_mfma_f32_16x16x32_bf16 v[120:123], v[140:143], v[196:199], v[120:123]
	v_mfma_f32_16x16x32_bf16 v[128:131], v[164:167], v[196:199], v[128:131]
	v_mfma_f32_16x16x32_bf16 v[96:99], v[140:143], v[218:221], v[96:99]
	v_mfma_f32_16x16x32_bf16 v[92:95], v[164:167], v[218:221], v[92:95]
	v_mfma_f32_16x16x32_bf16 v[80:83], v[140:143], v[226:229], v[80:83]
	v_mfma_f32_16x16x32_bf16 v[76:79], v[164:167], v[226:229], v[76:79]
	v_mfma_f32_16x16x32_bf16 v[116:119], v[168:171], v[184:187], 0
	v_mfma_f32_16x16x32_bf16 v[124:127], v[176:179], v[184:187], 0
	v_mfma_f32_16x16x32_bf16 v[112:115], v[168:171], v[192:195], 0
	v_mfma_f32_16x16x32_bf16 v[104:107], v[176:179], v[192:195], 0
	v_mfma_f32_16x16x32_bf16 v[88:91], v[168:171], v[214:217], 0
	v_mfma_f32_16x16x32_bf16 v[84:87], v[176:179], v[214:217], 0
	v_mfma_f32_16x16x32_bf16 v[72:75], v[168:171], v[222:225], 0
	v_mfma_f32_16x16x32_bf16 v[68:71], v[176:179], v[222:225], 0
	v_mfma_f32_16x16x32_bf16 v[116:119], v[172:175], v[188:191], v[116:119]
	v_mfma_f32_16x16x32_bf16 v[124:127], v[180:183], v[188:191], v[124:127]
	v_mfma_f32_16x16x32_bf16 v[112:115], v[172:175], v[196:199], v[112:115]
	v_mfma_f32_16x16x32_bf16 v[104:107], v[180:183], v[196:199], v[104:107]
	v_mfma_f32_16x16x32_bf16 v[88:91], v[172:175], v[218:221], v[88:91]
	v_mfma_f32_16x16x32_bf16 v[84:87], v[180:183], v[218:221], v[84:87]
	v_mfma_f32_16x16x32_bf16 v[72:75], v[172:175], v[226:229], v[72:75]
	v_mfma_f32_16x16x32_bf16 v[68:71], v[180:183], v[226:229], v[68:71]
	s_barrier
	s_add_i32 s77, s83, s70
	v_lshl_add_u64 v[200:201], s[26:27], 0, v[146:147]
	s_mov_b32 m0, s77
	ds_read_b128 v[184:187], v159 offset:16384
	ds_read_b128 v[188:191], v159 offset:17408
	ds_read_b128 v[192:195], v159 offset:18432
	ds_read_b128 v[196:199], v159 offset:19456
	ds_read_b128 v[214:217], v159 offset:20480
	ds_read_b128 v[218:221], v159 offset:21504
	ds_read_b128 v[222:225], v159 offset:22528
	ds_read_b128 v[226:229], v159 offset:23552
	global_load_lds_dwordx4 v[200:201], off
	s_add_i32 m0, s77, 0x2000
	s_add_u32 s86, s26, 0xb0000
	v_lshl_add_u64 v[230:231], s[26:27], 0, v[148:149]
	s_addc_u32 s87, s27, 0
	s_add_i32 s68, s68, s70
	global_load_lds_dwordx4 v[230:231], off
	v_lshl_add_u64 v[232:233], s[86:87], 0, v[146:147]
	s_mov_b32 m0, s68
	v_lshl_add_u64 v[234:235], s[28:29], 0, v[148:149]
	global_load_lds_dwordx4 v[232:233], off
	v_lshl_add_u64 v[232:233], s[86:87], 0, v[148:149]
	s_add_i32 m0, s68, 0x2000
	s_nop 0
	global_load_lds_dwordx4 v[232:233], off
	v_lshl_add_u64 v[232:233], s[28:29], 0, v[146:147]
	s_mov_b32 m0, s71
	s_nop 0
	global_load_lds_dwordx4 v[232:233], off
	s_mov_b32 m0, s72
	s_nop 0
	global_load_lds_dwordx4 v[234:235], off
	s_waitcnt vmcnt(8)
	s_waitcnt lgkmcnt(0)
	s_barrier
; #define PG8_STAGE(bufoff, gbase, voff) do { _Pragma("unroll") for (int _i = 0; _i < 2; ++_i) \
;         __builtin_amdgcn_global_load_lds((const unsigned*)((const char*)(gbase) + (voff)[_i]), (LAS unsigned*)(lds + (bufoff) + ldsw + _i * 8192), 16, 0, 0); } while (0)
; #define PG8_LDA(dst, b, h) do { _Pragma("unroll") for (int m = 0; m < 4; ++m) _Pragma("unroll") for (int k = 0; k < 2; ++k) dst[m][k] = *(const LAS bf16x8*)(lds + PG8_SA(b, h) + aoff + m * 2048 + k * 1024); } while (0)
; #define PG8_LDB(dst, b, h) do { _Pragma("unroll") for (int n = 0; n < 2; ++n) _Pragma("unroll") for (int k = 0; k < 2; ++k) dst[n][k] = *(const LAS bf16x8*)(lds + PG8_SB(b, h) + boff + n * 2048 + k * 1024); } while (0)
; #define PG8_MMA(ai, bj, At, Bt) do { __builtin_amdgcn_s_setprio(1); _Pragma("unroll") for (int m = 0; m < 4; ++m) _Pragma("unroll") for (int n = 0; n < 2; ++n) _Pragma("unroll") for (int k = 0; k < 2; ++k) \
;         acc[ai][bj][m][n] = __builtin_amdgcn_mfma_f32_16x16x32_bf16(Bt[n][k], At[m][k], acc[ai][bj][m][n], 0, 0, 0); __builtin_amdgcn_s_setprio(0); } while (0)
; #define PG8_WAIT_V(n) asm volatile("s_waitcnt vmcnt(" #n ")" ::: "memory")
; #define PG8_WAIT_L(n) asm volatile("s_waitcnt lgkmcnt(" #n ")" ::: "memory")
; #define PG8_BAR __builtin_amdgcn_s_barrier()
; #define PG8_SCHED __builtin_amdgcn_sched_barrier(0)
; template <class Epi>
; __device__ __forceinline__ void gemm_phase(LAS unsigned char* lds, const Gemm g, const int G, const int cidx, const Epi& E) {
;     ...
;             PG8_WAIT_V(8); PG8_WAIT_L(0); PG8_BAR; PG8_MMA(1, 0, At, B0); PG8_MMA(1, 1, At, B1); PG8_BAR; PG8_SCHED;
;             PG8_LDB(B0, 1, 0); PG8_LDB(B1, 1, 1); PG8_SCHED; PG8_LDA(At, 1, 0); PG8_STAGE(PG8_SA(0, 1), a2 + hstep, voffA);
;             PG8_WAIT_V(8); PG8_WAIT_L(0); PG8_BAR; PG8_MMA(0, 0, At, B0); PG8_MMA(0, 1, At, B1); PG8_BAR; PG8_SCHED;
;             PG8_LDA(At, 1, 1); PG8_STAGE(PG8_SB(1, 0), b3, voffB); PG8_STAGE(PG8_SB(1, 1), b3 + hstep, voffB); PG8_STAGE(PG8_SA(1, 0), a3, voffA);
;             PG8_WAIT_V(8); PG8_WAIT_L(0); PG8_BAR; PG8_MMA(1, 0, At, B0); PG8_MMA(1, 1, At, B1); PG8_BAR; PG8_SCHED;
	s_waitcnt lgkmcnt(0)
	v_mfma_f32_16x16x32_bf16 v[64:67], v[132:135], v[184:187], 0
	v_mfma_f32_16x16x32_bf16 v[60:63], v[160:163], v[184:187], 0
	v_mfma_f32_16x16x32_bf16 v[48:51], v[132:135], v[192:195], 0
	v_mfma_f32_16x16x32_bf16 v[44:47], v[160:163], v[192:195], 0
	v_mfma_f32_16x16x32_bf16 v[32:35], v[132:135], v[214:217], 0
	v_mfma_f32_16x16x32_bf16 v[28:31], v[160:163], v[214:217], 0
	v_mfma_f32_16x16x32_bf16 v[16:19], v[132:135], v[222:225], 0
	v_mfma_f32_16x16x32_bf16 v[12:15], v[160:163], v[222:225], 0
	v_mfma_f32_16x16x32_bf16 v[64:67], v[140:143], v[188:191], v[64:67]
	v_mfma_f32_16x16x32_bf16 v[60:63], v[164:167], v[188:191], v[60:63]
	v_mfma_f32_16x16x32_bf16 v[48:51], v[140:143], v[196:199], v[48:51]
	v_mfma_f32_16x16x32_bf16 v[44:47], v[164:167], v[196:199], v[44:47]
	v_mfma_f32_16x16x32_bf16 v[32:35], v[140:143], v[218:221], v[32:35]
	v_mfma_f32_16x16x32_bf16 v[28:31], v[164:167], v[218:221], v[28:31]
	v_mfma_f32_16x16x32_bf16 v[16:19], v[140:143], v[226:229], v[16:19]
	v_mfma_f32_16x16x32_bf16 v[12:15], v[164:167], v[226:229], v[12:15]
	v_mfma_f32_16x16x32_bf16 v[56:59], v[168:171], v[184:187], 0
	v_mfma_f32_16x16x32_bf16 v[52:55], v[176:179], v[184:187], 0
	v_mfma_f32_16x16x32_bf16 v[40:43], v[168:171], v[192:195], 0
	v_mfma_f32_16x16x32_bf16 v[36:39], v[176:179], v[192:195], 0
	v_mfma_f32_16x16x32_bf16 v[24:27], v[168:171], v[214:217], 0
	v_mfma_f32_16x16x32_bf16 v[20:23], v[176:179], v[214:217], 0
	v_mfma_f32_16x16x32_bf16 v[8:11], v[168:171], v[222:225], 0
	v_mfma_f32_16x16x32_bf16 v[4:7], v[176:179], v[222:225], 0
	v_mfma_f32_16x16x32_bf16 v[56:59], v[172:175], v[188:191], v[56:59]
	v_mfma_f32_16x16x32_bf16 v[52:55], v[180:183], v[188:191], v[52:55]
	v_mfma_f32_16x16x32_bf16 v[40:43], v[172:175], v[196:199], v[40:43]
	v_mfma_f32_16x16x32_bf16 v[36:39], v[180:183], v[196:199], v[36:39]
	v_mfma_f32_16x16x32_bf16 v[24:27], v[172:175], v[218:221], v[24:27]
	v_mfma_f32_16x16x32_bf16 v[20:23], v[180:183], v[218:221], v[20:23]
	v_mfma_f32_16x16x32_bf16 v[8:11], v[172:175], v[226:229], v[8:11]
	v_mfma_f32_16x16x32_bf16 v[4:7], v[180:183], v[226:229], v[4:7]
	s_barrier
	s_add_i32 s68, 0, 0x18000
	v_add_u32_e32 v3, s68, v157
	s_add_i32 s77, 0, 0x1c000
	ds_read_b128 v[132:135], v3
	ds_read_b128 v[140:143], v3 offset:1024
	ds_read_b128 v[160:163], v3 offset:2048
	ds_read_b128 v[164:167], v3 offset:3072
	v_add_u32_e32 v3, s77, v157
	ds_read_b128 v[168:171], v3
	ds_read_b128 v[172:175], v3 offset:1024
	ds_read_b128 v[176:179], v3 offset:2048
	ds_read_b128 v[180:183], v3 offset:3072
	s_add_u32 s28, s28, 0xb0000
	s_addc_u32 s29, s29, 0
	s_mov_b32 m0, s73
	v_lshl_add_u64 v[236:237], s[28:29], 0, v[146:147]
	ds_read_b128 v[184:187], v159 offset:32768
	ds_read_b128 v[188:191], v159 offset:33792
	ds_read_b128 v[192:195], v159 offset:34816
	ds_read_b128 v[196:199], v159 offset:35840
	ds_read_b128 v[214:217], v159 offset:36864
	ds_read_b128 v[218:221], v159 offset:37888
	ds_read_b128 v[222:225], v159 offset:38912
	ds_read_b128 v[226:229], v159 offset:39936
	global_load_lds_dwordx4 v[236:237], off
	v_lshl_add_u64 v[236:237], s[28:29], 0, v[148:149]
	s_mov_b32 m0, s74
	s_nop 0
	global_load_lds_dwordx4 v[236:237], off
	s_waitcnt vmcnt(8)
	s_waitcnt lgkmcnt(0)
	s_barrier
	s_waitcnt lgkmcnt(0)
	v_mfma_f32_16x16x32_bf16 v[100:103], v[132:135], v[184:187], v[100:103]
	v_mfma_f32_16x16x32_bf16 v[108:111], v[160:163], v[184:187], v[108:111]
	v_mfma_f32_16x16x32_bf16 v[120:123], v[132:135], v[192:195], v[120:123]
	v_mfma_f32_16x16x32_bf16 v[128:131], v[160:163], v[192:195], v[128:131]
	v_mfma_f32_16x16x32_bf16 v[96:99], v[132:135], v[214:217], v[96:99]
	v_mfma_f32_16x16x32_bf16 v[92:95], v[160:163], v[214:217], v[92:95]
	v_mfma_f32_16x16x32_bf16 v[80:83], v[132:135], v[222:225], v[80:83]
	v_mfma_f32_16x16x32_bf16 v[76:79], v[160:163], v[222:225], v[76:79]
	v_mfma_f32_16x16x32_bf16 v[100:103], v[140:143], v[188:191], v[100:103]
	v_mfma_f32_16x16x32_bf16 v[108:111], v[164:167], v[188:191], v[108:111]
	v_mfma_f32_16x16x32_bf16 v[120:123], v[140:143], v[196:199], v[120:123]
	v_mfma_f32_16x16x32_bf16 v[128:131], v[164:167], v[196:199], v[128:131]
	v_mfma_f32_16x16x32_bf16 v[96:99], v[140:143], v[218:221], v[96:99]
	v_mfma_f32_16x16x32_bf16 v[92:95], v[164:167], v[218:221], v[92:95]
	v_mfma_f32_16x16x32_bf16 v[80:83], v[140:143], v[226:229], v[80:83]
	v_mfma_f32_16x16x32_bf16 v[76:79], v[164:167], v[226:229], v[76:79]
	v_mfma_f32_16x16x32_bf16 v[116:119], v[168:171], v[184:187], v[116:119]
	v_mfma_f32_16x16x32_bf16 v[124:127], v[176:179], v[184:187], v[124:127]
	v_mfma_f32_16x16x32_bf16 v[112:115], v[168:171], v[192:195], v[112:115]
	v_mfma_f32_16x16x32_bf16 v[104:107], v[176:179], v[192:195], v[104:107]
	v_mfma_f32_16x16x32_bf16 v[88:91], v[168:171], v[214:217], v[88:91]
	v_mfma_f32_16x16x32_bf16 v[84:87], v[176:179], v[214:217], v[84:87]
	v_mfma_f32_16x16x32_bf16 v[72:75], v[168:171], v[222:225], v[72:75]
	v_mfma_f32_16x16x32_bf16 v[68:71], v[176:179], v[222:225], v[68:71]
	v_mfma_f32_16x16x32_bf16 v[116:119], v[172:175], v[188:191], v[116:119]
	v_mfma_f32_16x16x32_bf16 v[124:127], v[180:183], v[188:191], v[124:127]
	v_mfma_f32_16x16x32_bf16 v[112:115], v[172:175], v[196:199], v[112:115]
	v_mfma_f32_16x16x32_bf16 v[104:107], v[180:183], v[196:199], v[104:107]
	v_mfma_f32_16x16x32_bf16 v[88:91], v[172:175], v[218:221], v[88:91]
	v_mfma_f32_16x16x32_bf16 v[84:87], v[180:183], v[218:221], v[84:87]
	v_mfma_f32_16x16x32_bf16 v[72:75], v[172:175], v[226:229], v[72:75]
	v_mfma_f32_16x16x32_bf16 v[68:71], v[180:183], v[226:229], v[68:71]
	s_barrier
; #define PG8_STAGE(bufoff, gbase, voff) do { _Pragma("unroll") for (int _i = 0; _i < 2; ++_i) \
;         __builtin_amdgcn_global_load_lds((const unsigned*)((const char*)(gbase) + (voff)[_i]), (LAS unsigned*)(lds + (bufoff) + ldsw + _i * 8192), 16, 0, 0); } while (0)
; #define PG8_LDA(dst, b, h) do { _Pragma("unroll") for (int m = 0; m < 4; ++m) _Pragma("unroll") for (int k = 0; k < 2; ++k) dst[m][k] = *(const LAS bf16x8*)(lds + PG8_SA(b, h) + aoff + m * 2048 + k * 1024); } while (0)
; #define PG8_LDB(dst, b, h) do { _Pragma("unroll") for (int n = 0; n < 2; ++n) _Pragma("unroll") for (int k = 0; k < 2; ++k) dst[n][k] = *(const LAS bf16x8*)(lds + PG8_SB(b, h) + boff + n * 2048 + k * 1024); } while (0)
; #define PG8_MMA(ai, bj, At, Bt) do { __builtin_amdgcn_s_setprio(1); _Pragma("unroll") for (int m = 0; m < 4; ++m) _Pragma("unroll") for (int n = 0; n < 2; ++n) _Pragma("unroll") for (int k = 0; k < 2; ++k) \
;         acc[ai][bj][m][n] = __builtin_amdgcn_mfma_f32_16x16x32_bf16(Bt[n][k], At[m][k], acc[ai][bj][m][n], 0, 0, 0); __builtin_amdgcn_s_setprio(0); } while (0)
; #define PG8_WAIT_V(n) asm volatile("s_waitcnt vmcnt(" #n ")" ::: "memory")
; #define PG8_WAIT_L(n) asm volatile("s_waitcnt lgkmcnt(" #n ")" ::: "memory")
; #define PG8_BAR __builtin_amdgcn_s_barrier()
; #define PG8_SCHED __builtin_amdgcn_sched_barrier(0)
; template <class Epi>
; __device__ __forceinline__ void gemm_phase(LAS unsigned char* lds, const Gemm g, const int G, const int cidx, const Epi& E) {
;     ...
;         for (int t = 0; t < nt; t += 2) {
;             const bool last = (t == nt - 2);
;             const char* a1 = cA + (size_t)(t + 1) * kstep;
;             const char* a2 = last ? nA : cA + (size_t)(t + 2) * kstep; const char* b2 = last ? nB : cB + (size_t)(t + 2) * kstep;
;             const char* a3 = a2 + kstep; const char* b3 = b2 + kstep;
;             PG8_LDB(B0, 0, 0); PG8_LDB(B1, 0, 1); PG8_SCHED; PG8_LDA(At, 0, 0); PG8_STAGE(PG8_SA(1, 1), a1 + hstep, voffA);
;     ...
;             PG8_LDA(At, 1, 1); PG8_STAGE(PG8_SB(1, 0), b3, voffB); PG8_STAGE(PG8_SB(1, 1), b3 + hstep, voffB); PG8_STAGE(PG8_SA(1, 0), a3, voffA);
;             PG8_WAIT_V(8); PG8_WAIT_L(0); PG8_BAR; PG8_MMA(1, 0, At, B0); PG8_MMA(1, 1, At, B1); PG8_BAR; PG8_SCHED;
	s_add_i32 s28, s68, s70
	v_lshl_add_u64 v[200:201], v[200:201], 0, s[46:47]
	s_mov_b32 m0, s28
	ds_read_b128 v[184:187], v159 offset:49152
	ds_read_b128 v[188:191], v159 offset:50176
	ds_read_b128 v[192:195], v159 offset:51200
	ds_read_b128 v[196:199], v159 offset:52224
	ds_read_b128 v[214:217], v159 offset:53248
	ds_read_b128 v[218:221], v159 offset:54272
	ds_read_b128 v[222:225], v159 offset:55296
	ds_read_b128 v[226:229], v159 offset:56320
	global_load_lds_dwordx4 v[200:201], off
	s_add_i32 m0, s28, 0x2000
	s_add_u32 s26, s26, 0xb0080
	v_lshl_add_u64 v[200:201], v[230:231], 0, s[46:47]
	s_addc_u32 s27, s27, 0
	s_add_i32 s28, s77, s70
	global_load_lds_dwordx4 v[200:201], off
	v_lshl_add_u64 v[200:201], s[26:27], 0, v[146:147]
	s_mov_b32 m0, s28
	s_nop 0
	global_load_lds_dwordx4 v[200:201], off
	v_lshl_add_u64 v[200:201], s[26:27], 0, v[148:149]
	s_add_i32 m0, s28, 0x2000
	s_nop 0
	global_load_lds_dwordx4 v[200:201], off
	v_lshl_add_u64 v[200:201], v[232:233], 0, s[46:47]
	s_mov_b32 m0, s75
	s_nop 0
	global_load_lds_dwordx4 v[200:201], off
	v_lshl_add_u64 v[200:201], v[234:235], 0, s[46:47]
	s_mov_b32 m0, s76
	s_nop 0
	global_load_lds_dwordx4 v[200:201], off
	s_waitcnt vmcnt(8)
	s_waitcnt lgkmcnt(0)
	s_barrier
	s_waitcnt lgkmcnt(0)
	v_mfma_f32_16x16x32_bf16 v[64:67], v[132:135], v[184:187], v[64:67]
	v_mfma_f32_16x16x32_bf16 v[60:63], v[160:163], v[184:187], v[60:63]
	v_mfma_f32_16x16x32_bf16 v[48:51], v[132:135], v[192:195], v[48:51]
	v_mfma_f32_16x16x32_bf16 v[44:47], v[160:163], v[192:195], v[44:47]
	v_mfma_f32_16x16x32_bf16 v[32:35], v[132:135], v[214:217], v[32:35]
	v_mfma_f32_16x16x32_bf16 v[28:31], v[160:163], v[214:217], v[28:31]
	v_mfma_f32_16x16x32_bf16 v[16:19], v[132:135], v[222:225], v[16:19]
	v_mfma_f32_16x16x32_bf16 v[12:15], v[160:163], v[222:225], v[12:15]
	v_mfma_f32_16x16x32_bf16 v[64:67], v[140:143], v[188:191], v[64:67]
	v_mfma_f32_16x16x32_bf16 v[60:63], v[164:167], v[188:191], v[60:63]
	v_mfma_f32_16x16x32_bf16 v[48:51], v[140:143], v[196:199], v[48:51]
	v_mfma_f32_16x16x32_bf16 v[44:47], v[164:167], v[196:199], v[44:47]
	v_mfma_f32_16x16x32_bf16 v[32:35], v[140:143], v[218:221], v[32:35]
	v_mfma_f32_16x16x32_bf16 v[28:31], v[164:167], v[218:221], v[28:31]
	v_mfma_f32_16x16x32_bf16 v[16:19], v[140:143], v[226:229], v[16:19]
	v_mfma_f32_16x16x32_bf16 v[12:15], v[164:167], v[226:229], v[12:15]
	v_mfma_f32_16x16x32_bf16 v[56:59], v[168:171], v[184:187], v[56:59]
	v_mfma_f32_16x16x32_bf16 v[52:55], v[176:179], v[184:187], v[52:55]
	v_mfma_f32_16x16x32_bf16 v[40:43], v[168:171], v[192:195], v[40:43]
	v_mfma_f32_16x16x32_bf16 v[36:39], v[176:179], v[192:195], v[36:39]
	v_mfma_f32_16x16x32_bf16 v[24:27], v[168:171], v[214:217], v[24:27]
	v_mfma_f32_16x16x32_bf16 v[20:23], v[176:179], v[214:217], v[20:23]
	v_mfma_f32_16x16x32_bf16 v[8:11], v[168:171], v[222:225], v[8:11]
	v_mfma_f32_16x16x32_bf16 v[4:7], v[176:179], v[222:225], v[4:7]
	v_mfma_f32_16x16x32_bf16 v[56:59], v[172:175], v[188:191], v[56:59]
	v_mfma_f32_16x16x32_bf16 v[52:55], v[180:183], v[188:191], v[52:55]
	v_mfma_f32_16x16x32_bf16 v[40:43], v[172:175], v[196:199], v[40:43]
	v_mfma_f32_16x16x32_bf16 v[36:39], v[180:183], v[196:199], v[36:39]
	v_mfma_f32_16x16x32_bf16 v[24:27], v[172:175], v[218:221], v[24:27]
	v_mfma_f32_16x16x32_bf16 v[20:23], v[180:183], v[218:221], v[20:23]
	v_mfma_f32_16x16x32_bf16 v[8:11], v[172:175], v[226:229], v[8:11]
	v_mfma_f32_16x16x32_bf16 v[4:7], v[180:183], v[226:229], v[4:7]
	s_barrier
	s_add_i32 s45, s45, 2
	s_add_u32 s24, s24, 0x100
	s_addc_u32 s25, s25, 0
.LBB0_450:
	s_add_u32 s26, s10, s24
	s_addc_u32 s27, s11, s25
	s_add_u32 s26, s26, 0x100
	s_addc_u32 s27, s27, 0
	s_add_u32 s68, s43, s24
	s_addc_u32 s77, s44, s25
	s_add_i32 s83, 0, 0x10000
	s_cmpk_eq_i32 s24, 0x1500
	s_cselect_b32 s29, s21, s27
	s_cselect_b32 s28, s20, s26
	v_add_u32_e32 v3, s83, v157
	s_cselect_b32 s27, s9, s77
	s_cselect_b32 s26, s8, s68
	s_add_i32 s68, 0, 0x14000
	ds_read_b128 v[132:135], v3
	ds_read_b128 v[140:143], v3 offset:1024
	ds_read_b128 v[160:163], v3 offset:2048
	ds_read_b128 v[164:167], v3 offset:3072
	v_add_u32_e32 v3, s68, v157
	ds_read_b128 v[168:171], v3
	ds_read_b128 v[172:175], v3 offset:1024
	ds_read_b128 v[176:179], v3 offset:2048
	ds_read_b128 v[180:183], v3 offset:3072
	v_lshl_add_u64 v[200:201], v[154:155], 0, s[24:25]
	s_add_i32 m0, s71, 0xc000
	ds_read_b128 v[184:187], v159
	ds_read_b128 v[188:191], v159 offset:1024
	ds_read_b128 v[192:195], v159 offset:2048
	ds_read_b128 v[196:199], v159 offset:3072
	ds_read_b128 v[214:217], v159 offset:4096
	ds_read_b128 v[218:221], v159 offset:5120
	ds_read_b128 v[222:225], v159 offset:6144
	ds_read_b128 v[226:229], v159 offset:7168
	global_load_lds_dwordx4 v[200:201], off
	v_lshl_add_u64 v[200:201], v[0:1], 0, s[24:25]
	s_add_i32 m0, s71, 0xe000
	s_nop 0
	global_load_lds_dwordx4 v[200:201], off
	s_waitcnt vmcnt(8)
	s_waitcnt lgkmcnt(0)
	s_barrier
; #define PG8_STAGE(bufoff, gbase, voff) do { _Pragma("unroll") for (int _i = 0; _i < 2; ++_i) \
;         __builtin_amdgcn_global_load_lds((const unsigned*)((const char*)(gbase) + (voff)[_i]), (LAS unsigned*)(lds + (bufoff) + ldsw + _i * 8192), 16, 0, 0); } while (0)
; #define PG8_LDA(dst, b, h) do { _Pragma("unroll") for (int m = 0; m < 4; ++m) _Pragma("unroll") for (int k = 0; k < 2; ++k) dst[m][k] = *(const LAS bf16x8*)(lds + PG8_SA(b, h) + aoff + m * 2048 + k * 1024); } while (0)
; #define PG8_LDB(dst, b, h) do { _Pragma("unroll") for (int n = 0; n < 2; ++n) _Pragma("unroll") for (int k = 0; k < 2; ++k) dst[n][k] = *(const LAS bf16x8*)(lds + PG8_SB(b, h) + boff + n * 2048 + k * 1024); } while (0)
; #define PG8_MMA(ai, bj, At, Bt) do { __builtin_amdgcn_s_setprio(1); _Pragma("unroll") for (int m = 0; m < 4; ++m) _Pragma("unroll") for (int n = 0; n < 2; ++n) _Pragma("unroll") for (int k = 0; k < 2; ++k) \
;         acc[ai][bj][m][n] = __builtin_amdgcn_mfma_f32_16x16x32_bf16(Bt[n][k], At[m][k], acc[ai][bj][m][n], 0, 0, 0); __builtin_amdgcn_s_setprio(0); } while (0)
; #define PG8_WAIT_V(n) asm volatile("s_waitcnt vmcnt(" #n ")" ::: "memory")
; #define PG8_WAIT_L(n) asm volatile("s_waitcnt lgkmcnt(" #n ")" ::: "memory")
; #define PG8_BAR __builtin_amdgcn_s_barrier()
; #define PG8_SCHED __builtin_amdgcn_sched_barrier(0)
; template <class Epi>
; __device__ __forceinline__ void gemm_phase(LAS unsigned char* lds, const Gemm g, const int G, const int cidx, const Epi& E) {
;     ...
;             PG8_WAIT_V(8); PG8_WAIT_L(0); PG8_BAR; PG8_MMA(0, 0, At, B0); PG8_MMA(0, 1, At, B1); PG8_BAR; PG8_SCHED;
;             PG8_LDA(At, 0, 1); PG8_STAGE(PG8_SB(0, 0), b2, voffB); PG8_STAGE(PG8_SB(0, 1), b2 + hstep, voffB); PG8_STAGE(PG8_SA(0, 0), a2, voffA);
;             PG8_WAIT_V(8); PG8_WAIT_L(0); PG8_BAR; PG8_MMA(1, 0, At, B0); PG8_MMA(1, 1, At, B1); PG8_BAR; PG8_SCHED;
;             PG8_LDB(B0, 1, 0); PG8_LDB(B1, 1, 1); PG8_SCHED; PG8_LDA(At, 1, 0); PG8_STAGE(PG8_SA(0, 1), a2 + hstep, voffA);
;             PG8_WAIT_V(8); PG8_WAIT_L(0); PG8_BAR; PG8_MMA(0, 0, At, B0); PG8_MMA(0, 1, At, B1); PG8_BAR; PG8_SCHED;
	s_waitcnt lgkmcnt(0)
	v_mfma_f32_16x16x32_bf16 v[100:103], v[132:135], v[184:187], v[100:103]
	v_mfma_f32_16x16x32_bf16 v[108:111], v[160:163], v[184:187], v[108:111]
	v_mfma_f32_16x16x32_bf16 v[120:123], v[132:135], v[192:195], v[120:123]
	v_mfma_f32_16x16x32_bf16 v[128:131], v[160:163], v[192:195], v[128:131]
	v_mfma_f32_16x16x32_bf16 v[96:99], v[132:135], v[214:217], v[96:99]
	v_mfma_f32_16x16x32_bf16 v[92:95], v[160:163], v[214:217], v[92:95]
	v_mfma_f32_16x16x32_bf16 v[80:83], v[132:135], v[222:225], v[80:83]
	v_mfma_f32_16x16x32_bf16 v[76:79], v[160:163], v[222:225], v[76:79]
	v_mfma_f32_16x16x32_bf16 v[100:103], v[140:143], v[188:191], v[100:103]
	v_mfma_f32_16x16x32_bf16 v[108:111], v[164:167], v[188:191], v[108:111]
	v_mfma_f32_16x16x32_bf16 v[120:123], v[140:143], v[196:199], v[120:123]
	v_mfma_f32_16x16x32_bf16 v[128:131], v[164:167], v[196:199], v[128:131]
	v_mfma_f32_16x16x32_bf16 v[96:99], v[140:143], v[218:221], v[96:99]
	v_mfma_f32_16x16x32_bf16 v[92:95], v[164:167], v[218:221], v[92:95]
	v_mfma_f32_16x16x32_bf16 v[80:83], v[140:143], v[226:229], v[80:83]
	v_mfma_f32_16x16x32_bf16 v[76:79], v[164:167], v[226:229], v[76:79]
	v_mfma_f32_16x16x32_bf16 v[116:119], v[168:171], v[184:187], v[116:119]
	v_mfma_f32_16x16x32_bf16 v[124:127], v[176:179], v[184:187], v[124:127]
	v_mfma_f32_16x16x32_bf16 v[112:115], v[168:171], v[192:195], v[112:115]
	v_mfma_f32_16x16x32_bf16 v[104:107], v[176:179], v[192:195], v[104:107]
	v_mfma_f32_16x16x32_bf16 v[88:91], v[168:171], v[214:217], v[88:91]
	v_mfma_f32_16x16x32_bf16 v[84:87], v[176:179], v[214:217], v[84:87]
	v_mfma_f32_16x16x32_bf16 v[72:75], v[168:171], v[222:225], v[72:75]
	v_mfma_f32_16x16x32_bf16 v[68:71], v[176:179], v[222:225], v[68:71]
	v_mfma_f32_16x16x32_bf16 v[116:119], v[172:175], v[188:191], v[116:119]
	v_mfma_f32_16x16x32_bf16 v[124:127], v[180:183], v[188:191], v[124:127]
	v_mfma_f32_16x16x32_bf16 v[112:115], v[172:175], v[196:199], v[112:115]
	v_mfma_f32_16x16x32_bf16 v[104:107], v[180:183], v[196:199], v[104:107]
	v_mfma_f32_16x16x32_bf16 v[88:91], v[172:175], v[218:221], v[88:91]
	v_mfma_f32_16x16x32_bf16 v[84:87], v[180:183], v[218:221], v[84:87]
	v_mfma_f32_16x16x32_bf16 v[72:75], v[172:175], v[226:229], v[72:75]
	v_mfma_f32_16x16x32_bf16 v[68:71], v[180:183], v[226:229], v[68:71]
	s_barrier
	s_add_i32 s77, s83, s70
	v_lshl_add_u64 v[200:201], s[26:27], 0, v[146:147]
	s_mov_b32 m0, s77
	ds_read_b128 v[184:187], v159 offset:16384
	ds_read_b128 v[188:191], v159 offset:17408
	ds_read_b128 v[192:195], v159 offset:18432
	ds_read_b128 v[196:199], v159 offset:19456
	ds_read_b128 v[214:217], v159 offset:20480
	ds_read_b128 v[218:221], v159 offset:21504
	ds_read_b128 v[222:225], v159 offset:22528
	ds_read_b128 v[226:229], v159 offset:23552
	global_load_lds_dwordx4 v[200:201], off
	s_add_i32 m0, s77, 0x2000
	s_add_u32 s86, s26, 0xb0000
	v_lshl_add_u64 v[230:231], s[26:27], 0, v[148:149]
	s_addc_u32 s87, s27, 0
	s_add_i32 s68, s68, s70
	global_load_lds_dwordx4 v[230:231], off
	v_lshl_add_u64 v[232:233], s[86:87], 0, v[146:147]
	s_mov_b32 m0, s68
	v_lshl_add_u64 v[234:235], s[28:29], 0, v[148:149]
	global_load_lds_dwordx4 v[232:233], off
	v_lshl_add_u64 v[232:233], s[86:87], 0, v[148:149]
	s_add_i32 m0, s68, 0x2000
	s_nop 0
	global_load_lds_dwordx4 v[232:233], off
	v_lshl_add_u64 v[232:233], s[28:29], 0, v[146:147]
	s_mov_b32 m0, s71
	s_nop 0
	global_load_lds_dwordx4 v[232:233], off
	s_mov_b32 m0, s72
	s_nop 0
	global_load_lds_dwordx4 v[234:235], off
	s_waitcnt vmcnt(8)
	s_waitcnt lgkmcnt(0)
	s_barrier
	s_waitcnt lgkmcnt(0)
	v_mfma_f32_16x16x32_bf16 v[64:67], v[132:135], v[184:187], v[64:67]
	v_mfma_f32_16x16x32_bf16 v[60:63], v[160:163], v[184:187], v[60:63]
	v_mfma_f32_16x16x32_bf16 v[48:51], v[132:135], v[192:195], v[48:51]
	v_mfma_f32_16x16x32_bf16 v[44:47], v[160:163], v[192:195], v[44:47]
	v_mfma_f32_16x16x32_bf16 v[32:35], v[132:135], v[214:217], v[32:35]
	v_mfma_f32_16x16x32_bf16 v[28:31], v[160:163], v[214:217], v[28:31]
	v_mfma_f32_16x16x32_bf16 v[16:19], v[132:135], v[222:225], v[16:19]
	v_mfma_f32_16x16x32_bf16 v[12:15], v[160:163], v[222:225], v[12:15]
	v_mfma_f32_16x16x32_bf16 v[64:67], v[140:143], v[188:191], v[64:67]
	v_mfma_f32_16x16x32_bf16 v[60:63], v[164:167], v[188:191], v[60:63]
	v_mfma_f32_16x16x32_bf16 v[48:51], v[140:143], v[196:199], v[48:51]
	v_mfma_f32_16x16x32_bf16 v[44:47], v[164:167], v[196:199], v[44:47]
	v_mfma_f32_16x16x32_bf16 v[32:35], v[140:143], v[218:221], v[32:35]
	v_mfma_f32_16x16x32_bf16 v[28:31], v[164:167], v[218:221], v[28:31]
	v_mfma_f32_16x16x32_bf16 v[16:19], v[140:143], v[226:229], v[16:19]
	v_mfma_f32_16x16x32_bf16 v[12:15], v[164:167], v[226:229], v[12:15]
	v_mfma_f32_16x16x32_bf16 v[56:59], v[168:171], v[184:187], v[56:59]
	v_mfma_f32_16x16x32_bf16 v[52:55], v[176:179], v[184:187], v[52:55]
	v_mfma_f32_16x16x32_bf16 v[40:43], v[168:171], v[192:195], v[40:43]
	v_mfma_f32_16x16x32_bf16 v[36:39], v[176:179], v[192:195], v[36:39]
	v_mfma_f32_16x16x32_bf16 v[24:27], v[168:171], v[214:217], v[24:27]
	v_mfma_f32_16x16x32_bf16 v[20:23], v[176:179], v[214:217], v[20:23]
	v_mfma_f32_16x16x32_bf16 v[8:11], v[168:171], v[222:225], v[8:11]
	v_mfma_f32_16x16x32_bf16 v[4:7], v[176:179], v[222:225], v[4:7]
	v_mfma_f32_16x16x32_bf16 v[56:59], v[172:175], v[188:191], v[56:59]
	v_mfma_f32_16x16x32_bf16 v[52:55], v[180:183], v[188:191], v[52:55]
	v_mfma_f32_16x16x32_bf16 v[40:43], v[172:175], v[196:199], v[40:43]
	v_mfma_f32_16x16x32_bf16 v[36:39], v[180:183], v[196:199], v[36:39]
	v_mfma_f32_16x16x32_bf16 v[24:27], v[172:175], v[218:221], v[24:27]
	v_mfma_f32_16x16x32_bf16 v[20:23], v[180:183], v[218:221], v[20:23]
	v_mfma_f32_16x16x32_bf16 v[8:11], v[172:175], v[226:229], v[8:11]
	v_mfma_f32_16x16x32_bf16 v[4:7], v[180:183], v[226:229], v[4:7]
	s_barrier
; #define PG8_STAGE(bufoff, gbase, voff) do { _Pragma("unroll") for (int _i = 0; _i < 2; ++_i) \
;         __builtin_amdgcn_global_load_lds((const unsigned*)((const char*)(gbase) + (voff)[_i]), (LAS unsigned*)(lds + (bufoff) + ldsw + _i * 8192), 16, 0, 0); } while (0)
; #define PG8_LDA(dst, b, h) do { _Pragma("unroll") for (int m = 0; m < 4; ++m) _Pragma("unroll") for (int k = 0; k < 2; ++k) dst[m][k] = *(const LAS bf16x8*)(lds + PG8_SA(b, h) + aoff + m * 2048 + k * 1024); } while (0)
; #define PG8_LDB(dst, b, h) do { _Pragma("unroll") for (int n = 0; n < 2; ++n) _Pragma("unroll") for (int k = 0; k < 2; ++k) dst[n][k] = *(const LAS bf16x8*)(lds + PG8_SB(b, h) + boff + n * 2048 + k * 1024); } while (0)
; #define PG8_MMA(ai, bj, At, Bt) do { __builtin_amdgcn_s_setprio(1); _Pragma("unroll") for (int m = 0; m < 4; ++m) _Pragma("unroll") for (int n = 0; n < 2; ++n) _Pragma("unroll") for (int k = 0; k < 2; ++k) \
;         acc[ai][bj][m][n] = __builtin_amdgcn_mfma_f32_16x16x32_bf16(Bt[n][k], At[m][k], acc[ai][bj][m][n], 0, 0, 0); __builtin_amdgcn_s_setprio(0); } while (0)
; #define PG8_WAIT_V(n) asm volatile("s_waitcnt vmcnt(" #n ")" ::: "memory")
; #define PG8_WAIT_L(n) asm volatile("s_waitcnt lgkmcnt(" #n ")" ::: "memory")
; #define PG8_BAR __builtin_amdgcn_s_barrier()
; #define PG8_SCHED __builtin_amdgcn_sched_barrier(0)
; template <class Epi>
; __device__ __forceinline__ void gemm_phase(LAS unsigned char* lds, const Gemm g, const int G, const int cidx, const Epi& E) {
;     ...
;             PG8_LDB(B0, 1, 0); PG8_LDB(B1, 1, 1); PG8_SCHED; PG8_LDA(At, 1, 0); PG8_STAGE(PG8_SA(0, 1), a2 + hstep, voffA);
;             PG8_WAIT_V(8); PG8_WAIT_L(0); PG8_BAR; PG8_MMA(0, 0, At, B0); PG8_MMA(0, 1, At, B1); PG8_BAR; PG8_SCHED;
;             PG8_LDA(At, 1, 1); PG8_STAGE(PG8_SB(1, 0), b3, voffB); PG8_STAGE(PG8_SB(1, 1), b3 + hstep, voffB); PG8_STAGE(PG8_SA(1, 0), a3, voffA);
;             PG8_WAIT_V(8); PG8_WAIT_L(0); PG8_BAR; PG8_MMA(1, 0, At, B0); PG8_MMA(1, 1, At, B1); PG8_BAR; PG8_SCHED;
	s_add_i32 s68, 0, 0x18000
	v_add_u32_e32 v3, s68, v157
	s_add_i32 s77, 0, 0x1c000
	ds_read_b128 v[132:135], v3
	ds_read_b128 v[140:143], v3 offset:1024
	ds_read_b128 v[160:163], v3 offset:2048
	ds_read_b128 v[164:167], v3 offset:3072
	v_add_u32_e32 v3, s77, v157
	ds_read_b128 v[168:171], v3
	ds_read_b128 v[172:175], v3 offset:1024
	ds_read_b128 v[176:179], v3 offset:2048
	ds_read_b128 v[180:183], v3 offset:3072
	s_add_u32 s28, s28, 0xb0000
	s_addc_u32 s29, s29, 0
	s_mov_b32 m0, s73
	v_lshl_add_u64 v[236:237], s[28:29], 0, v[146:147]
	ds_read_b128 v[184:187], v159 offset:32768
	ds_read_b128 v[188:191], v159 offset:33792
	ds_read_b128 v[192:195], v159 offset:34816
	ds_read_b128 v[196:199], v159 offset:35840
	ds_read_b128 v[214:217], v159 offset:36864
	ds_read_b128 v[218:221], v159 offset:37888
	ds_read_b128 v[222:225], v159 offset:38912
	ds_read_b128 v[226:229], v159 offset:39936
	global_load_lds_dwordx4 v[236:237], off
	v_lshl_add_u64 v[236:237], s[28:29], 0, v[148:149]
	s_mov_b32 m0, s74
	s_nop 0
	global_load_lds_dwordx4 v[236:237], off
	s_waitcnt vmcnt(8)
	s_waitcnt lgkmcnt(0)
	s_barrier
	s_waitcnt lgkmcnt(0)
	v_mfma_f32_16x16x32_bf16 v[100:103], v[132:135], v[184:187], v[100:103]
	v_mfma_f32_16x16x32_bf16 v[108:111], v[160:163], v[184:187], v[108:111]
	v_mfma_f32_16x16x32_bf16 v[120:123], v[132:135], v[192:195], v[120:123]
	v_mfma_f32_16x16x32_bf16 v[128:131], v[160:163], v[192:195], v[128:131]
	v_mfma_f32_16x16x32_bf16 v[96:99], v[132:135], v[214:217], v[96:99]
	v_mfma_f32_16x16x32_bf16 v[92:95], v[160:163], v[214:217], v[92:95]
	v_mfma_f32_16x16x32_bf16 v[80:83], v[132:135], v[222:225], v[80:83]
	v_mfma_f32_16x16x32_bf16 v[76:79], v[160:163], v[222:225], v[76:79]
	v_mfma_f32_16x16x32_bf16 v[100:103], v[140:143], v[188:191], v[100:103]
	v_mfma_f32_16x16x32_bf16 v[108:111], v[164:167], v[188:191], v[108:111]
	v_mfma_f32_16x16x32_bf16 v[120:123], v[140:143], v[196:199], v[120:123]
	v_mfma_f32_16x16x32_bf16 v[128:131], v[164:167], v[196:199], v[128:131]
	v_mfma_f32_16x16x32_bf16 v[96:99], v[140:143], v[218:221], v[96:99]
	v_mfma_f32_16x16x32_bf16 v[92:95], v[164:167], v[218:221], v[92:95]
	v_mfma_f32_16x16x32_bf16 v[80:83], v[140:143], v[226:229], v[80:83]
	v_mfma_f32_16x16x32_bf16 v[76:79], v[164:167], v[226:229], v[76:79]
	v_mfma_f32_16x16x32_bf16 v[116:119], v[168:171], v[184:187], v[116:119]
	v_mfma_f32_16x16x32_bf16 v[124:127], v[176:179], v[184:187], v[124:127]
	v_mfma_f32_16x16x32_bf16 v[112:115], v[168:171], v[192:195], v[112:115]
	v_mfma_f32_16x16x32_bf16 v[104:107], v[176:179], v[192:195], v[104:107]
	v_mfma_f32_16x16x32_bf16 v[88:91], v[168:171], v[214:217], v[88:91]
	v_mfma_f32_16x16x32_bf16 v[84:87], v[176:179], v[214:217], v[84:87]
	v_mfma_f32_16x16x32_bf16 v[72:75], v[168:171], v[222:225], v[72:75]
	v_mfma_f32_16x16x32_bf16 v[68:71], v[176:179], v[222:225], v[68:71]
	v_mfma_f32_16x16x32_bf16 v[116:119], v[172:175], v[188:191], v[116:119]
	v_mfma_f32_16x16x32_bf16 v[124:127], v[180:183], v[188:191], v[124:127]
	v_mfma_f32_16x16x32_bf16 v[112:115], v[172:175], v[196:199], v[112:115]
	v_mfma_f32_16x16x32_bf16 v[104:107], v[180:183], v[196:199], v[104:107]
	v_mfma_f32_16x16x32_bf16 v[88:91], v[172:175], v[218:221], v[88:91]
	v_mfma_f32_16x16x32_bf16 v[84:87], v[180:183], v[218:221], v[84:87]
	v_mfma_f32_16x16x32_bf16 v[72:75], v[172:175], v[226:229], v[72:75]
	v_mfma_f32_16x16x32_bf16 v[68:71], v[180:183], v[226:229], v[68:71]
	s_barrier
	s_add_i32 s28, s68, s70
	v_lshl_add_u64 v[200:201], v[200:201], 0, s[46:47]
	s_mov_b32 m0, s28
	ds_read_b128 v[184:187], v159 offset:49152
	ds_read_b128 v[188:191], v159 offset:50176
	ds_read_b128 v[192:195], v159 offset:51200
	ds_read_b128 v[196:199], v159 offset:52224
	ds_read_b128 v[214:217], v159 offset:53248
	ds_read_b128 v[218:221], v159 offset:54272
	ds_read_b128 v[222:225], v159 offset:55296
	ds_read_b128 v[226:229], v159 offset:56320
	global_load_lds_dwordx4 v[200:201], off
	s_add_i32 m0, s28, 0x2000
	s_add_u32 s26, s26, 0xb0080
	v_lshl_add_u64 v[200:201], v[230:231], 0, s[46:47]
	s_addc_u32 s27, s27, 0
	s_add_i32 s28, s77, s70
	global_load_lds_dwordx4 v[200:201], off
	v_lshl_add_u64 v[200:201], s[26:27], 0, v[146:147]
	s_mov_b32 m0, s28
	s_nop 0
	global_load_lds_dwordx4 v[200:201], off
	v_lshl_add_u64 v[200:201], s[26:27], 0, v[148:149]
	s_add_i32 m0, s28, 0x2000
	s_nop 0
	global_load_lds_dwordx4 v[200:201], off
	v_lshl_add_u64 v[200:201], v[232:233], 0, s[46:47]
	s_mov_b32 m0, s75
	s_nop 0
	global_load_lds_dwordx4 v[200:201], off
	v_lshl_add_u64 v[200:201], v[234:235], 0, s[46:47]
	s_mov_b32 m0, s76
	s_nop 0
	global_load_lds_dwordx4 v[200:201], off
	s_waitcnt vmcnt(8)
	s_waitcnt lgkmcnt(0)
	s_barrier
; #define PG8_MMA(ai, bj, At, Bt) do { __builtin_amdgcn_s_setprio(1); _Pragma("unroll") for (int m = 0; m < 4; ++m) _Pragma("unroll") for (int n = 0; n < 2; ++n) _Pragma("unroll") for (int k = 0; k < 2; ++k) \
;         acc[ai][bj][m][n] = __builtin_amdgcn_mfma_f32_16x16x32_bf16(Bt[n][k], At[m][k], acc[ai][bj][m][n], 0, 0, 0); __builtin_amdgcn_s_setprio(0); } while (0)
; #define PG8_WAIT_V(n) asm volatile("s_waitcnt vmcnt(" #n ")" ::: "memory")
; #define PG8_WAIT_L(n) asm volatile("s_waitcnt lgkmcnt(" #n ")" ::: "memory")
; #define PG8_BAR __builtin_amdgcn_s_barrier()
; #define PG8_SCHED __builtin_amdgcn_sched_barrier(0)
; template <class Epi>
; __device__ __forceinline__ void gemm_phase(LAS unsigned char* lds, const Gemm g, const int G, const int cidx, const Epi& E) {
;     ...
;             PG8_WAIT_V(8); PG8_WAIT_L(0); PG8_BAR; PG8_MMA(1, 0, At, B0); PG8_MMA(1, 1, At, B1); PG8_BAR; PG8_SCHED;
;         }
;         if constexpr (!Epi::AFTER_DRAIN) E(acc, cur, wr, wc, fr, fq);
;         if (!has_next) break;
; #pragma unroll
;         for (int a = 0; a < 2; ++a)
; #pragma unroll
;             for (int b = 0; b < 2; ++b)
; #pragma unroll
;                 for (int m = 0; m < 4; ++m)
; #pragma unroll
;                     for (int n = 0; n < 2; ++n) acc[a][b][m][n] = ZERO4;
;         cur = nxt; cA = nA; cB = nB; ++ui;
	s_waitcnt lgkmcnt(0)
	v_mfma_f32_16x16x32_bf16 v[64:67], v[132:135], v[184:187], v[64:67]
	v_mfma_f32_16x16x32_bf16 v[60:63], v[160:163], v[184:187], v[60:63]
	v_mfma_f32_16x16x32_bf16 v[48:51], v[132:135], v[192:195], v[48:51]
	v_mfma_f32_16x16x32_bf16 v[44:47], v[160:163], v[192:195], v[44:47]
	v_mfma_f32_16x16x32_bf16 v[32:35], v[132:135], v[214:217], v[32:35]
	v_mfma_f32_16x16x32_bf16 v[28:31], v[160:163], v[214:217], v[28:31]
	v_mfma_f32_16x16x32_bf16 v[16:19], v[132:135], v[222:225], v[16:19]
	v_mfma_f32_16x16x32_bf16 v[12:15], v[160:163], v[222:225], v[12:15]
	v_mfma_f32_16x16x32_bf16 v[64:67], v[140:143], v[188:191], v[64:67]
	v_mfma_f32_16x16x32_bf16 v[60:63], v[164:167], v[188:191], v[60:63]
	v_mfma_f32_16x16x32_bf16 v[48:51], v[140:143], v[196:199], v[48:51]
	v_mfma_f32_16x16x32_bf16 v[44:47], v[164:167], v[196:199], v[44:47]
	v_mfma_f32_16x16x32_bf16 v[32:35], v[140:143], v[218:221], v[32:35]
	v_mfma_f32_16x16x32_bf16 v[28:31], v[164:167], v[218:221], v[28:31]
	v_mfma_f32_16x16x32_bf16 v[16:19], v[140:143], v[226:229], v[16:19]
	v_mfma_f32_16x16x32_bf16 v[12:15], v[164:167], v[226:229], v[12:15]
	v_mfma_f32_16x16x32_bf16 v[56:59], v[168:171], v[184:187], v[56:59]
	v_mfma_f32_16x16x32_bf16 v[52:55], v[176:179], v[184:187], v[52:55]
	v_mfma_f32_16x16x32_bf16 v[40:43], v[168:171], v[192:195], v[40:43]
	v_mfma_f32_16x16x32_bf16 v[36:39], v[176:179], v[192:195], v[36:39]
	v_mfma_f32_16x16x32_bf16 v[24:27], v[168:171], v[214:217], v[24:27]
	v_mfma_f32_16x16x32_bf16 v[20:23], v[176:179], v[214:217], v[20:23]
	v_mfma_f32_16x16x32_bf16 v[8:11], v[168:171], v[222:225], v[8:11]
	v_mfma_f32_16x16x32_bf16 v[4:7], v[176:179], v[222:225], v[4:7]
	v_mfma_f32_16x16x32_bf16 v[56:59], v[172:175], v[188:191], v[56:59]
	v_mfma_f32_16x16x32_bf16 v[52:55], v[180:183], v[188:191], v[52:55]
	v_mfma_f32_16x16x32_bf16 v[40:43], v[172:175], v[196:199], v[40:43]
	v_mfma_f32_16x16x32_bf16 v[36:39], v[180:183], v[196:199], v[36:39]
	v_mfma_f32_16x16x32_bf16 v[24:27], v[172:175], v[218:221], v[24:27]
	v_mfma_f32_16x16x32_bf16 v[20:23], v[180:183], v[218:221], v[20:23]
	v_mfma_f32_16x16x32_bf16 v[8:11], v[172:175], v[226:229], v[8:11]
	v_mfma_f32_16x16x32_bf16 v[4:7], v[180:183], v[226:229], v[4:7]
	s_barrier
	s_add_i32 s45, s45, 2
	s_add_u32 s24, s24, 0x100
	s_addc_u32 s25, s25, 0
	s_cmp_gt_u32 s45, 41
	s_cbranch_scc0 .LBB0_450
	s_add_u32 s24, s43, 0xffffff00
	s_addc_u32 s25, s44, -1
	s_and_b64 vcc, exec, s[6:7]
	s_cbranch_vccnz .LBB0_453
	v_mov_b32_e32 v4, 0
	s_mov_b32 s14, s84
	s_mov_b32 s35, s88
	s_mov_b64 s[10:11], s[20:21]
	s_mov_b32 s79, s33
	v_mov_b32_e32 v5, v4
	v_mov_b32_e32 v6, v4
	v_mov_b32_e32 v7, v4
	v_mov_b32_e32 v8, v4
	v_mov_b32_e32 v9, v4
	v_mov_b32_e32 v10, v4
	v_mov_b32_e32 v11, v4
	v_mov_b32_e32 v20, v4
	v_mov_b32_e32 v21, v4
	v_mov_b32_e32 v22, v4
	v_mov_b32_e32 v23, v4
	v_mov_b32_e32 v24, v4
	v_mov_b32_e32 v25, v4
	v_mov_b32_e32 v26, v4
	v_mov_b32_e32 v27, v4
	v_mov_b32_e32 v36, v4
	v_mov_b32_e32 v37, v4
	v_mov_b32_e32 v38, v4
	v_mov_b32_e32 v39, v4
	v_mov_b32_e32 v40, v4
	v_mov_b32_e32 v41, v4
	v_mov_b32_e32 v42, v4
	v_mov_b32_e32 v43, v4
	v_mov_b32_e32 v52, v4
	v_mov_b32_e32 v53, v4
	v_mov_b32_e32 v54, v4
	v_mov_b32_e32 v55, v4
	v_mov_b32_e32 v56, v4
	v_mov_b32_e32 v57, v4
	v_mov_b32_e32 v58, v4
	v_mov_b32_e32 v59, v4
	v_mov_b32_e32 v12, v4
	v_mov_b32_e32 v13, v4
	v_mov_b32_e32 v14, v4
	v_mov_b32_e32 v15, v4
	v_mov_b32_e32 v16, v4
	v_mov_b32_e32 v17, v4
	v_mov_b32_e32 v18, v4
	v_mov_b32_e32 v19, v4
	v_mov_b32_e32 v28, v4
	v_mov_b32_e32 v29, v4
	v_mov_b32_e32 v30, v4
	v_mov_b32_e32 v31, v4
	v_mov_b32_e32 v32, v4
	v_mov_b32_e32 v33, v4
	v_mov_b32_e32 v34, v4
	v_mov_b32_e32 v35, v4
	v_mov_b32_e32 v44, v4
	v_mov_b32_e32 v45, v4
	v_mov_b32_e32 v46, v4
	v_mov_b32_e32 v47, v4
	v_mov_b32_e32 v48, v4
	v_mov_b32_e32 v49, v4
	v_mov_b32_e32 v50, v4
	v_mov_b32_e32 v51, v4
	v_mov_b32_e32 v60, v4
	v_mov_b32_e32 v61, v4
	v_mov_b32_e32 v62, v4
	v_mov_b32_e32 v63, v4
	v_mov_b32_e32 v64, v4
	v_mov_b32_e32 v65, v4
	v_mov_b32_e32 v66, v4
	v_mov_b32_e32 v67, v4
	v_mov_b32_e32 v68, v4
	v_mov_b32_e32 v69, v4
	v_mov_b32_e32 v70, v4
	v_mov_b32_e32 v71, v4
	v_mov_b32_e32 v72, v4
	v_mov_b32_e32 v73, v4
	v_mov_b32_e32 v74, v4
	v_mov_b32_e32 v75, v4
	v_mov_b32_e32 v84, v4
	v_mov_b32_e32 v85, v4
	v_mov_b32_e32 v86, v4
	v_mov_b32_e32 v87, v4
	v_mov_b32_e32 v88, v4
	v_mov_b32_e32 v89, v4
	v_mov_b32_e32 v90, v4
	v_mov_b32_e32 v91, v4
	v_mov_b32_e32 v104, v4
	v_mov_b32_e32 v105, v4
	v_mov_b32_e32 v106, v4
	v_mov_b32_e32 v107, v4
	v_mov_b32_e32 v112, v4
	v_mov_b32_e32 v113, v4
	v_mov_b32_e32 v114, v4
	v_mov_b32_e32 v115, v4
	v_mov_b32_e32 v124, v4
	v_mov_b32_e32 v125, v4
	v_mov_b32_e32 v126, v4
	v_mov_b32_e32 v127, v4
	v_mov_b32_e32 v116, v4
	v_mov_b32_e32 v117, v4
	v_mov_b32_e32 v118, v4
	v_mov_b32_e32 v119, v4
	v_mov_b32_e32 v76, v4
	v_mov_b32_e32 v77, v4
	v_mov_b32_e32 v78, v4
	v_mov_b32_e32 v79, v4
	v_mov_b32_e32 v80, v4
	v_mov_b32_e32 v81, v4
	v_mov_b32_e32 v82, v4
	v_mov_b32_e32 v83, v4
	v_mov_b32_e32 v92, v4
	v_mov_b32_e32 v93, v4
	v_mov_b32_e32 v94, v4
	v_mov_b32_e32 v95, v4
	v_mov_b32_e32 v96, v4
	v_mov_b32_e32 v97, v4
	v_mov_b32_e32 v98, v4
	v_mov_b32_e32 v99, v4
	v_mov_b32_e32 v128, v4
	v_mov_b32_e32 v129, v4
	v_mov_b32_e32 v130, v4
	v_mov_b32_e32 v131, v4
	v_mov_b32_e32 v120, v4
	v_mov_b32_e32 v121, v4
	v_mov_b32_e32 v122, v4
	v_mov_b32_e32 v123, v4
	v_mov_b32_e32 v108, v4
	v_mov_b32_e32 v109, v4
	v_mov_b32_e32 v110, v4
	v_mov_b32_e32 v111, v4
	v_mov_b32_e32 v100, v4
	v_mov_b32_e32 v101, v4
	v_mov_b32_e32 v102, v4
	v_mov_b32_e32 v103, v4
	s_mov_b32 s83, 0x18000
	s_mov_b32 s86, 0x3fb8aa3b
	s_andn2_b64 vcc, exec, s[4:5]
	s_cbranch_vccnz .LBB0_454
	s_branch .LBB0_455

; #define PG8_STAGE(bufoff, gbase, voff) do { _Pragma("unroll") for (int _i = 0; _i < 2; ++_i) \
;         __builtin_amdgcn_global_load_lds((const unsigned*)((const char*)(gbase) + (voff)[_i]), (LAS unsigned*)(lds + (bufoff) + ldsw + _i * 8192), 16, 0, 0); } while (0)
; #define PG8_LDA(dst, b, h) do { _Pragma("unroll") for (int m = 0; m < 4; ++m) _Pragma("unroll") for (int k = 0; k < 2; ++k) dst[m][k] = *(const LAS bf16x8*)(lds + PG8_SA(b, h) + aoff + m * 2048 + k * 1024); } while (0)
; #define PG8_LDB(dst, b, h) do { _Pragma("unroll") for (int n = 0; n < 2; ++n) _Pragma("unroll") for (int k = 0; k < 2; ++k) dst[n][k] = *(const LAS bf16x8*)(lds + PG8_SB(b, h) + boff + n * 2048 + k * 1024); } while (0)
; #define PG8_MMA(ai, bj, At, Bt) do { __builtin_amdgcn_s_setprio(1); _Pragma("unroll") for (int m = 0; m < 4; ++m) _Pragma("unroll") for (int n = 0; n < 2; ++n) _Pragma("unroll") for (int k = 0; k < 2; ++k) \
;         acc[ai][bj][m][n] = __builtin_amdgcn_mfma_f32_16x16x32_bf16(Bt[n][k], At[m][k], acc[ai][bj][m][n], 0, 0, 0); __builtin_amdgcn_s_setprio(0); } while (0)
; #define PG8_WAIT_V(n) asm volatile("s_waitcnt vmcnt(" #n ")" ::: "memory")
; template <class Epi>
; __device__ __forceinline__ void gemm_phase(LAS unsigned char* lds, const Gemm g, const int G, const int cidx, const Epi& E) {
;     ...
;         const bool has_next = S.next(ui + 1, nxt);
;         const char* nA = has_next ? PG8_ABASE(nxt) : cA; const char* nB = has_next ? (const char*)g.Bt + (size_t)nxt.pn * tstep : cB;
;         for (int t = 0; t < nt; t += 2) {
;             const bool last = (t == nt - 2);
;             const char* a1 = cA + (size_t)(t + 1) * kstep;
;             const char* a2 = last ? nA : cA + (size_t)(t + 2) * kstep; const char* b2 = last ? nB : cB + (size_t)(t + 2) * kstep;
;             const char* a3 = a2 + kstep; const char* b3 = b2 + kstep;
;             PG8_LDB(B0, 0, 0); PG8_LDB(B1, 0, 1); PG8_SCHED; PG8_LDA(At, 0, 0); PG8_STAGE(PG8_SA(1, 1), a1 + hstep, voffA);
;             PG8_WAIT_V(8); PG8_WAIT_L(0); PG8_BAR; PG8_MMA(0, 0, At, B0); PG8_MMA(0, 1, At, B1); PG8_BAR; PG8_SCHED;
;             PG8_LDA(At, 0, 1); PG8_STAGE(PG8_SB(0, 0), b2, voffB); PG8_STAGE(PG8_SB(0, 1), b2 + hstep, voffB); PG8_STAGE(PG8_SA(0, 0), a2, voffA);
;             PG8_WAIT_V(8); PG8_WAIT_L(0); PG8_BAR; PG8_MMA(1, 0, At, B0); PG8_MMA(1, 1, At, B1); PG8_BAR; PG8_SCHED;
.LBB0_600:
	s_ashr_i32 s11, s10, 31
	v_cmp_lt_i64_e32 vcc, s[12:13], v[244:245]
	s_lshl_b64 s[12:13], s[10:11], 19
	s_add_u32 s12, s74, s12
	s_addc_u32 s13, s75, s13
	s_and_b64 s[14:15], vcc, exec
	s_cselect_b32 s11, s13, s25
	s_cselect_b32 s19, s12, s24
	s_ashr_i32 s9, s8, 31
	s_lshl_b64 s[14:15], s[8:9], 19
	s_add_u32 s14, s88, s14
	s_addc_u32 s15, s94, s15
	s_and_b64 s[26:27], vcc, exec
	s_cselect_b32 s9, s15, s21
	s_cselect_b32 s33, s14, s20
	s_add_u32 s42, s20, 0x100
	s_addc_u32 s44, s21, 0
	s_add_u32 s20, s24, 0x40080
	s_addc_u32 s21, s25, 0
	s_mov_b32 s45, -2
	s_add_u32 s24, s20, 0xfffc0080
	s_addc_u32 s25, s21, -1
	s_add_i32 s43, 0, 0x10000
	s_cmp_eq_u32 s45, 12
	s_cselect_b32 s27, s11, s25
	s_cselect_b32 s26, s19, s24
	v_add_u32_e32 v132, s43, v145
	s_cselect_b32 s25, s9, s44
	s_cselect_b32 s24, s33, s42
	s_add_i32 s68, 0, 0x14000
	ds_read_b128 v[158:161], v132
	ds_read_b128 v[164:167], v132 offset:1024
	ds_read_b128 v[168:171], v132 offset:2048
	ds_read_b128 v[172:175], v132 offset:3072
	v_add_u32_e32 v132, s68, v145
	ds_read_b128 v[176:179], v132
	ds_read_b128 v[180:183], v132 offset:1024
	ds_read_b128 v[184:187], v132 offset:2048
	ds_read_b128 v[188:191], v132 offset:3072
	v_lshl_add_u64 v[132:133], s[20:21], 0, v[156:157]
	s_add_i32 m0, s97, 0xc000
	ds_read_b128 v[192:195], v163
	ds_read_b128 v[196:199], v163 offset:1024
	ds_read_b128 v[214:217], v163 offset:2048
	ds_read_b128 v[218:221], v163 offset:3072
	ds_read_b128 v[222:225], v163 offset:4096
	ds_read_b128 v[226:229], v163 offset:5120
	ds_read_b128 v[230:233], v163 offset:6144
	ds_read_b128 v[234:237], v163 offset:7168
	global_load_lds_dwordx4 v[132:133], off
	v_lshl_add_u64 v[132:133], s[20:21], 0, v[154:155]
	s_add_i32 m0, s97, 0xe000
	s_nop 0
	global_load_lds_dwordx4 v[132:133], off
	s_waitcnt vmcnt(8)
	s_waitcnt lgkmcnt(0)
	s_barrier
	s_waitcnt lgkmcnt(0)
	v_mfma_f32_16x16x32_bf16 v[128:131], v[158:161], v[192:195], 0
	v_mfma_f32_16x16x32_bf16 v[124:127], v[168:171], v[192:195], 0
	v_mfma_f32_16x16x32_bf16 v[120:123], v[158:161], v[214:217], 0
	v_mfma_f32_16x16x32_bf16 v[112:115], v[168:171], v[214:217], 0
	v_mfma_f32_16x16x32_bf16 v[104:107], v[158:161], v[222:225], 0
	v_mfma_f32_16x16x32_bf16 v[96:99], v[168:171], v[222:225], 0
	v_mfma_f32_16x16x32_bf16 v[88:91], v[158:161], v[230:233], 0
	v_mfma_f32_16x16x32_bf16 v[80:83], v[168:171], v[230:233], 0
	v_mfma_f32_16x16x32_bf16 v[128:131], v[164:167], v[196:199], v[128:131]
	v_mfma_f32_16x16x32_bf16 v[124:127], v[172:175], v[196:199], v[124:127]
	v_mfma_f32_16x16x32_bf16 v[120:123], v[164:167], v[218:221], v[120:123]
	v_mfma_f32_16x16x32_bf16 v[112:115], v[172:175], v[218:221], v[112:115]
	v_mfma_f32_16x16x32_bf16 v[104:107], v[164:167], v[226:229], v[104:107]
	v_mfma_f32_16x16x32_bf16 v[96:99], v[172:175], v[226:229], v[96:99]
	v_mfma_f32_16x16x32_bf16 v[88:91], v[164:167], v[234:237], v[88:91]
	v_mfma_f32_16x16x32_bf16 v[80:83], v[172:175], v[234:237], v[80:83]
	v_mfma_f32_16x16x32_bf16 v[116:119], v[176:179], v[192:195], 0
	v_mfma_f32_16x16x32_bf16 v[108:111], v[184:187], v[192:195], 0
	v_mfma_f32_16x16x32_bf16 v[100:103], v[176:179], v[214:217], 0
	v_mfma_f32_16x16x32_bf16 v[92:95], v[184:187], v[214:217], 0
	v_mfma_f32_16x16x32_bf16 v[84:87], v[176:179], v[222:225], 0
	v_mfma_f32_16x16x32_bf16 v[76:79], v[184:187], v[222:225], 0
	v_mfma_f32_16x16x32_bf16 v[72:75], v[176:179], v[230:233], 0
	v_mfma_f32_16x16x32_bf16 v[68:71], v[184:187], v[230:233], 0
	v_mfma_f32_16x16x32_bf16 v[116:119], v[180:183], v[196:199], v[116:119]
	v_mfma_f32_16x16x32_bf16 v[108:111], v[188:191], v[196:199], v[108:111]
	v_mfma_f32_16x16x32_bf16 v[100:103], v[180:183], v[218:221], v[100:103]
	v_mfma_f32_16x16x32_bf16 v[92:95], v[188:191], v[218:221], v[92:95]
	v_mfma_f32_16x16x32_bf16 v[84:87], v[180:183], v[226:229], v[84:87]
	v_mfma_f32_16x16x32_bf16 v[76:79], v[188:191], v[226:229], v[76:79]
	v_mfma_f32_16x16x32_bf16 v[72:75], v[180:183], v[234:237], v[72:75]
	v_mfma_f32_16x16x32_bf16 v[68:71], v[188:191], v[234:237], v[68:71]
	s_barrier
	s_add_i32 s43, s43, s95
	v_lshl_add_u64 v[132:133], s[24:25], 0, v[148:149]
	s_mov_b32 m0, s43
	ds_read_b128 v[192:195], v163 offset:16384
	ds_read_b128 v[196:199], v163 offset:17408
	ds_read_b128 v[214:217], v163 offset:18432
	ds_read_b128 v[218:221], v163 offset:19456
	ds_read_b128 v[222:225], v163 offset:20480
	ds_read_b128 v[226:229], v163 offset:21504
	ds_read_b128 v[230:233], v163 offset:22528
	ds_read_b128 v[234:237], v163 offset:23552
	global_load_lds_dwordx4 v[132:133], off
	s_add_i32 m0, s43, 0x2000
	s_add_u32 s86, s24, 0x40000
	v_lshl_add_u64 v[134:135], s[24:25], 0, v[0:1]
	s_addc_u32 s87, s25, 0
	s_add_i32 s43, s68, s95
	global_load_lds_dwordx4 v[134:135], off
	v_lshl_add_u64 v[140:141], s[86:87], 0, v[148:149]
	s_mov_b32 m0, s43
	v_lshl_add_u64 v[142:143], s[26:27], 0, v[146:147]
	global_load_lds_dwordx4 v[140:141], off
	v_lshl_add_u64 v[140:141], s[86:87], 0, v[0:1]
	s_add_i32 m0, s43, 0x2000
	s_nop 0
	global_load_lds_dwordx4 v[140:141], off
	v_lshl_add_u64 v[140:141], s[26:27], 0, v[150:151]
	s_mov_b32 m0, s97
	s_nop 0
	global_load_lds_dwordx4 v[140:141], off
	s_mov_b32 m0, s22
	s_nop 0
	global_load_lds_dwordx4 v[142:143], off
	s_waitcnt vmcnt(8)
	s_waitcnt lgkmcnt(0)
	s_barrier
; #define PG8_STAGE(bufoff, gbase, voff) do { _Pragma("unroll") for (int _i = 0; _i < 2; ++_i) \
;         __builtin_amdgcn_global_load_lds((const unsigned*)((const char*)(gbase) + (voff)[_i]), (LAS unsigned*)(lds + (bufoff) + ldsw + _i * 8192), 16, 0, 0); } while (0)
; #define PG8_LDA(dst, b, h) do { _Pragma("unroll") for (int m = 0; m < 4; ++m) _Pragma("unroll") for (int k = 0; k < 2; ++k) dst[m][k] = *(const LAS bf16x8*)(lds + PG8_SA(b, h) + aoff + m * 2048 + k * 1024); } while (0)
; #define PG8_LDB(dst, b, h) do { _Pragma("unroll") for (int n = 0; n < 2; ++n) _Pragma("unroll") for (int k = 0; k < 2; ++k) dst[n][k] = *(const LAS bf16x8*)(lds + PG8_SB(b, h) + boff + n * 2048 + k * 1024); } while (0)
; #define PG8_MMA(ai, bj, At, Bt) do { __builtin_amdgcn_s_setprio(1); _Pragma("unroll") for (int m = 0; m < 4; ++m) _Pragma("unroll") for (int n = 0; n < 2; ++n) _Pragma("unroll") for (int k = 0; k < 2; ++k) \
;         acc[ai][bj][m][n] = __builtin_amdgcn_mfma_f32_16x16x32_bf16(Bt[n][k], At[m][k], acc[ai][bj][m][n], 0, 0, 0); __builtin_amdgcn_s_setprio(0); } while (0)
; #define PG8_WAIT_V(n) asm volatile("s_waitcnt vmcnt(" #n ")" ::: "memory")
; #define PG8_WAIT_L(n) asm volatile("s_waitcnt lgkmcnt(" #n ")" ::: "memory")
; #define PG8_BAR __builtin_amdgcn_s_barrier()
; #define PG8_SCHED __builtin_amdgcn_sched_barrier(0)
; template <class Epi>
; __device__ __forceinline__ void gemm_phase(LAS unsigned char* lds, const Gemm g, const int G, const int cidx, const Epi& E) {
;     ...
;             PG8_WAIT_V(8); PG8_WAIT_L(0); PG8_BAR; PG8_MMA(1, 0, At, B0); PG8_MMA(1, 1, At, B1); PG8_BAR; PG8_SCHED;
;             PG8_LDB(B0, 1, 0); PG8_LDB(B1, 1, 1); PG8_SCHED; PG8_LDA(At, 1, 0); PG8_STAGE(PG8_SA(0, 1), a2 + hstep, voffA);
;             PG8_WAIT_V(8); PG8_WAIT_L(0); PG8_BAR; PG8_MMA(0, 0, At, B0); PG8_MMA(0, 1, At, B1); PG8_BAR; PG8_SCHED;
	s_waitcnt lgkmcnt(0)
	v_mfma_f32_16x16x32_bf16 v[64:67], v[158:161], v[192:195], 0
	v_mfma_f32_16x16x32_bf16 v[60:63], v[168:171], v[192:195], 0
	v_mfma_f32_16x16x32_bf16 v[56:59], v[158:161], v[214:217], 0
	v_mfma_f32_16x16x32_bf16 v[48:51], v[168:171], v[214:217], 0
	v_mfma_f32_16x16x32_bf16 v[40:43], v[158:161], v[222:225], 0
	v_mfma_f32_16x16x32_bf16 v[32:35], v[168:171], v[222:225], 0
	v_mfma_f32_16x16x32_bf16 v[24:27], v[158:161], v[230:233], 0
	v_mfma_f32_16x16x32_bf16 v[16:19], v[168:171], v[230:233], 0
	v_mfma_f32_16x16x32_bf16 v[64:67], v[164:167], v[196:199], v[64:67]
	v_mfma_f32_16x16x32_bf16 v[60:63], v[172:175], v[196:199], v[60:63]
	v_mfma_f32_16x16x32_bf16 v[56:59], v[164:167], v[218:221], v[56:59]
	v_mfma_f32_16x16x32_bf16 v[48:51], v[172:175], v[218:221], v[48:51]
	v_mfma_f32_16x16x32_bf16 v[40:43], v[164:167], v[226:229], v[40:43]
	v_mfma_f32_16x16x32_bf16 v[32:35], v[172:175], v[226:229], v[32:35]
	v_mfma_f32_16x16x32_bf16 v[24:27], v[164:167], v[234:237], v[24:27]
	v_mfma_f32_16x16x32_bf16 v[16:19], v[172:175], v[234:237], v[16:19]
	v_mfma_f32_16x16x32_bf16 v[52:55], v[176:179], v[192:195], 0
	v_mfma_f32_16x16x32_bf16 v[44:47], v[184:187], v[192:195], 0
	v_mfma_f32_16x16x32_bf16 v[36:39], v[176:179], v[214:217], 0
	v_mfma_f32_16x16x32_bf16 v[28:31], v[184:187], v[214:217], 0
	v_mfma_f32_16x16x32_bf16 v[20:23], v[176:179], v[222:225], 0
	v_mfma_f32_16x16x32_bf16 v[12:15], v[184:187], v[222:225], 0
	v_mfma_f32_16x16x32_bf16 v[8:11], v[176:179], v[230:233], 0
	v_mfma_f32_16x16x32_bf16 v[4:7], v[184:187], v[230:233], 0
	v_mfma_f32_16x16x32_bf16 v[52:55], v[180:183], v[196:199], v[52:55]
	v_mfma_f32_16x16x32_bf16 v[44:47], v[188:191], v[196:199], v[44:47]
	v_mfma_f32_16x16x32_bf16 v[36:39], v[180:183], v[218:221], v[36:39]
	v_mfma_f32_16x16x32_bf16 v[28:31], v[188:191], v[218:221], v[28:31]
	v_mfma_f32_16x16x32_bf16 v[20:23], v[180:183], v[226:229], v[20:23]
	v_mfma_f32_16x16x32_bf16 v[12:15], v[188:191], v[226:229], v[12:15]
	v_mfma_f32_16x16x32_bf16 v[8:11], v[180:183], v[234:237], v[8:11]
	v_mfma_f32_16x16x32_bf16 v[4:7], v[188:191], v[234:237], v[4:7]
	s_barrier
	s_add_i32 s43, 0, 0x18000
	s_add_i32 s68, 0, 0x1c000
	v_add_u32_e32 v172, s43, v145
	v_add_u32_e32 v188, s68, v145
	ds_read_b128 v[158:161], v172
	ds_read_b128 v[164:167], v172 offset:1024
	ds_read_b128 v[168:171], v172 offset:2048
	ds_read_b128 v[172:175], v172 offset:3072
	ds_read_b128 v[176:179], v188
	ds_read_b128 v[180:183], v188 offset:1024
	ds_read_b128 v[184:187], v188 offset:2048
	ds_read_b128 v[188:191], v188 offset:3072
	s_add_u32 s26, s26, 0x40000
	s_addc_u32 s27, s27, 0
	s_mov_b32 m0, s16
	v_lshl_add_u64 v[200:201], s[26:27], 0, v[150:151]
	ds_read_b128 v[192:195], v163 offset:32768
	ds_read_b128 v[196:199], v163 offset:33792
	ds_read_b128 v[214:217], v163 offset:34816
	ds_read_b128 v[218:221], v163 offset:35840
	ds_read_b128 v[222:225], v163 offset:36864
	ds_read_b128 v[226:229], v163 offset:37888
	ds_read_b128 v[230:233], v163 offset:38912
	ds_read_b128 v[234:237], v163 offset:39936
	global_load_lds_dwordx4 v[200:201], off
	v_lshl_add_u64 v[200:201], s[26:27], 0, v[146:147]
	s_mov_b32 m0, s17
	s_nop 0
	global_load_lds_dwordx4 v[200:201], off
	s_waitcnt vmcnt(8)
	s_waitcnt lgkmcnt(0)
	s_barrier
	s_waitcnt lgkmcnt(0)
	v_mfma_f32_16x16x32_bf16 v[128:131], v[158:161], v[192:195], v[128:131]
	v_mfma_f32_16x16x32_bf16 v[124:127], v[168:171], v[192:195], v[124:127]
	v_mfma_f32_16x16x32_bf16 v[120:123], v[158:161], v[214:217], v[120:123]
	v_mfma_f32_16x16x32_bf16 v[112:115], v[168:171], v[214:217], v[112:115]
	v_mfma_f32_16x16x32_bf16 v[104:107], v[158:161], v[222:225], v[104:107]
	v_mfma_f32_16x16x32_bf16 v[96:99], v[168:171], v[222:225], v[96:99]
	v_mfma_f32_16x16x32_bf16 v[88:91], v[158:161], v[230:233], v[88:91]
	v_mfma_f32_16x16x32_bf16 v[80:83], v[168:171], v[230:233], v[80:83]
	v_mfma_f32_16x16x32_bf16 v[128:131], v[164:167], v[196:199], v[128:131]
	v_mfma_f32_16x16x32_bf16 v[124:127], v[172:175], v[196:199], v[124:127]
	v_mfma_f32_16x16x32_bf16 v[120:123], v[164:167], v[218:221], v[120:123]
	v_mfma_f32_16x16x32_bf16 v[112:115], v[172:175], v[218:221], v[112:115]
	v_mfma_f32_16x16x32_bf16 v[104:107], v[164:167], v[226:229], v[104:107]
	v_mfma_f32_16x16x32_bf16 v[96:99], v[172:175], v[226:229], v[96:99]
	v_mfma_f32_16x16x32_bf16 v[88:91], v[164:167], v[234:237], v[88:91]
	v_mfma_f32_16x16x32_bf16 v[80:83], v[172:175], v[234:237], v[80:83]
	v_mfma_f32_16x16x32_bf16 v[116:119], v[176:179], v[192:195], v[116:119]
	v_mfma_f32_16x16x32_bf16 v[108:111], v[184:187], v[192:195], v[108:111]
	v_mfma_f32_16x16x32_bf16 v[100:103], v[176:179], v[214:217], v[100:103]
	v_mfma_f32_16x16x32_bf16 v[92:95], v[184:187], v[214:217], v[92:95]
	v_mfma_f32_16x16x32_bf16 v[84:87], v[176:179], v[222:225], v[84:87]
	v_mfma_f32_16x16x32_bf16 v[76:79], v[184:187], v[222:225], v[76:79]
	v_mfma_f32_16x16x32_bf16 v[72:75], v[176:179], v[230:233], v[72:75]
	v_mfma_f32_16x16x32_bf16 v[68:71], v[184:187], v[230:233], v[68:71]
	v_mfma_f32_16x16x32_bf16 v[116:119], v[180:183], v[196:199], v[116:119]
	v_mfma_f32_16x16x32_bf16 v[108:111], v[188:191], v[196:199], v[108:111]
	v_mfma_f32_16x16x32_bf16 v[100:103], v[180:183], v[218:221], v[100:103]
	v_mfma_f32_16x16x32_bf16 v[92:95], v[188:191], v[218:221], v[92:95]
	v_mfma_f32_16x16x32_bf16 v[84:87], v[180:183], v[226:229], v[84:87]
	v_mfma_f32_16x16x32_bf16 v[76:79], v[188:191], v[226:229], v[76:79]
	v_mfma_f32_16x16x32_bf16 v[72:75], v[180:183], v[234:237], v[72:75]
	v_mfma_f32_16x16x32_bf16 v[68:71], v[188:191], v[234:237], v[68:71]
	s_barrier
; #define PG8_STAGE(bufoff, gbase, voff) do { _Pragma("unroll") for (int _i = 0; _i < 2; ++_i) \
;         __builtin_amdgcn_global_load_lds((const unsigned*)((const char*)(gbase) + (voff)[_i]), (LAS unsigned*)(lds + (bufoff) + ldsw + _i * 8192), 16, 0, 0); } while (0)
; #define PG8_LDA(dst, b, h) do { _Pragma("unroll") for (int m = 0; m < 4; ++m) _Pragma("unroll") for (int k = 0; k < 2; ++k) dst[m][k] = *(const LAS bf16x8*)(lds + PG8_SA(b, h) + aoff + m * 2048 + k * 1024); } while (0)
; #define PG8_LDB(dst, b, h) do { _Pragma("unroll") for (int n = 0; n < 2; ++n) _Pragma("unroll") for (int k = 0; k < 2; ++k) dst[n][k] = *(const LAS bf16x8*)(lds + PG8_SB(b, h) + boff + n * 2048 + k * 1024); } while (0)
; #define PG8_WAIT_V(n) asm volatile("s_waitcnt vmcnt(" #n ")" ::: "memory")
; #define PG8_WAIT_L(n) asm volatile("s_waitcnt lgkmcnt(" #n ")" ::: "memory")
; template <class Epi>
; __device__ __forceinline__ void gemm_phase(LAS unsigned char* lds, const Gemm g, const int G, const int cidx, const Epi& E) {
;     ...
;         for (int t = 0; t < nt; t += 2) {
;             const bool last = (t == nt - 2);
;             const char* a1 = cA + (size_t)(t + 1) * kstep;
;             const char* a2 = last ? nA : cA + (size_t)(t + 2) * kstep; const char* b2 = last ? nB : cB + (size_t)(t + 2) * kstep;
;             const char* a3 = a2 + kstep; const char* b3 = b2 + kstep;
;             PG8_LDB(B0, 0, 0); PG8_LDB(B1, 0, 1); PG8_SCHED; PG8_LDA(At, 0, 0); PG8_STAGE(PG8_SA(1, 1), a1 + hstep, voffA);
;             PG8_WAIT_V(8); PG8_WAIT_L(0); PG8_BAR; PG8_MMA(0, 0, At, B0); PG8_MMA(0, 1, At, B1); PG8_BAR; PG8_SCHED;
;             PG8_LDA(At, 0, 1); PG8_STAGE(PG8_SB(0, 0), b2, voffB); PG8_STAGE(PG8_SB(0, 1), b2 + hstep, voffB); PG8_STAGE(PG8_SA(0, 0), a2, voffA);
;             PG8_WAIT_V(8); PG8_WAIT_L(0); PG8_BAR; PG8_MMA(1, 0, At, B0); PG8_MMA(1, 1, At, B1); PG8_BAR; PG8_SCHED;
;             PG8_LDB(B0, 1, 0); PG8_LDB(B1, 1, 1); PG8_SCHED; PG8_LDA(At, 1, 0); PG8_STAGE(PG8_SA(0, 1), a2 + hstep, voffA);
;             PG8_WAIT_V(8); PG8_WAIT_L(0); PG8_BAR; PG8_MMA(0, 0, At, B0); PG8_MMA(0, 1, At, B1); PG8_BAR; PG8_SCHED;
;             PG8_LDA(At, 1, 1); PG8_STAGE(PG8_SB(1, 0), b3, voffB); PG8_STAGE(PG8_SB(1, 1), b3 + hstep, voffB); PG8_STAGE(PG8_SA(1, 0), a3, voffA);
;             PG8_WAIT_V(8); PG8_WAIT_L(0); PG8_BAR; PG8_MMA(1, 0, At, B0); PG8_MMA(1, 1, At, B1); PG8_BAR; PG8_SCHED;
	s_add_i32 s26, s43, s95
	v_lshl_add_u64 v[132:133], v[132:133], 0, s[46:47]
	s_mov_b32 m0, s26
	ds_read_b128 v[192:195], v163 offset:49152
	ds_read_b128 v[196:199], v163 offset:50176
	ds_read_b128 v[214:217], v163 offset:51200
	ds_read_b128 v[218:221], v163 offset:52224
	ds_read_b128 v[222:225], v163 offset:53248
	ds_read_b128 v[226:229], v163 offset:54272
	ds_read_b128 v[230:233], v163 offset:55296
	ds_read_b128 v[234:237], v163 offset:56320
	global_load_lds_dwordx4 v[132:133], off
	s_add_i32 m0, s26, 0x2000
	s_add_u32 s24, s24, 0x40080
	v_lshl_add_u64 v[132:133], v[134:135], 0, s[46:47]
	s_addc_u32 s25, s25, 0
	s_add_i32 s26, s68, s95
	global_load_lds_dwordx4 v[132:133], off
	v_lshl_add_u64 v[132:133], s[24:25], 0, v[148:149]
	s_mov_b32 m0, s26
	s_nop 0
	global_load_lds_dwordx4 v[132:133], off
	v_lshl_add_u64 v[132:133], s[24:25], 0, v[0:1]
	s_add_i32 m0, s26, 0x2000
	s_nop 0
	global_load_lds_dwordx4 v[132:133], off
	v_lshl_add_u64 v[132:133], v[140:141], 0, s[46:47]
	s_mov_b32 m0, s84
	s_nop 0
	global_load_lds_dwordx4 v[132:133], off
	v_lshl_add_u64 v[132:133], v[142:143], 0, s[46:47]
	s_mov_b32 m0, s76
	s_nop 0
	global_load_lds_dwordx4 v[132:133], off
	s_waitcnt vmcnt(8)
	s_waitcnt lgkmcnt(0)
	s_barrier
	s_waitcnt lgkmcnt(0)
	v_mfma_f32_16x16x32_bf16 v[64:67], v[158:161], v[192:195], v[64:67]
	v_mfma_f32_16x16x32_bf16 v[60:63], v[168:171], v[192:195], v[60:63]
	v_mfma_f32_16x16x32_bf16 v[56:59], v[158:161], v[214:217], v[56:59]
	v_mfma_f32_16x16x32_bf16 v[48:51], v[168:171], v[214:217], v[48:51]
	v_mfma_f32_16x16x32_bf16 v[40:43], v[158:161], v[222:225], v[40:43]
	v_mfma_f32_16x16x32_bf16 v[32:35], v[168:171], v[222:225], v[32:35]
	v_mfma_f32_16x16x32_bf16 v[24:27], v[158:161], v[230:233], v[24:27]
	v_mfma_f32_16x16x32_bf16 v[16:19], v[168:171], v[230:233], v[16:19]
	v_mfma_f32_16x16x32_bf16 v[64:67], v[164:167], v[196:199], v[64:67]
	v_mfma_f32_16x16x32_bf16 v[60:63], v[172:175], v[196:199], v[60:63]
	v_mfma_f32_16x16x32_bf16 v[56:59], v[164:167], v[218:221], v[56:59]
	v_mfma_f32_16x16x32_bf16 v[48:51], v[172:175], v[218:221], v[48:51]
	v_mfma_f32_16x16x32_bf16 v[40:43], v[164:167], v[226:229], v[40:43]
	v_mfma_f32_16x16x32_bf16 v[32:35], v[172:175], v[226:229], v[32:35]
	v_mfma_f32_16x16x32_bf16 v[24:27], v[164:167], v[234:237], v[24:27]
	v_mfma_f32_16x16x32_bf16 v[16:19], v[172:175], v[234:237], v[16:19]
	v_mfma_f32_16x16x32_bf16 v[52:55], v[176:179], v[192:195], v[52:55]
	v_mfma_f32_16x16x32_bf16 v[44:47], v[184:187], v[192:195], v[44:47]
	v_mfma_f32_16x16x32_bf16 v[36:39], v[176:179], v[214:217], v[36:39]
	v_mfma_f32_16x16x32_bf16 v[28:31], v[184:187], v[214:217], v[28:31]
	v_mfma_f32_16x16x32_bf16 v[20:23], v[176:179], v[222:225], v[20:23]
	v_mfma_f32_16x16x32_bf16 v[12:15], v[184:187], v[222:225], v[12:15]
	v_mfma_f32_16x16x32_bf16 v[8:11], v[176:179], v[230:233], v[8:11]
	v_mfma_f32_16x16x32_bf16 v[4:7], v[184:187], v[230:233], v[4:7]
	v_mfma_f32_16x16x32_bf16 v[52:55], v[180:183], v[196:199], v[52:55]
	v_mfma_f32_16x16x32_bf16 v[44:47], v[188:191], v[196:199], v[44:47]
	v_mfma_f32_16x16x32_bf16 v[36:39], v[180:183], v[218:221], v[36:39]
	v_mfma_f32_16x16x32_bf16 v[28:31], v[188:191], v[218:221], v[28:31]
	v_mfma_f32_16x16x32_bf16 v[20:23], v[180:183], v[226:229], v[20:23]
	v_mfma_f32_16x16x32_bf16 v[12:15], v[188:191], v[226:229], v[12:15]
	v_mfma_f32_16x16x32_bf16 v[8:11], v[180:183], v[234:237], v[8:11]
	v_mfma_f32_16x16x32_bf16 v[4:7], v[188:191], v[234:237], v[4:7]
	s_barrier
	s_add_i32 s45, s45, 2
	s_add_u32 s42, s42, 0x100
	s_addc_u32 s44, s44, 0
	s_add_u32 s20, s20, 0x100
	s_addc_u32 s21, s21, 0
.LBB0_601:
	s_add_u32 s24, s20, 0xfffc0080
	s_addc_u32 s25, s21, -1
	s_add_i32 s43, 0, 0x10000
	s_cmp_eq_u32 s45, 12
	s_cselect_b32 s27, s11, s25
	s_cselect_b32 s26, s19, s24
	v_add_u32_e32 v132, s43, v145
	s_cselect_b32 s25, s9, s44
	s_cselect_b32 s24, s33, s42
	s_add_i32 s68, 0, 0x14000
	ds_read_b128 v[158:161], v132
	ds_read_b128 v[164:167], v132 offset:1024
	ds_read_b128 v[168:171], v132 offset:2048
	ds_read_b128 v[172:175], v132 offset:3072
	v_add_u32_e32 v132, s68, v145
	ds_read_b128 v[176:179], v132
	ds_read_b128 v[180:183], v132 offset:1024
	ds_read_b128 v[184:187], v132 offset:2048
	ds_read_b128 v[188:191], v132 offset:3072
	v_lshl_add_u64 v[132:133], s[20:21], 0, v[156:157]
	s_add_i32 m0, s97, 0xc000
	ds_read_b128 v[192:195], v163
	ds_read_b128 v[196:199], v163 offset:1024
	ds_read_b128 v[214:217], v163 offset:2048
	ds_read_b128 v[218:221], v163 offset:3072
	ds_read_b128 v[222:225], v163 offset:4096
	ds_read_b128 v[226:229], v163 offset:5120
	ds_read_b128 v[230:233], v163 offset:6144
	ds_read_b128 v[234:237], v163 offset:7168
	global_load_lds_dwordx4 v[132:133], off
	v_lshl_add_u64 v[132:133], s[20:21], 0, v[154:155]
	s_add_i32 m0, s97, 0xe000
	s_nop 0
	global_load_lds_dwordx4 v[132:133], off
	s_waitcnt vmcnt(8)
	s_waitcnt lgkmcnt(0)
	s_barrier
; #define PG8_STAGE(bufoff, gbase, voff) do { _Pragma("unroll") for (int _i = 0; _i < 2; ++_i) \
;         __builtin_amdgcn_global_load_lds((const unsigned*)((const char*)(gbase) + (voff)[_i]), (LAS unsigned*)(lds + (bufoff) + ldsw + _i * 8192), 16, 0, 0); } while (0)
; #define PG8_LDA(dst, b, h) do { _Pragma("unroll") for (int m = 0; m < 4; ++m) _Pragma("unroll") for (int k = 0; k < 2; ++k) dst[m][k] = *(const LAS bf16x8*)(lds + PG8_SA(b, h) + aoff + m * 2048 + k * 1024); } while (0)
; #define PG8_LDB(dst, b, h) do { _Pragma("unroll") for (int n = 0; n < 2; ++n) _Pragma("unroll") for (int k = 0; k < 2; ++k) dst[n][k] = *(const LAS bf16x8*)(lds + PG8_SB(b, h) + boff + n * 2048 + k * 1024); } while (0)
; #define PG8_MMA(ai, bj, At, Bt) do { __builtin_amdgcn_s_setprio(1); _Pragma("unroll") for (int m = 0; m < 4; ++m) _Pragma("unroll") for (int n = 0; n < 2; ++n) _Pragma("unroll") for (int k = 0; k < 2; ++k) \
;         acc[ai][bj][m][n] = __builtin_amdgcn_mfma_f32_16x16x32_bf16(Bt[n][k], At[m][k], acc[ai][bj][m][n], 0, 0, 0); __builtin_amdgcn_s_setprio(0); } while (0)
; #define PG8_WAIT_V(n) asm volatile("s_waitcnt vmcnt(" #n ")" ::: "memory")
; #define PG8_WAIT_L(n) asm volatile("s_waitcnt lgkmcnt(" #n ")" ::: "memory")
; #define PG8_BAR __builtin_amdgcn_s_barrier()
; #define PG8_SCHED __builtin_amdgcn_sched_barrier(0)
; template <class Epi>
; __device__ __forceinline__ void gemm_phase(LAS unsigned char* lds, const Gemm g, const int G, const int cidx, const Epi& E) {
;     ...
;             PG8_WAIT_V(8); PG8_WAIT_L(0); PG8_BAR; PG8_MMA(0, 0, At, B0); PG8_MMA(0, 1, At, B1); PG8_BAR; PG8_SCHED;
;             PG8_LDA(At, 0, 1); PG8_STAGE(PG8_SB(0, 0), b2, voffB); PG8_STAGE(PG8_SB(0, 1), b2 + hstep, voffB); PG8_STAGE(PG8_SA(0, 0), a2, voffA);
;             PG8_WAIT_V(8); PG8_WAIT_L(0); PG8_BAR; PG8_MMA(1, 0, At, B0); PG8_MMA(1, 1, At, B1); PG8_BAR; PG8_SCHED;
;             PG8_LDB(B0, 1, 0); PG8_LDB(B1, 1, 1); PG8_SCHED; PG8_LDA(At, 1, 0); PG8_STAGE(PG8_SA(0, 1), a2 + hstep, voffA);
;             PG8_WAIT_V(8); PG8_WAIT_L(0); PG8_BAR; PG8_MMA(0, 0, At, B0); PG8_MMA(0, 1, At, B1); PG8_BAR; PG8_SCHED;
;             PG8_LDA(At, 1, 1); PG8_STAGE(PG8_SB(1, 0), b3, voffB); PG8_STAGE(PG8_SB(1, 1), b3 + hstep, voffB); PG8_STAGE(PG8_SA(1, 0), a3, voffA);
	s_waitcnt lgkmcnt(0)
	v_mfma_f32_16x16x32_bf16 v[128:131], v[158:161], v[192:195], v[128:131]
	v_mfma_f32_16x16x32_bf16 v[124:127], v[168:171], v[192:195], v[124:127]
	v_mfma_f32_16x16x32_bf16 v[120:123], v[158:161], v[214:217], v[120:123]
	v_mfma_f32_16x16x32_bf16 v[112:115], v[168:171], v[214:217], v[112:115]
	v_mfma_f32_16x16x32_bf16 v[104:107], v[158:161], v[222:225], v[104:107]
	v_mfma_f32_16x16x32_bf16 v[96:99], v[168:171], v[222:225], v[96:99]
	v_mfma_f32_16x16x32_bf16 v[88:91], v[158:161], v[230:233], v[88:91]
	v_mfma_f32_16x16x32_bf16 v[80:83], v[168:171], v[230:233], v[80:83]
	v_mfma_f32_16x16x32_bf16 v[128:131], v[164:167], v[196:199], v[128:131]
	v_mfma_f32_16x16x32_bf16 v[124:127], v[172:175], v[196:199], v[124:127]
	v_mfma_f32_16x16x32_bf16 v[120:123], v[164:167], v[218:221], v[120:123]
	v_mfma_f32_16x16x32_bf16 v[112:115], v[172:175], v[218:221], v[112:115]
	v_mfma_f32_16x16x32_bf16 v[104:107], v[164:167], v[226:229], v[104:107]
	v_mfma_f32_16x16x32_bf16 v[96:99], v[172:175], v[226:229], v[96:99]
	v_mfma_f32_16x16x32_bf16 v[88:91], v[164:167], v[234:237], v[88:91]
	v_mfma_f32_16x16x32_bf16 v[80:83], v[172:175], v[234:237], v[80:83]
	v_mfma_f32_16x16x32_bf16 v[116:119], v[176:179], v[192:195], v[116:119]
	v_mfma_f32_16x16x32_bf16 v[108:111], v[184:187], v[192:195], v[108:111]
	v_mfma_f32_16x16x32_bf16 v[100:103], v[176:179], v[214:217], v[100:103]
	v_mfma_f32_16x16x32_bf16 v[92:95], v[184:187], v[214:217], v[92:95]
	v_mfma_f32_16x16x32_bf16 v[84:87], v[176:179], v[222:225], v[84:87]
	v_mfma_f32_16x16x32_bf16 v[76:79], v[184:187], v[222:225], v[76:79]
	v_mfma_f32_16x16x32_bf16 v[72:75], v[176:179], v[230:233], v[72:75]
	v_mfma_f32_16x16x32_bf16 v[68:71], v[184:187], v[230:233], v[68:71]
	v_mfma_f32_16x16x32_bf16 v[116:119], v[180:183], v[196:199], v[116:119]
	v_mfma_f32_16x16x32_bf16 v[108:111], v[188:191], v[196:199], v[108:111]
	v_mfma_f32_16x16x32_bf16 v[100:103], v[180:183], v[218:221], v[100:103]
	v_mfma_f32_16x16x32_bf16 v[92:95], v[188:191], v[218:221], v[92:95]
	v_mfma_f32_16x16x32_bf16 v[84:87], v[180:183], v[226:229], v[84:87]
	v_mfma_f32_16x16x32_bf16 v[76:79], v[188:191], v[226:229], v[76:79]
	v_mfma_f32_16x16x32_bf16 v[72:75], v[180:183], v[234:237], v[72:75]
	v_mfma_f32_16x16x32_bf16 v[68:71], v[188:191], v[234:237], v[68:71]
	s_barrier
	s_add_i32 s43, s43, s95
	v_lshl_add_u64 v[132:133], s[24:25], 0, v[148:149]
	s_mov_b32 m0, s43
	ds_read_b128 v[192:195], v163 offset:16384
	ds_read_b128 v[196:199], v163 offset:17408
	ds_read_b128 v[214:217], v163 offset:18432
	ds_read_b128 v[218:221], v163 offset:19456
	ds_read_b128 v[222:225], v163 offset:20480
	ds_read_b128 v[226:229], v163 offset:21504
	ds_read_b128 v[230:233], v163 offset:22528
	ds_read_b128 v[234:237], v163 offset:23552
	global_load_lds_dwordx4 v[132:133], off
	s_add_i32 m0, s43, 0x2000
	s_add_u32 s86, s24, 0x40000
	v_lshl_add_u64 v[134:135], s[24:25], 0, v[0:1]
	s_addc_u32 s87, s25, 0
	s_add_i32 s43, s68, s95
	global_load_lds_dwordx4 v[134:135], off
	v_lshl_add_u64 v[140:141], s[86:87], 0, v[148:149]
	s_mov_b32 m0, s43
	v_lshl_add_u64 v[142:143], s[26:27], 0, v[146:147]
	global_load_lds_dwordx4 v[140:141], off
	v_lshl_add_u64 v[140:141], s[86:87], 0, v[0:1]
	s_add_i32 m0, s43, 0x2000
	s_nop 0
	global_load_lds_dwordx4 v[140:141], off
	v_lshl_add_u64 v[140:141], s[26:27], 0, v[150:151]
	s_mov_b32 m0, s97
	s_nop 0
	global_load_lds_dwordx4 v[140:141], off
	s_mov_b32 m0, s22
	s_nop 0
	global_load_lds_dwordx4 v[142:143], off
	s_waitcnt vmcnt(8)
	s_waitcnt lgkmcnt(0)
	s_barrier
	s_waitcnt lgkmcnt(0)
	v_mfma_f32_16x16x32_bf16 v[64:67], v[158:161], v[192:195], v[64:67]
	v_mfma_f32_16x16x32_bf16 v[60:63], v[168:171], v[192:195], v[60:63]
	v_mfma_f32_16x16x32_bf16 v[56:59], v[158:161], v[214:217], v[56:59]
	v_mfma_f32_16x16x32_bf16 v[48:51], v[168:171], v[214:217], v[48:51]
	v_mfma_f32_16x16x32_bf16 v[40:43], v[158:161], v[222:225], v[40:43]
	v_mfma_f32_16x16x32_bf16 v[32:35], v[168:171], v[222:225], v[32:35]
	v_mfma_f32_16x16x32_bf16 v[24:27], v[158:161], v[230:233], v[24:27]
	v_mfma_f32_16x16x32_bf16 v[16:19], v[168:171], v[230:233], v[16:19]
	v_mfma_f32_16x16x32_bf16 v[64:67], v[164:167], v[196:199], v[64:67]
	v_mfma_f32_16x16x32_bf16 v[60:63], v[172:175], v[196:199], v[60:63]
	v_mfma_f32_16x16x32_bf16 v[56:59], v[164:167], v[218:221], v[56:59]
	v_mfma_f32_16x16x32_bf16 v[48:51], v[172:175], v[218:221], v[48:51]
	v_mfma_f32_16x16x32_bf16 v[40:43], v[164:167], v[226:229], v[40:43]
	v_mfma_f32_16x16x32_bf16 v[32:35], v[172:175], v[226:229], v[32:35]
	v_mfma_f32_16x16x32_bf16 v[24:27], v[164:167], v[234:237], v[24:27]
	v_mfma_f32_16x16x32_bf16 v[16:19], v[172:175], v[234:237], v[16:19]
	v_mfma_f32_16x16x32_bf16 v[52:55], v[176:179], v[192:195], v[52:55]
	v_mfma_f32_16x16x32_bf16 v[44:47], v[184:187], v[192:195], v[44:47]
	v_mfma_f32_16x16x32_bf16 v[36:39], v[176:179], v[214:217], v[36:39]
	v_mfma_f32_16x16x32_bf16 v[28:31], v[184:187], v[214:217], v[28:31]
	v_mfma_f32_16x16x32_bf16 v[20:23], v[176:179], v[222:225], v[20:23]
	v_mfma_f32_16x16x32_bf16 v[12:15], v[184:187], v[222:225], v[12:15]
	v_mfma_f32_16x16x32_bf16 v[8:11], v[176:179], v[230:233], v[8:11]
	v_mfma_f32_16x16x32_bf16 v[4:7], v[184:187], v[230:233], v[4:7]
	v_mfma_f32_16x16x32_bf16 v[52:55], v[180:183], v[196:199], v[52:55]
	v_mfma_f32_16x16x32_bf16 v[44:47], v[188:191], v[196:199], v[44:47]
	v_mfma_f32_16x16x32_bf16 v[36:39], v[180:183], v[218:221], v[36:39]
	v_mfma_f32_16x16x32_bf16 v[28:31], v[188:191], v[218:221], v[28:31]
	v_mfma_f32_16x16x32_bf16 v[20:23], v[180:183], v[226:229], v[20:23]
	v_mfma_f32_16x16x32_bf16 v[12:15], v[188:191], v[226:229], v[12:15]
	v_mfma_f32_16x16x32_bf16 v[8:11], v[180:183], v[234:237], v[8:11]
	v_mfma_f32_16x16x32_bf16 v[4:7], v[188:191], v[234:237], v[4:7]
	s_barrier
; #define PG8_STAGE(bufoff, gbase, voff) do { _Pragma("unroll") for (int _i = 0; _i < 2; ++_i) \
;         __builtin_amdgcn_global_load_lds((const unsigned*)((const char*)(gbase) + (voff)[_i]), (LAS unsigned*)(lds + (bufoff) + ldsw + _i * 8192), 16, 0, 0); } while (0)
; #define PG8_LDA(dst, b, h) do { _Pragma("unroll") for (int m = 0; m < 4; ++m) _Pragma("unroll") for (int k = 0; k < 2; ++k) dst[m][k] = *(const LAS bf16x8*)(lds + PG8_SA(b, h) + aoff + m * 2048 + k * 1024); } while (0)
; #define PG8_LDB(dst, b, h) do { _Pragma("unroll") for (int n = 0; n < 2; ++n) _Pragma("unroll") for (int k = 0; k < 2; ++k) dst[n][k] = *(const LAS bf16x8*)(lds + PG8_SB(b, h) + boff + n * 2048 + k * 1024); } while (0)
; #define PG8_MMA(ai, bj, At, Bt) do { __builtin_amdgcn_s_setprio(1); _Pragma("unroll") for (int m = 0; m < 4; ++m) _Pragma("unroll") for (int n = 0; n < 2; ++n) _Pragma("unroll") for (int k = 0; k < 2; ++k) \
;         acc[ai][bj][m][n] = __builtin_amdgcn_mfma_f32_16x16x32_bf16(Bt[n][k], At[m][k], acc[ai][bj][m][n], 0, 0, 0); __builtin_amdgcn_s_setprio(0); } while (0)
; #define PG8_WAIT_V(n) asm volatile("s_waitcnt vmcnt(" #n ")" ::: "memory")
; #define PG8_WAIT_L(n) asm volatile("s_waitcnt lgkmcnt(" #n ")" ::: "memory")
; #define PG8_BAR __builtin_amdgcn_s_barrier()
; #define PG8_SCHED __builtin_amdgcn_sched_barrier(0)
; template <class Epi>
; __device__ __forceinline__ void gemm_phase(LAS unsigned char* lds, const Gemm g, const int G, const int cidx, const Epi& E) {
;     ...
;             PG8_LDB(B0, 1, 0); PG8_LDB(B1, 1, 1); PG8_SCHED; PG8_LDA(At, 1, 0); PG8_STAGE(PG8_SA(0, 1), a2 + hstep, voffA);
;             PG8_WAIT_V(8); PG8_WAIT_L(0); PG8_BAR; PG8_MMA(0, 0, At, B0); PG8_MMA(0, 1, At, B1); PG8_BAR; PG8_SCHED;
;             PG8_LDA(At, 1, 1); PG8_STAGE(PG8_SB(1, 0), b3, voffB); PG8_STAGE(PG8_SB(1, 1), b3 + hstep, voffB); PG8_STAGE(PG8_SA(1, 0), a3, voffA);
;             PG8_WAIT_V(8); PG8_WAIT_L(0); PG8_BAR; PG8_MMA(1, 0, At, B0); PG8_MMA(1, 1, At, B1); PG8_BAR; PG8_SCHED;
	s_add_i32 s43, 0, 0x18000
	s_add_i32 s68, 0, 0x1c000
	v_add_u32_e32 v172, s43, v145
	v_add_u32_e32 v188, s68, v145
	ds_read_b128 v[158:161], v172
	ds_read_b128 v[164:167], v172 offset:1024
	ds_read_b128 v[168:171], v172 offset:2048
	ds_read_b128 v[172:175], v172 offset:3072
	ds_read_b128 v[176:179], v188
	ds_read_b128 v[180:183], v188 offset:1024
	ds_read_b128 v[184:187], v188 offset:2048
	ds_read_b128 v[188:191], v188 offset:3072
	s_add_u32 s26, s26, 0x40000
	s_addc_u32 s27, s27, 0
	s_mov_b32 m0, s16
	v_lshl_add_u64 v[200:201], s[26:27], 0, v[150:151]
	ds_read_b128 v[192:195], v163 offset:32768
	ds_read_b128 v[196:199], v163 offset:33792
	ds_read_b128 v[214:217], v163 offset:34816
	ds_read_b128 v[218:221], v163 offset:35840
	ds_read_b128 v[222:225], v163 offset:36864
	ds_read_b128 v[226:229], v163 offset:37888
	ds_read_b128 v[230:233], v163 offset:38912
	ds_read_b128 v[234:237], v163 offset:39936
	global_load_lds_dwordx4 v[200:201], off
	v_lshl_add_u64 v[200:201], s[26:27], 0, v[146:147]
	s_mov_b32 m0, s17
	s_nop 0
	global_load_lds_dwordx4 v[200:201], off
	s_waitcnt vmcnt(8)
	s_waitcnt lgkmcnt(0)
	s_barrier
	s_waitcnt lgkmcnt(0)
	v_mfma_f32_16x16x32_bf16 v[128:131], v[158:161], v[192:195], v[128:131]
	v_mfma_f32_16x16x32_bf16 v[124:127], v[168:171], v[192:195], v[124:127]
	v_mfma_f32_16x16x32_bf16 v[120:123], v[158:161], v[214:217], v[120:123]
	v_mfma_f32_16x16x32_bf16 v[112:115], v[168:171], v[214:217], v[112:115]
	v_mfma_f32_16x16x32_bf16 v[104:107], v[158:161], v[222:225], v[104:107]
	v_mfma_f32_16x16x32_bf16 v[96:99], v[168:171], v[222:225], v[96:99]
	v_mfma_f32_16x16x32_bf16 v[88:91], v[158:161], v[230:233], v[88:91]
	v_mfma_f32_16x16x32_bf16 v[80:83], v[168:171], v[230:233], v[80:83]
	v_mfma_f32_16x16x32_bf16 v[128:131], v[164:167], v[196:199], v[128:131]
	v_mfma_f32_16x16x32_bf16 v[124:127], v[172:175], v[196:199], v[124:127]
	v_mfma_f32_16x16x32_bf16 v[120:123], v[164:167], v[218:221], v[120:123]
	v_mfma_f32_16x16x32_bf16 v[112:115], v[172:175], v[218:221], v[112:115]
	v_mfma_f32_16x16x32_bf16 v[104:107], v[164:167], v[226:229], v[104:107]
	v_mfma_f32_16x16x32_bf16 v[96:99], v[172:175], v[226:229], v[96:99]
	v_mfma_f32_16x16x32_bf16 v[88:91], v[164:167], v[234:237], v[88:91]
	v_mfma_f32_16x16x32_bf16 v[80:83], v[172:175], v[234:237], v[80:83]
	v_mfma_f32_16x16x32_bf16 v[116:119], v[176:179], v[192:195], v[116:119]
	v_mfma_f32_16x16x32_bf16 v[108:111], v[184:187], v[192:195], v[108:111]
	v_mfma_f32_16x16x32_bf16 v[100:103], v[176:179], v[214:217], v[100:103]
	v_mfma_f32_16x16x32_bf16 v[92:95], v[184:187], v[214:217], v[92:95]
	v_mfma_f32_16x16x32_bf16 v[84:87], v[176:179], v[222:225], v[84:87]
	v_mfma_f32_16x16x32_bf16 v[76:79], v[184:187], v[222:225], v[76:79]
	v_mfma_f32_16x16x32_bf16 v[72:75], v[176:179], v[230:233], v[72:75]
	v_mfma_f32_16x16x32_bf16 v[68:71], v[184:187], v[230:233], v[68:71]
	v_mfma_f32_16x16x32_bf16 v[116:119], v[180:183], v[196:199], v[116:119]
	v_mfma_f32_16x16x32_bf16 v[108:111], v[188:191], v[196:199], v[108:111]
	v_mfma_f32_16x16x32_bf16 v[100:103], v[180:183], v[218:221], v[100:103]
	v_mfma_f32_16x16x32_bf16 v[92:95], v[188:191], v[218:221], v[92:95]
	v_mfma_f32_16x16x32_bf16 v[84:87], v[180:183], v[226:229], v[84:87]
	v_mfma_f32_16x16x32_bf16 v[76:79], v[188:191], v[226:229], v[76:79]
	v_mfma_f32_16x16x32_bf16 v[72:75], v[180:183], v[234:237], v[72:75]
	v_mfma_f32_16x16x32_bf16 v[68:71], v[188:191], v[234:237], v[68:71]
	s_barrier
	s_add_i32 s26, s43, s95
	v_lshl_add_u64 v[132:133], v[132:133], 0, s[46:47]
	s_mov_b32 m0, s26
	ds_read_b128 v[192:195], v163 offset:49152
	ds_read_b128 v[196:199], v163 offset:50176
	ds_read_b128 v[214:217], v163 offset:51200
	ds_read_b128 v[218:221], v163 offset:52224
	ds_read_b128 v[222:225], v163 offset:53248
	ds_read_b128 v[226:229], v163 offset:54272
	ds_read_b128 v[230:233], v163 offset:55296
	ds_read_b128 v[234:237], v163 offset:56320
	global_load_lds_dwordx4 v[132:133], off
	s_add_i32 m0, s26, 0x2000
	s_add_u32 s24, s24, 0x40080
	v_lshl_add_u64 v[132:133], v[134:135], 0, s[46:47]
	s_addc_u32 s25, s25, 0
	s_add_i32 s26, s68, s95
	global_load_lds_dwordx4 v[132:133], off
	v_lshl_add_u64 v[132:133], s[24:25], 0, v[148:149]
	s_mov_b32 m0, s26
	s_nop 0
	global_load_lds_dwordx4 v[132:133], off
	v_lshl_add_u64 v[132:133], s[24:25], 0, v[0:1]
	s_add_i32 m0, s26, 0x2000
	s_nop 0
	global_load_lds_dwordx4 v[132:133], off
	v_lshl_add_u64 v[132:133], v[140:141], 0, s[46:47]
	s_mov_b32 m0, s84
	s_nop 0
	global_load_lds_dwordx4 v[132:133], off
	v_lshl_add_u64 v[132:133], v[142:143], 0, s[46:47]
	s_mov_b32 m0, s76
	s_nop 0
	global_load_lds_dwordx4 v[132:133], off
	s_waitcnt vmcnt(8)
	s_waitcnt lgkmcnt(0)
	s_barrier
; __device__ __forceinline__ unsigned pk2(float lo, float hi) { unsigned r; asm("v_cvt_pk_bf16_f32 %0, %1, %2" : "=v"(r) : "v"(lo), "v"(hi)); return r; }
; #define PG8_MMA(ai, bj, At, Bt) do { __builtin_amdgcn_s_setprio(1); _Pragma("unroll") for (int m = 0; m < 4; ++m) _Pragma("unroll") for (int n = 0; n < 2; ++n) _Pragma("unroll") for (int k = 0; k < 2; ++k) \
;         acc[ai][bj][m][n] = __builtin_amdgcn_mfma_f32_16x16x32_bf16(Bt[n][k], At[m][k], acc[ai][bj][m][n], 0, 0, 0); __builtin_amdgcn_s_setprio(0); } while (0)
; #define PG8_WAIT_V(n) asm volatile("s_waitcnt vmcnt(" #n ")" ::: "memory")
; #define PG8_WAIT_L(n) asm volatile("s_waitcnt lgkmcnt(" #n ")" ::: "memory")
; #define PG8_BAR __builtin_amdgcn_s_barrier()
; #define PG8_SCHED __builtin_amdgcn_sched_barrier(0)
;     __device__ __forceinline__ void operator()(const f32x4 (&acc)[2][2][4][2], const Unit& u, int wr, int wc, int fr, int fq) const {
;     ...
;             const int g = u.pn - 11, n = g >> 2, q = g & 3;
;             bf16_t* blk = Gt + (((size_t)n * 64 + u.pm) * 8 + q * 2) * 32768 + (size_t)((wr * 4 * 4 + wc) * 64 + fq * 16 + fr) * 8;
; #pragma unroll
;             for (int ai = 0; ai < 2; ++ai)
; #pragma unroll
;                 for (int m = 0; m < 4; ++m)
; #pragma unroll
;                     for (int bj = 0; bj < 2; ++bj) { const f32x4 v0 = acc[ai][bj][m][0], v1 = acc[ai][bj][m][1];
;                         u32x4 w; w.x = pk2(v0[0], v0[1]); w.y = pk2(v0[2], v0[3]); w.z = pk2(v1[0], v1[1]); w.w = pk2(v1[2], v1[3]);
;                         *(u32x4*)(blk + (size_t)bj * 32768 + (size_t)((ai * 8 + m) * 4) * 512) = w; }
;         }
; template <class Epi>
; __device__ __forceinline__ void gemm_phase(LAS unsigned char* lds, const Gemm g, const int G, const int cidx, const Epi& E) {
;     ...
;             PG8_WAIT_V(8); PG8_WAIT_L(0); PG8_BAR; PG8_MMA(1, 0, At, B0); PG8_MMA(1, 1, At, B1); PG8_BAR; PG8_SCHED;
;         }
;         if constexpr (!Epi::AFTER_DRAIN) E(acc, cur, wr, wc, fr, fq);
	s_waitcnt lgkmcnt(0)
	v_mfma_f32_16x16x32_bf16 v[64:67], v[158:161], v[192:195], v[64:67]
	v_mfma_f32_16x16x32_bf16 v[60:63], v[168:171], v[192:195], v[60:63]
	v_mfma_f32_16x16x32_bf16 v[56:59], v[158:161], v[214:217], v[56:59]
	v_mfma_f32_16x16x32_bf16 v[48:51], v[168:171], v[214:217], v[48:51]
	v_mfma_f32_16x16x32_bf16 v[40:43], v[158:161], v[222:225], v[40:43]
	v_mfma_f32_16x16x32_bf16 v[32:35], v[168:171], v[222:225], v[32:35]
	v_mfma_f32_16x16x32_bf16 v[24:27], v[158:161], v[230:233], v[24:27]
	v_mfma_f32_16x16x32_bf16 v[16:19], v[168:171], v[230:233], v[16:19]
	v_mfma_f32_16x16x32_bf16 v[64:67], v[164:167], v[196:199], v[64:67]
	v_mfma_f32_16x16x32_bf16 v[60:63], v[172:175], v[196:199], v[60:63]
	v_mfma_f32_16x16x32_bf16 v[56:59], v[164:167], v[218:221], v[56:59]
	v_mfma_f32_16x16x32_bf16 v[48:51], v[172:175], v[218:221], v[48:51]
	v_mfma_f32_16x16x32_bf16 v[40:43], v[164:167], v[226:229], v[40:43]
	v_mfma_f32_16x16x32_bf16 v[32:35], v[172:175], v[226:229], v[32:35]
	v_mfma_f32_16x16x32_bf16 v[24:27], v[164:167], v[234:237], v[24:27]
	v_mfma_f32_16x16x32_bf16 v[16:19], v[172:175], v[234:237], v[16:19]
	v_mfma_f32_16x16x32_bf16 v[52:55], v[176:179], v[192:195], v[52:55]
	v_mfma_f32_16x16x32_bf16 v[44:47], v[184:187], v[192:195], v[44:47]
	v_mfma_f32_16x16x32_bf16 v[36:39], v[176:179], v[214:217], v[36:39]
	v_mfma_f32_16x16x32_bf16 v[28:31], v[184:187], v[214:217], v[28:31]
	v_mfma_f32_16x16x32_bf16 v[20:23], v[176:179], v[222:225], v[20:23]
	v_mfma_f32_16x16x32_bf16 v[12:15], v[184:187], v[222:225], v[12:15]
	v_mfma_f32_16x16x32_bf16 v[8:11], v[176:179], v[230:233], v[8:11]
	v_mfma_f32_16x16x32_bf16 v[4:7], v[184:187], v[230:233], v[4:7]
	v_mfma_f32_16x16x32_bf16 v[52:55], v[180:183], v[196:199], v[52:55]
	v_mfma_f32_16x16x32_bf16 v[44:47], v[188:191], v[196:199], v[44:47]
	v_mfma_f32_16x16x32_bf16 v[36:39], v[180:183], v[218:221], v[36:39]
	v_mfma_f32_16x16x32_bf16 v[28:31], v[188:191], v[218:221], v[28:31]
	v_mfma_f32_16x16x32_bf16 v[20:23], v[180:183], v[226:229], v[20:23]
	v_mfma_f32_16x16x32_bf16 v[12:15], v[188:191], v[226:229], v[12:15]
	v_mfma_f32_16x16x32_bf16 v[8:11], v[180:183], v[234:237], v[8:11]
	v_mfma_f32_16x16x32_bf16 v[4:7], v[188:191], v[234:237], v[4:7]
	s_barrier
	s_add_i32 s45, s45, 2
	s_add_u32 s42, s42, 0x100
	s_addc_u32 s44, s44, 0
	s_add_u32 s20, s20, 0x100
	s_addc_u32 s21, s21, 0
	s_cmp_gt_u32 s45, 13
	s_cbranch_scc0 .LBB0_601
	s_cmp_gt_i32 s35, 10
	s_mov_b64 s[20:21], -1
	s_mov_b32 s26, 0x1a000
	s_mov_b32 s27, 0x19000
	s_cbranch_scc0 .LBB0_604
	s_add_i32 s9, s35, -11
	s_mov_b32 s21, s77
	s_lshr_b32 s20, s9, 2
	s_ashr_i32 s19, s18, 31
	s_lshl_b64 s[20:21], s[20:21], 9
	s_lshl_b64 s[24:25], s[18:19], 3
	s_add_u32 s11, s20, s24
	s_addc_u32 s21, s21, s25
	s_lshl_b32 s9, s9, 1
	s_and_b32 s9, s9, 6
	s_or_b32 s20, s11, s9
	s_lshl_b64 s[20:21], s[20:21], 16
	v_lshl_add_u64 v[158:159], v[152:153], 0, s[20:21]
	s_mov_b32 s9, 0x11000
	v_add_co_u32_e32 v132, vcc, s9, v158
	v_cvt_pk_bf16_f32 v164, v128, v129
	v_cvt_pk_bf16_f32 v165, v130, v131
	v_cvt_pk_bf16_f32 v166, v124, v125
	v_cvt_pk_bf16_f32 v167, v126, v127
	s_nop 1
	v_addc_co_u32_e32 v133, vcc, 0, v159, vcc
	global_store_dwordx4 v[158:159], v[164:167], off
	v_add_co_u32_e32 v134, vcc, s81, v158
	s_nop 0
	v_cvt_pk_bf16_f32 v164, v116, v117
	v_cvt_pk_bf16_f32 v165, v118, v119
	v_cvt_pk_bf16_f32 v166, v108, v109
	v_cvt_pk_bf16_f32 v167, v110, v111
	global_store_dwordx4 v[132:133], v[164:167], off offset:-4096
	v_addc_co_u32_e32 v135, vcc, 0, v159, vcc
	s_nop 0
	v_cvt_pk_bf16_f32 v164, v120, v121
	v_cvt_pk_bf16_f32 v165, v122, v123
	v_cvt_pk_bf16_f32 v166, v112, v113
	v_cvt_pk_bf16_f32 v167, v114, v115
	s_mov_b32 s9, 0x13000
	global_store_dwordx4 v[134:135], v[164:167], off offset:-4096
	s_mov_b64 s[20:21], 0
	s_nop 0
	v_cvt_pk_bf16_f32 v164, v100, v101
	v_cvt_pk_bf16_f32 v165, v102, v103
	v_cvt_pk_bf16_f32 v166, v92, v93
	v_cvt_pk_bf16_f32 v167, v94, v95
	global_store_dwordx4 v[132:133], v[164:167], off
	v_add_co_u32_e32 v132, vcc, s9, v158
	s_nop 0
	v_cvt_pk_bf16_f32 v164, v104, v105
	v_cvt_pk_bf16_f32 v165, v106, v107
	v_cvt_pk_bf16_f32 v166, v96, v97
	v_cvt_pk_bf16_f32 v167, v98, v99
	s_nop 0
	v_addc_co_u32_e32 v133, vcc, 0, v159, vcc
	global_store_dwordx4 v[134:135], v[164:167], off
	v_add_co_u32_e32 v134, vcc, s82, v158
	s_nop 0
	v_cvt_pk_bf16_f32 v164, v84, v85
	v_cvt_pk_bf16_f32 v165, v86, v87
	v_cvt_pk_bf16_f32 v166, v76, v77
	v_cvt_pk_bf16_f32 v167, v78, v79
	global_store_dwordx4 v[132:133], v[164:167], off offset:-4096
	v_addc_co_u32_e32 v135, vcc, 0, v159, vcc
	s_nop 0
	v_cvt_pk_bf16_f32 v164, v88, v89
	v_cvt_pk_bf16_f32 v165, v90, v91
	v_cvt_pk_bf16_f32 v166, v80, v81
	v_cvt_pk_bf16_f32 v167, v82, v83
	s_mov_b32 s9, 0x9000
	global_store_dwordx4 v[134:135], v[164:167], off
	s_nop 1
	v_cvt_pk_bf16_f32 v164, v72, v73
	v_cvt_pk_bf16_f32 v165, v74, v75
	v_cvt_pk_bf16_f32 v166, v68, v69
	v_cvt_pk_bf16_f32 v167, v70, v71
	global_store_dwordx4 v[132:133], v[164:167], off
	v_add_co_u32_e32 v132, vcc, s9, v158
	s_nop 0
	v_cvt_pk_bf16_f32 v164, v64, v65
	v_cvt_pk_bf16_f32 v165, v66, v67
	v_cvt_pk_bf16_f32 v166, v60, v61
	v_cvt_pk_bf16_f32 v167, v62, v63
	s_nop 0
	v_addc_co_u32_e32 v133, vcc, 0, v159, vcc
	v_add_co_u32_e32 v134, vcc, s27, v158
	global_store_dwordx4 v[132:133], v[164:167], off offset:-4096
	s_nop 0
	v_addc_co_u32_e32 v135, vcc, 0, v159, vcc
	v_cvt_pk_bf16_f32 v164, v52, v53
	v_cvt_pk_bf16_f32 v165, v54, v55
	v_cvt_pk_bf16_f32 v166, v44, v45
	v_cvt_pk_bf16_f32 v167, v46, v47
	s_mov_b32 s9, 0xb000
	global_store_dwordx4 v[134:135], v[164:167], off offset:-4096
	s_nop 1
	v_cvt_pk_bf16_f32 v164, v56, v57
	v_cvt_pk_bf16_f32 v165, v58, v59
	v_cvt_pk_bf16_f32 v166, v48, v49
	v_cvt_pk_bf16_f32 v167, v50, v51
	global_store_dwordx4 v[132:133], v[164:167], off
	v_add_co_u32_e32 v132, vcc, s9, v158
	s_nop 0
	v_cvt_pk_bf16_f32 v164, v36, v37
	v_cvt_pk_bf16_f32 v165, v38, v39
	v_cvt_pk_bf16_f32 v166, v28, v29
	v_cvt_pk_bf16_f32 v167, v30, v31
	s_nop 0
	v_addc_co_u32_e32 v133, vcc, 0, v159, vcc
	global_store_dwordx4 v[134:135], v[164:167], off
	v_add_co_u32_e32 v134, vcc, s26, v158
	s_nop 0
	v_cvt_pk_bf16_f32 v164, v40, v41
	v_cvt_pk_bf16_f32 v165, v42, v43
	v_cvt_pk_bf16_f32 v166, v32, v33
	v_cvt_pk_bf16_f32 v167, v34, v35
	global_store_dwordx4 v[132:133], v[164:167], off offset:-4096
	v_addc_co_u32_e32 v135, vcc, 0, v159, vcc
	s_nop 0
	v_cvt_pk_bf16_f32 v164, v20, v21
	v_cvt_pk_bf16_f32 v165, v22, v23
	v_cvt_pk_bf16_f32 v166, v12, v13
	v_cvt_pk_bf16_f32 v167, v14, v15
	global_store_dwordx4 v[134:135], v[164:167], off
	s_nop 1
	v_cvt_pk_bf16_f32 v164, v24, v25
	v_cvt_pk_bf16_f32 v165, v26, v27
	v_cvt_pk_bf16_f32 v166, v16, v17
	v_cvt_pk_bf16_f32 v167, v18, v19
	global_store_dwordx4 v[132:133], v[164:167], off
	v_add_co_u32_e32 v132, vcc, 0x1b000, v158
	s_nop 0
	v_cvt_pk_bf16_f32 v164, v8, v9
	v_cvt_pk_bf16_f32 v165, v10, v11
	v_cvt_pk_bf16_f32 v166, v4, v5
	v_cvt_pk_bf16_f32 v167, v6, v7
	s_nop 0
	v_addc_co_u32_e32 v133, vcc, 0, v159, vcc
	global_store_dwordx4 v[132:133], v[164:167], off
